# saddr-dma
# speedup vs baseline: 1.0223x; 1.0053x over previous
; #define PG8_STAGE(bufoff, gbase, voff) do { _Pragma("unroll") for (int _i = 0; _i < 2; ++_i) \
;         __builtin_amdgcn_global_load_lds((const unsigned*)((const char*)(gbase) + (voff)[_i]), (LAS unsigned*)(lds + (bufoff) + ldsw + _i * 8192), 16, 0, 0); } while (0)
; #define PG8_LDA(dst, b, h) do { _Pragma("unroll") for (int m = 0; m < 4; ++m) _Pragma("unroll") for (int k = 0; k < 2; ++k) dst[m][k] = *(const LAS bf16x8*)(lds + PG8_SA(b, h) + aoff + m * 2048 + k * 1024); } while (0)
; #define PG8_LDB(dst, b, h) do { _Pragma("unroll") for (int n = 0; n < 2; ++n) _Pragma("unroll") for (int k = 0; k < 2; ++k) dst[n][k] = *(const LAS bf16x8*)(lds + PG8_SB(b, h) + boff + n * 2048 + k * 1024); } while (0)
; #define PG8_MMA(ai, bj, At, Bt) do { __builtin_amdgcn_s_setprio(1); _Pragma("unroll") for (int m = 0; m < 4; ++m) _Pragma("unroll") for (int n = 0; n < 2; ++n) _Pragma("unroll") for (int k = 0; k < 2; ++k) \
;         acc[ai][bj][m][n] = __builtin_amdgcn_mfma_f32_16x16x32_bf16(Bt[n][k], At[m][k], acc[ai][bj][m][n], 0, 0, 0); __builtin_amdgcn_s_setprio(0); } while (0)
; #define PG8_WAIT_L(n) asm volatile("s_waitcnt lgkmcnt(" #n ")" ::: "memory")
; #define PG8_BAR __builtin_amdgcn_s_barrier()
; #define PG8_SCHED __builtin_amdgcn_sched_barrier(0)
; template <class Epi, class Sched, bool ATILE = false>
; __device__ __forceinline__ void gemm_phase(LAS unsigned char* lds, const Gemm g, const Sched& S, const Epi& E) {
;     ...
;         for (int t = 0; t < nt; t += 2) {
;             const bool last = (t == nt - 2);
;             const char* a1 = cA + (size_t)(t + 1) * kstepA;
;             const char* a2 = last ? nA : cA + (size_t)(t + 2) * kstepA; const char* b2 = last ? nB : cB + (size_t)(t + 2) * kstep;
;             const char* a3 = a2 + kstepA; const char* b3 = b2 + kstep;
;             PG8_LDB(B0, 0, 0); PG8_SCHED; PG8_LDA(At, 0, 0); PG8_STAGE(PG8_SA(1, 1), a1 + hstepA, voffA);
;             PG8_WAIT_L(8); PG8_BAR; PG8_WAIT_L(0); PG8_MMA(0, 0, At, B0); PG8_BAR; PG8_SCHED;
;             PG8_LDB(B1, 0, 1); PG8_STAGE(PG8_SB(0, 0), b2, voffB);
;             PG8_BAR; PG8_WAIT_L(0); PG8_MMA(0, 1, At, B1); PG8_BAR;
;             PG8_LDA(At, 0, 1); PG8_STAGE(PG8_SA(0, 0), a2, voffA);
;             PG8_BAR; PG8_WAIT_L(0); PG8_MMA(1, 0, At, B0); PG8_BAR; PG8_SCHED;
.LBB0_625:
	ds_read_b128 v[182:185], v139
	ds_read_b128 v[186:189], v139 offset:1024
	ds_read_b128 v[190:193], v139 offset:2048
	ds_read_b128 v[194:197], v139 offset:3072
	s_add_i32 s62, s28, 2
	s_add_u32 s29, s26, 0xfff80080
	s_addc_u32 s30, s27, -1
	s_cmp_eq_u32 s59, s28
	s_cselect_b32 s28, s58, s60
	s_cselect_b32 s31, s13, s30
	s_cselect_b32 s30, s56, s29
	s_cselect_b32 s29, s57, s61
	s_add_i32 m0, s35, 0xc000
	ds_read_b128 v[198:201], v163
	ds_read_b128 v[202:205], v163 offset:1024
	ds_read_b128 v[206:209], v163 offset:2048
	ds_read_b128 v[210:213], v163 offset:3072
	ds_read_b128 v[214:217], v163 offset:4096
	ds_read_b128 v[218:221], v163 offset:5120
	ds_read_b128 v[222:225], v163 offset:6144
	ds_read_b128 v[226:229], v163 offset:7168
	global_load_lds_dwordx4 v172, s[26:27]
	s_add_i32 m0, s35, 0xe000
	s_nop 0
	global_load_lds_dwordx4 v174, s[26:27]
	s_waitcnt lgkmcnt(8)
	s_barrier
	s_waitcnt lgkmcnt(0)
	s_setprio 1
	s_waitcnt lgkmcnt(0)
	v_mfma_f32_16x16x32_bf16 v[120:123], v[182:185], v[198:201], v[120:123]
	v_mfma_f32_16x16x32_bf16 v[112:115], v[190:193], v[198:201], v[112:115]
	v_mfma_f32_16x16x32_bf16 v[104:107], v[182:185], v[206:209], v[104:107]
	v_mfma_f32_16x16x32_bf16 v[96:99], v[190:193], v[206:209], v[96:99]
	v_mfma_f32_16x16x32_bf16 v[88:91], v[182:185], v[214:217], v[88:91]
	v_mfma_f32_16x16x32_bf16 v[80:83], v[190:193], v[214:217], v[80:83]
	v_mfma_f32_16x16x32_bf16 v[72:75], v[182:185], v[222:225], v[72:75]
	v_mfma_f32_16x16x32_bf16 v[64:67], v[190:193], v[222:225], v[64:67]
	v_mfma_f32_16x16x32_bf16 v[120:123], v[186:189], v[202:205], v[120:123]
	v_mfma_f32_16x16x32_bf16 v[112:115], v[194:197], v[202:205], v[112:115]
	v_mfma_f32_16x16x32_bf16 v[104:107], v[186:189], v[210:213], v[104:107]
	v_mfma_f32_16x16x32_bf16 v[96:99], v[194:197], v[210:213], v[96:99]
	v_mfma_f32_16x16x32_bf16 v[88:91], v[186:189], v[218:221], v[88:91]
	v_mfma_f32_16x16x32_bf16 v[80:83], v[194:197], v[218:221], v[80:83]
	v_mfma_f32_16x16x32_bf16 v[72:75], v[186:189], v[226:229], v[72:75]
	v_mfma_f32_16x16x32_bf16 v[64:67], v[194:197], v[226:229], v[64:67]
	s_setprio 0
	s_barrier
	s_add_i32 s63, s53, s34
	v_lshl_add_u64 v[246:247], s[28:29], 0, v[130:131]
	s_mov_b32 m0, s63
	ds_read_b128 v[230:233], v167
	ds_read_b128 v[234:237], v167 offset:1024
	ds_read_b128 v[238:241], v167 offset:2048
	ds_read_b128 v[242:245], v167 offset:3072
	global_load_lds_dwordx4 v[246:247], off
	v_lshl_add_u64 v[248:249], s[28:29], 0, v[134:135]
	s_add_i32 m0, s63, 0x2000
	s_nop 0
	global_load_lds_dwordx4 v[248:249], off
	s_barrier
	s_waitcnt lgkmcnt(0)
	s_setprio 1
	s_waitcnt lgkmcnt(0)
	v_mfma_f32_16x16x32_bf16 v[124:127], v[230:233], v[198:201], v[124:127]
	v_mfma_f32_16x16x32_bf16 v[116:119], v[238:241], v[198:201], v[116:119]
	v_mfma_f32_16x16x32_bf16 v[108:111], v[230:233], v[206:209], v[108:111]
	v_mfma_f32_16x16x32_bf16 v[100:103], v[238:241], v[206:209], v[100:103]
	v_mfma_f32_16x16x32_bf16 v[92:95], v[230:233], v[214:217], v[92:95]
	v_mfma_f32_16x16x32_bf16 v[84:87], v[238:241], v[214:217], v[84:87]
	v_mfma_f32_16x16x32_bf16 v[76:79], v[230:233], v[222:225], v[76:79]
	v_mfma_f32_16x16x32_bf16 v[68:71], v[238:241], v[222:225], v[68:71]
	v_mfma_f32_16x16x32_bf16 v[124:127], v[234:237], v[202:205], v[124:127]
	v_mfma_f32_16x16x32_bf16 v[116:119], v[242:245], v[202:205], v[116:119]
	v_mfma_f32_16x16x32_bf16 v[108:111], v[234:237], v[210:213], v[108:111]
	v_mfma_f32_16x16x32_bf16 v[100:103], v[242:245], v[210:213], v[100:103]
	v_mfma_f32_16x16x32_bf16 v[92:95], v[234:237], v[218:221], v[92:95]
	v_mfma_f32_16x16x32_bf16 v[84:87], v[242:245], v[218:221], v[84:87]
	v_mfma_f32_16x16x32_bf16 v[76:79], v[234:237], v[226:229], v[76:79]
	v_mfma_f32_16x16x32_bf16 v[68:71], v[242:245], v[226:229], v[68:71]
	s_setprio 0
	s_barrier
	s_mov_b32 m0, s35
	v_lshl_add_u64 v[250:251], s[30:31], 0, v[128:129]
	ds_read_b128 v[198:201], v163 offset:16384
	ds_read_b128 v[202:205], v163 offset:17408
	ds_read_b128 v[206:209], v163 offset:18432
	ds_read_b128 v[210:213], v163 offset:19456
	ds_read_b128 v[214:217], v163 offset:20480
	ds_read_b128 v[218:221], v163 offset:21504
	ds_read_b128 v[222:225], v163 offset:22528
	ds_read_b128 v[226:229], v163 offset:23552
	global_load_lds_dwordx4 v[250:251], off
	v_lshl_add_u64 v[252:253], s[30:31], 0, v[132:133]
	s_mov_b32 m0, s36
	s_nop 0
	global_load_lds_dwordx4 v[252:253], off
	s_barrier
	s_waitcnt lgkmcnt(0)
	s_setprio 1
	s_waitcnt lgkmcnt(0)
	v_mfma_f32_16x16x32_bf16 v[56:59], v[182:185], v[198:201], v[56:59]
	v_mfma_f32_16x16x32_bf16 v[48:51], v[190:193], v[198:201], v[48:51]
	v_mfma_f32_16x16x32_bf16 v[40:43], v[182:185], v[206:209], v[40:43]
	v_mfma_f32_16x16x32_bf16 v[32:35], v[190:193], v[206:209], v[32:35]
	v_mfma_f32_16x16x32_bf16 v[24:27], v[182:185], v[214:217], v[24:27]
	v_mfma_f32_16x16x32_bf16 v[16:19], v[190:193], v[214:217], v[16:19]
	v_mfma_f32_16x16x32_bf16 v[8:11], v[182:185], v[222:225], v[8:11]
	v_mfma_f32_16x16x32_bf16 v[4:7], v[190:193], v[222:225], v[4:7]
	v_mfma_f32_16x16x32_bf16 v[56:59], v[186:189], v[202:205], v[56:59]
	v_mfma_f32_16x16x32_bf16 v[48:51], v[194:197], v[202:205], v[48:51]
	v_mfma_f32_16x16x32_bf16 v[40:43], v[186:189], v[210:213], v[40:43]
	v_mfma_f32_16x16x32_bf16 v[32:35], v[194:197], v[210:213], v[32:35]
	v_mfma_f32_16x16x32_bf16 v[24:27], v[186:189], v[218:221], v[24:27]
	v_mfma_f32_16x16x32_bf16 v[16:19], v[194:197], v[218:221], v[16:19]
	v_mfma_f32_16x16x32_bf16 v[8:11], v[186:189], v[226:229], v[8:11]
	v_mfma_f32_16x16x32_bf16 v[4:7], v[194:197], v[226:229], v[4:7]
	s_setprio 0
	s_barrier
; #define PG8_STAGE(bufoff, gbase, voff) do { _Pragma("unroll") for (int _i = 0; _i < 2; ++_i) \
;         __builtin_amdgcn_global_load_lds((const unsigned*)((const char*)(gbase) + (voff)[_i]), (LAS unsigned*)(lds + (bufoff) + ldsw + _i * 8192), 16, 0, 0); } while (0)
; #define PG8_LDA(dst, b, h) do { _Pragma("unroll") for (int m = 0; m < 4; ++m) _Pragma("unroll") for (int k = 0; k < 2; ++k) dst[m][k] = *(const LAS bf16x8*)(lds + PG8_SA(b, h) + aoff + m * 2048 + k * 1024); } while (0)
; #define PG8_LDB(dst, b, h) do { _Pragma("unroll") for (int n = 0; n < 2; ++n) _Pragma("unroll") for (int k = 0; k < 2; ++k) dst[n][k] = *(const LAS bf16x8*)(lds + PG8_SB(b, h) + boff + n * 2048 + k * 1024); } while (0)
; #define PG8_MMA(ai, bj, At, Bt) do { __builtin_amdgcn_s_setprio(1); _Pragma("unroll") for (int m = 0; m < 4; ++m) _Pragma("unroll") for (int n = 0; n < 2; ++n) _Pragma("unroll") for (int k = 0; k < 2; ++k) \
;         acc[ai][bj][m][n] = __builtin_amdgcn_mfma_f32_16x16x32_bf16(Bt[n][k], At[m][k], acc[ai][bj][m][n], 0, 0, 0); __builtin_amdgcn_s_setprio(0); } while (0)
; #define PG8_WAIT_V(n) asm volatile("s_waitcnt vmcnt(" #n ")" ::: "memory")
; #define PG8_WAIT_L(n) asm volatile("s_waitcnt lgkmcnt(" #n ")" ::: "memory")
; #define PG8_BAR __builtin_amdgcn_s_barrier()
; #define PG8_SCHED __builtin_amdgcn_sched_barrier(0)
; template <class Epi, class Sched, bool ATILE = false>
; __device__ __forceinline__ void gemm_phase(LAS unsigned char* lds, const Gemm g, const Sched& S, const Epi& E) {
;     ...
;             PG8_BAR; PG8_WAIT_L(0); PG8_MMA(1, 0, At, B0); PG8_BAR; PG8_SCHED;
;             PG8_STAGE(PG8_SB(0, 1), b2 + hstepB, voffB);
;             PG8_WAIT_V(6); PG8_BAR; PG8_MMA(1, 1, At, B1); PG8_BAR;
;             PG8_LDB(B0, 1, 0); PG8_SCHED; PG8_LDA(At, 1, 0); PG8_STAGE(PG8_SA(0, 1), a2 + hstepA, voffA);
;             PG8_WAIT_L(8); PG8_BAR; PG8_WAIT_L(0); PG8_MMA(0, 0, At, B0); PG8_BAR; PG8_SCHED;
;             PG8_LDB(B1, 1, 1); PG8_STAGE(PG8_SB(1, 0), b3, voffB);
;             PG8_BAR; PG8_WAIT_L(0); PG8_MMA(0, 1, At, B1); PG8_BAR;
	s_add_u32 s64, s28, 0x80000
	s_addc_u32 s65, s29, 0
	s_add_i32 s63, s54, s34
	s_mov_b32 m0, s63
	s_nop 0
	global_load_lds_dwordx4 v130, s[64:65]
	s_add_i32 m0, s63, 0x2000
	s_nop 0
	global_load_lds_dwordx4 v134, s[64:65]
	s_waitcnt vmcnt(6)
	s_barrier
	s_setprio 1
	v_mfma_f32_16x16x32_bf16 v[60:63], v[230:233], v[198:201], v[60:63]
	v_mfma_f32_16x16x32_bf16 v[52:55], v[238:241], v[198:201], v[52:55]
	v_mfma_f32_16x16x32_bf16 v[44:47], v[230:233], v[206:209], v[44:47]
	v_mfma_f32_16x16x32_bf16 v[36:39], v[238:241], v[206:209], v[36:39]
	v_mfma_f32_16x16x32_bf16 v[28:31], v[230:233], v[214:217], v[28:31]
	v_mfma_f32_16x16x32_bf16 v[20:23], v[238:241], v[214:217], v[20:23]
	v_mfma_f32_16x16x32_bf16 v[12:15], v[230:233], v[222:225], v[12:15]
	v_mfma_f32_16x16x32_bf16 v[0:3], v[238:241], v[222:225], v[0:3]
	v_mfma_f32_16x16x32_bf16 v[60:63], v[234:237], v[202:205], v[60:63]
	v_mfma_f32_16x16x32_bf16 v[52:55], v[242:245], v[202:205], v[52:55]
	v_mfma_f32_16x16x32_bf16 v[44:47], v[234:237], v[210:213], v[44:47]
	v_mfma_f32_16x16x32_bf16 v[36:39], v[242:245], v[210:213], v[36:39]
	v_mfma_f32_16x16x32_bf16 v[28:31], v[234:237], v[218:221], v[28:31]
	v_mfma_f32_16x16x32_bf16 v[20:23], v[242:245], v[218:221], v[20:23]
	v_mfma_f32_16x16x32_bf16 v[12:15], v[234:237], v[226:229], v[12:15]
	v_mfma_f32_16x16x32_bf16 v[0:3], v[242:245], v[226:229], v[0:3]
	s_setprio 0
	s_barrier
	s_add_i32 s63, 0, 0x18000
	v_add_u32_e32 v176, s63, v161
	ds_read_b128 v[182:185], v176
	ds_read_b128 v[186:189], v176 offset:1024
	ds_read_b128 v[190:193], v176 offset:2048
	ds_read_b128 v[194:197], v176 offset:3072
	s_add_u32 s30, s30, 0x80000
	s_addc_u32 s31, s31, 0
	s_mov_b32 m0, s37
	ds_read_b128 v[198:201], v163 offset:32768
	ds_read_b128 v[202:205], v163 offset:33792
	ds_read_b128 v[206:209], v163 offset:34816
	ds_read_b128 v[210:213], v163 offset:35840
	ds_read_b128 v[214:217], v163 offset:36864
	ds_read_b128 v[218:221], v163 offset:37888
	ds_read_b128 v[222:225], v163 offset:38912
	ds_read_b128 v[226:229], v163 offset:39936
	global_load_lds_dwordx4 v128, s[30:31]
	s_mov_b32 m0, s38
	s_nop 0
	global_load_lds_dwordx4 v132, s[30:31]
	s_waitcnt lgkmcnt(8)
	s_barrier
	s_waitcnt lgkmcnt(0)
	s_setprio 1
	s_waitcnt lgkmcnt(0)
	v_mfma_f32_16x16x32_bf16 v[120:123], v[182:185], v[198:201], v[120:123]
	v_mfma_f32_16x16x32_bf16 v[112:115], v[190:193], v[198:201], v[112:115]
	v_mfma_f32_16x16x32_bf16 v[104:107], v[182:185], v[206:209], v[104:107]
	v_mfma_f32_16x16x32_bf16 v[96:99], v[190:193], v[206:209], v[96:99]
	v_mfma_f32_16x16x32_bf16 v[88:91], v[182:185], v[214:217], v[88:91]
	v_mfma_f32_16x16x32_bf16 v[80:83], v[190:193], v[214:217], v[80:83]
	v_mfma_f32_16x16x32_bf16 v[72:75], v[182:185], v[222:225], v[72:75]
	v_mfma_f32_16x16x32_bf16 v[64:67], v[190:193], v[222:225], v[64:67]
	v_mfma_f32_16x16x32_bf16 v[120:123], v[186:189], v[202:205], v[120:123]
	v_mfma_f32_16x16x32_bf16 v[112:115], v[194:197], v[202:205], v[112:115]
	v_mfma_f32_16x16x32_bf16 v[104:107], v[186:189], v[210:213], v[104:107]
	v_mfma_f32_16x16x32_bf16 v[96:99], v[194:197], v[210:213], v[96:99]
	v_mfma_f32_16x16x32_bf16 v[88:91], v[186:189], v[218:221], v[88:91]
	v_mfma_f32_16x16x32_bf16 v[80:83], v[194:197], v[218:221], v[80:83]
	v_mfma_f32_16x16x32_bf16 v[72:75], v[186:189], v[226:229], v[72:75]
	v_mfma_f32_16x16x32_bf16 v[64:67], v[194:197], v[226:229], v[64:67]
	s_setprio 0
	s_barrier
	s_add_i32 s30, 0, 0x1c000
	s_add_i32 s31, s63, s34
	v_add_u32_e32 v176, s30, v161
	v_lshl_add_u64 v[246:247], v[246:247], 0, s[0:1]
	s_mov_b32 m0, s31
	ds_read_b128 v[230:233], v176
	ds_read_b128 v[234:237], v176 offset:1024
	ds_read_b128 v[238:241], v176 offset:2048
	ds_read_b128 v[242:245], v176 offset:3072
	global_load_lds_dwordx4 v[246:247], off
	v_lshl_add_u64 v[246:247], v[248:249], 0, s[0:1]
	s_add_i32 m0, s31, 0x2000
	s_nop 0
	global_load_lds_dwordx4 v[246:247], off
	s_barrier
; #define PG8_STAGE(bufoff, gbase, voff) do { _Pragma("unroll") for (int _i = 0; _i < 2; ++_i) \
;         __builtin_amdgcn_global_load_lds((const unsigned*)((const char*)(gbase) + (voff)[_i]), (LAS unsigned*)(lds + (bufoff) + ldsw + _i * 8192), 16, 0, 0); } while (0)
; #define PG8_LDA(dst, b, h) do { _Pragma("unroll") for (int m = 0; m < 4; ++m) _Pragma("unroll") for (int k = 0; k < 2; ++k) dst[m][k] = *(const LAS bf16x8*)(lds + PG8_SA(b, h) + aoff + m * 2048 + k * 1024); } while (0)
; #define PG8_MMA(ai, bj, At, Bt) do { __builtin_amdgcn_s_setprio(1); _Pragma("unroll") for (int m = 0; m < 4; ++m) _Pragma("unroll") for (int n = 0; n < 2; ++n) _Pragma("unroll") for (int k = 0; k < 2; ++k) \
;         acc[ai][bj][m][n] = __builtin_amdgcn_mfma_f32_16x16x32_bf16(Bt[n][k], At[m][k], acc[ai][bj][m][n], 0, 0, 0); __builtin_amdgcn_s_setprio(0); } while (0)
; #define PG8_WAIT_V(n) asm volatile("s_waitcnt vmcnt(" #n ")" ::: "memory")
; #define PG8_WAIT_L(n) asm volatile("s_waitcnt lgkmcnt(" #n ")" ::: "memory")
; #define PG8_BAR __builtin_amdgcn_s_barrier()
; #define PG8_SCHED __builtin_amdgcn_sched_barrier(0)
; template <class Epi, class Sched, bool ATILE = false>
; __device__ __forceinline__ void gemm_phase(LAS unsigned char* lds, const Gemm g, const Sched& S, const Epi& E) {
;     ...
;             PG8_BAR; PG8_WAIT_L(0); PG8_MMA(0, 1, At, B1); PG8_BAR;
;             PG8_LDA(At, 1, 1); PG8_STAGE(PG8_SA(1, 0), a3, voffA);
;             PG8_BAR; PG8_WAIT_L(0); PG8_MMA(1, 0, At, B0); PG8_BAR; PG8_SCHED;
;             PG8_STAGE(PG8_SB(1, 1), b3 + hstepB, voffB);
;             PG8_WAIT_V(6); PG8_BAR; PG8_MMA(1, 1, At, B1); PG8_BAR;
;         }
	s_waitcnt lgkmcnt(0)
	s_setprio 1
	s_waitcnt lgkmcnt(0)
	v_mfma_f32_16x16x32_bf16 v[124:127], v[230:233], v[198:201], v[124:127]
	v_mfma_f32_16x16x32_bf16 v[116:119], v[238:241], v[198:201], v[116:119]
	v_mfma_f32_16x16x32_bf16 v[108:111], v[230:233], v[206:209], v[108:111]
	v_mfma_f32_16x16x32_bf16 v[100:103], v[238:241], v[206:209], v[100:103]
	v_mfma_f32_16x16x32_bf16 v[92:95], v[230:233], v[214:217], v[92:95]
	v_mfma_f32_16x16x32_bf16 v[84:87], v[238:241], v[214:217], v[84:87]
	v_mfma_f32_16x16x32_bf16 v[76:79], v[230:233], v[222:225], v[76:79]
	v_mfma_f32_16x16x32_bf16 v[68:71], v[238:241], v[222:225], v[68:71]
	v_mfma_f32_16x16x32_bf16 v[124:127], v[234:237], v[202:205], v[124:127]
	v_mfma_f32_16x16x32_bf16 v[116:119], v[242:245], v[202:205], v[116:119]
	v_mfma_f32_16x16x32_bf16 v[108:111], v[234:237], v[210:213], v[108:111]
	v_mfma_f32_16x16x32_bf16 v[100:103], v[242:245], v[210:213], v[100:103]
	v_mfma_f32_16x16x32_bf16 v[92:95], v[234:237], v[218:221], v[92:95]
	v_mfma_f32_16x16x32_bf16 v[84:87], v[242:245], v[218:221], v[84:87]
	v_mfma_f32_16x16x32_bf16 v[76:79], v[234:237], v[226:229], v[76:79]
	v_mfma_f32_16x16x32_bf16 v[68:71], v[242:245], v[226:229], v[68:71]
	s_setprio 0
	s_barrier
	s_mov_b32 m0, s41
	v_lshl_add_u64 v[246:247], v[250:251], 0, s[0:1]
	ds_read_b128 v[198:201], v163 offset:49152
	ds_read_b128 v[202:205], v163 offset:50176
	ds_read_b128 v[206:209], v163 offset:51200
	ds_read_b128 v[210:213], v163 offset:52224
	ds_read_b128 v[214:217], v163 offset:53248
	ds_read_b128 v[218:221], v163 offset:54272
	ds_read_b128 v[222:225], v163 offset:55296
	ds_read_b128 v[226:229], v163 offset:56320
	global_load_lds_dwordx4 v[246:247], off
	v_lshl_add_u64 v[246:247], v[252:253], 0, s[0:1]
	s_mov_b32 m0, s42
	s_nop 0
	global_load_lds_dwordx4 v[246:247], off
	s_barrier
	s_waitcnt lgkmcnt(0)
	s_setprio 1
	s_waitcnt lgkmcnt(0)
	v_mfma_f32_16x16x32_bf16 v[56:59], v[182:185], v[198:201], v[56:59]
	v_mfma_f32_16x16x32_bf16 v[48:51], v[190:193], v[198:201], v[48:51]
	v_mfma_f32_16x16x32_bf16 v[40:43], v[182:185], v[206:209], v[40:43]
	v_mfma_f32_16x16x32_bf16 v[32:35], v[190:193], v[206:209], v[32:35]
	v_mfma_f32_16x16x32_bf16 v[24:27], v[182:185], v[214:217], v[24:27]
	v_mfma_f32_16x16x32_bf16 v[16:19], v[190:193], v[214:217], v[16:19]
	v_mfma_f32_16x16x32_bf16 v[8:11], v[182:185], v[222:225], v[8:11]
	v_mfma_f32_16x16x32_bf16 v[4:7], v[190:193], v[222:225], v[4:7]
	v_mfma_f32_16x16x32_bf16 v[56:59], v[186:189], v[202:205], v[56:59]
	v_mfma_f32_16x16x32_bf16 v[48:51], v[194:197], v[202:205], v[48:51]
	v_mfma_f32_16x16x32_bf16 v[40:43], v[186:189], v[210:213], v[40:43]
	v_mfma_f32_16x16x32_bf16 v[32:35], v[194:197], v[210:213], v[32:35]
	v_mfma_f32_16x16x32_bf16 v[24:27], v[186:189], v[218:221], v[24:27]
	v_mfma_f32_16x16x32_bf16 v[16:19], v[194:197], v[218:221], v[16:19]
	v_mfma_f32_16x16x32_bf16 v[8:11], v[186:189], v[226:229], v[8:11]
	v_mfma_f32_16x16x32_bf16 v[4:7], v[194:197], v[226:229], v[4:7]
	s_setprio 0
	s_barrier
	s_add_u32 s28, s28, 0x80080
	s_addc_u32 s29, s29, 0
	s_add_i32 s30, s30, s34
	s_mov_b32 m0, s30
	s_nop 0
	global_load_lds_dwordx4 v130, s[28:29]
	s_add_i32 m0, s30, 0x2000
	s_nop 0
	global_load_lds_dwordx4 v134, s[28:29]
	s_waitcnt vmcnt(6)
	s_barrier
	s_setprio 1
	v_mfma_f32_16x16x32_bf16 v[60:63], v[230:233], v[198:201], v[60:63]
	v_mfma_f32_16x16x32_bf16 v[52:55], v[238:241], v[198:201], v[52:55]
	v_mfma_f32_16x16x32_bf16 v[44:47], v[230:233], v[206:209], v[44:47]
	v_mfma_f32_16x16x32_bf16 v[36:39], v[238:241], v[206:209], v[36:39]
	v_mfma_f32_16x16x32_bf16 v[28:31], v[230:233], v[214:217], v[28:31]
	v_mfma_f32_16x16x32_bf16 v[20:23], v[238:241], v[214:217], v[20:23]
	v_mfma_f32_16x16x32_bf16 v[12:15], v[230:233], v[222:225], v[12:15]
	v_mfma_f32_16x16x32_bf16 v[0:3], v[238:241], v[222:225], v[0:3]
	v_mfma_f32_16x16x32_bf16 v[60:63], v[234:237], v[202:205], v[60:63]
	v_mfma_f32_16x16x32_bf16 v[52:55], v[242:245], v[202:205], v[52:55]
	v_mfma_f32_16x16x32_bf16 v[44:47], v[234:237], v[210:213], v[44:47]
	v_mfma_f32_16x16x32_bf16 v[36:39], v[242:245], v[210:213], v[36:39]
	v_mfma_f32_16x16x32_bf16 v[28:31], v[234:237], v[218:221], v[28:31]
	v_mfma_f32_16x16x32_bf16 v[20:23], v[242:245], v[218:221], v[20:23]
	v_mfma_f32_16x16x32_bf16 v[12:15], v[234:237], v[226:229], v[12:15]
	v_mfma_f32_16x16x32_bf16 v[0:3], v[242:245], v[226:229], v[0:3]
	s_setprio 0
	s_barrier
	s_add_u32 s26, s26, 0x100
	s_addc_u32 s27, s27, 0
	s_add_u32 s60, s60, 0x100
	s_addc_u32 s61, s61, 0
	s_cmp_ge_i32 s62, s11
	s_mov_b32 s28, s62
	s_cbranch_scc0 .LBB0_625
	s_branch .LBB0_616

; #define PG8_STAGE(bufoff, gbase, voff) do { _Pragma("unroll") for (int _i = 0; _i < 2; ++_i) \
;         __builtin_amdgcn_global_load_lds((const unsigned*)((const char*)(gbase) + (voff)[_i]), (LAS unsigned*)(lds + (bufoff) + ldsw + _i * 8192), 16, 0, 0); } while (0)
; #define PG8_LDA(dst, b, h) do { _Pragma("unroll") for (int m = 0; m < 4; ++m) _Pragma("unroll") for (int k = 0; k < 2; ++k) dst[m][k] = *(const LAS bf16x8*)(lds + PG8_SA(b, h) + aoff + m * 2048 + k * 1024); } while (0)
; #define PG8_LDB(dst, b, h) do { _Pragma("unroll") for (int n = 0; n < 2; ++n) _Pragma("unroll") for (int k = 0; k < 2; ++k) dst[n][k] = *(const LAS bf16x8*)(lds + PG8_SB(b, h) + boff + n * 2048 + k * 1024); } while (0)
; #define PG8_MMA(ai, bj, At, Bt) do { __builtin_amdgcn_s_setprio(1); _Pragma("unroll") for (int m = 0; m < 4; ++m) _Pragma("unroll") for (int n = 0; n < 2; ++n) _Pragma("unroll") for (int k = 0; k < 2; ++k) \
;         acc[ai][bj][m][n] = __builtin_amdgcn_mfma_f32_16x16x32_bf16(Bt[n][k], At[m][k], acc[ai][bj][m][n], 0, 0, 0); __builtin_amdgcn_s_setprio(0); } while (0)
; #define PG8_WAIT_V(n) asm volatile("s_waitcnt vmcnt(" #n ")" ::: "memory")
; #define PG8_WAIT_L(n) asm volatile("s_waitcnt lgkmcnt(" #n ")" ::: "memory")
; template <class Epi, class Sched, bool ATILE = false>
; __device__ __forceinline__ void gemm_phase(LAS unsigned char* lds, const Gemm g, const Sched& S, const Epi& E) {
;     ...
;         for (int t = 0; t < nt; t += 2) {
;             const bool last = (t == nt - 2);
;             const char* a1 = cA + (size_t)(t + 1) * kstepA;
;             const char* a2 = last ? nA : cA + (size_t)(t + 2) * kstepA; const char* b2 = last ? nB : cB + (size_t)(t + 2) * kstep;
;             const char* a3 = a2 + kstepA; const char* b3 = b2 + kstep;
;             PG8_LDB(B0, 0, 0); PG8_SCHED; PG8_LDA(At, 0, 0); PG8_STAGE(PG8_SA(1, 1), a1 + hstepA, voffA);
;             PG8_WAIT_L(8); PG8_BAR; PG8_WAIT_L(0); PG8_MMA(0, 0, At, B0); PG8_BAR; PG8_SCHED;
;             PG8_LDB(B1, 0, 1); PG8_STAGE(PG8_SB(0, 0), b2, voffB);
;             PG8_BAR; PG8_WAIT_L(0); PG8_MMA(0, 1, At, B1); PG8_BAR;
;             PG8_LDA(At, 0, 1); PG8_STAGE(PG8_SA(0, 0), a2, voffA);
;             PG8_BAR; PG8_WAIT_L(0); PG8_MMA(1, 0, At, B0); PG8_BAR; PG8_SCHED;
;             PG8_STAGE(PG8_SB(0, 1), b2 + hstepB, voffB);
;             PG8_WAIT_V(6); PG8_BAR; PG8_MMA(1, 1, At, B1); PG8_BAR;
.LBB0_739:
	ds_read_b128 v[20:23], v165
	ds_read_b128 v[28:31], v165 offset:1024
	ds_read_b128 v[136:139], v165 offset:2048
	ds_read_b128 v[140:143], v165 offset:3072
	s_add_i32 s62, s26, 2
	s_add_u32 s27, s24, 0x4000
	s_addc_u32 s28, s25, 0
	s_cmp_eq_u32 s11, s26
	s_cselect_b32 s30, s20, s27
	s_cselect_b32 s31, s21, s28
	s_cselect_b32 s26, s22, s60
	s_cselect_b32 s27, s23, s61
	s_add_u32 s28, s30, 0x8000
	s_addc_u32 s29, s31, 0
	s_add_i32 m0, s34, 0xc000
	ds_read_b128 v[144:147], v167
	ds_read_b128 v[148:151], v167 offset:1024
	ds_read_b128 v[200:203], v167 offset:2048
	ds_read_b128 v[204:207], v167 offset:3072
	ds_read_b128 v[208:211], v167 offset:4096
	ds_read_b128 v[212:215], v167 offset:5120
	ds_read_b128 v[220:223], v167 offset:6144
	ds_read_b128 v[224:227], v167 offset:7168
	global_load_lds_dwordx4 v194, s[24:25]
	s_add_i32 m0, s34, 0xe000
	s_nop 0
	global_load_lds_dwordx4 v196, s[24:25]
	s_waitcnt lgkmcnt(8)
	s_barrier
	s_waitcnt lgkmcnt(0)
	s_setprio 1
	s_waitcnt lgkmcnt(0)
	v_mfma_f32_16x16x32_bf16 v[0:3], v[20:23], v[144:147], v[0:3]
	v_mfma_f32_16x16x32_bf16 v[4:7], v[136:139], v[144:147], v[4:7]
	v_mfma_f32_16x16x32_bf16 v[44:47], v[20:23], v[200:203], v[44:47]
	v_mfma_f32_16x16x32_bf16 v[36:39], v[136:139], v[200:203], v[36:39]
	v_mfma_f32_16x16x32_bf16 v[52:55], v[20:23], v[208:211], v[52:55]
	v_mfma_f32_16x16x32_bf16 v[48:51], v[136:139], v[208:211], v[48:51]
	v_mfma_f32_16x16x32_bf16 v[92:95], v[20:23], v[220:223], v[92:95]
	v_mfma_f32_16x16x32_bf16 v[84:87], v[136:139], v[220:223], v[84:87]
	v_mfma_f32_16x16x32_bf16 v[0:3], v[28:31], v[148:151], v[0:3]
	v_mfma_f32_16x16x32_bf16 v[4:7], v[140:143], v[148:151], v[4:7]
	v_mfma_f32_16x16x32_bf16 v[44:47], v[28:31], v[204:207], v[44:47]
	v_mfma_f32_16x16x32_bf16 v[36:39], v[140:143], v[204:207], v[36:39]
	v_mfma_f32_16x16x32_bf16 v[52:55], v[28:31], v[212:215], v[52:55]
	v_mfma_f32_16x16x32_bf16 v[48:51], v[140:143], v[212:215], v[48:51]
	v_mfma_f32_16x16x32_bf16 v[92:95], v[28:31], v[224:227], v[92:95]
	v_mfma_f32_16x16x32_bf16 v[84:87], v[140:143], v[224:227], v[84:87]
	s_setprio 0
	s_barrier
	s_add_i32 s63, s52, s33
	v_lshl_add_u64 v[216:217], s[26:27], 0, v[170:171]
	s_mov_b32 m0, s63
	ds_read_b128 v[228:231], v177
	ds_read_b128 v[232:235], v177 offset:1024
	ds_read_b128 v[236:239], v177 offset:2048
	ds_read_b128 v[240:243], v177 offset:3072
	global_load_lds_dwordx4 v[216:217], off
	v_lshl_add_u64 v[244:245], s[26:27], 0, v[174:175]
	s_add_i32 m0, s63, 0x2000
	s_nop 0
	global_load_lds_dwordx4 v[244:245], off
	s_barrier
	s_waitcnt lgkmcnt(0)
	s_setprio 1
	s_waitcnt lgkmcnt(0)
	v_mfma_f32_16x16x32_bf16 v[12:15], v[228:231], v[144:147], v[12:15]
	v_mfma_f32_16x16x32_bf16 v[8:11], v[236:239], v[144:147], v[8:11]
	v_mfma_f32_16x16x32_bf16 v[24:27], v[228:231], v[200:203], v[24:27]
	v_mfma_f32_16x16x32_bf16 v[16:19], v[236:239], v[200:203], v[16:19]
	v_mfma_f32_16x16x32_bf16 v[40:43], v[228:231], v[208:211], v[40:43]
	v_mfma_f32_16x16x32_bf16 v[32:35], v[236:239], v[208:211], v[32:35]
	v_mfma_f32_16x16x32_bf16 v[56:59], v[228:231], v[220:223], v[56:59]
	v_mfma_f32_16x16x32_bf16 v[60:63], v[236:239], v[220:223], v[60:63]
	v_mfma_f32_16x16x32_bf16 v[12:15], v[232:235], v[148:151], v[12:15]
	v_mfma_f32_16x16x32_bf16 v[8:11], v[240:243], v[148:151], v[8:11]
	v_mfma_f32_16x16x32_bf16 v[24:27], v[232:235], v[204:207], v[24:27]
	v_mfma_f32_16x16x32_bf16 v[16:19], v[240:243], v[204:207], v[16:19]
	v_mfma_f32_16x16x32_bf16 v[40:43], v[232:235], v[212:215], v[40:43]
	v_mfma_f32_16x16x32_bf16 v[32:35], v[240:243], v[212:215], v[32:35]
	v_mfma_f32_16x16x32_bf16 v[56:59], v[232:235], v[224:227], v[56:59]
	v_mfma_f32_16x16x32_bf16 v[60:63], v[240:243], v[224:227], v[60:63]
	s_setprio 0
	s_barrier
	s_mov_b32 m0, s34
	ds_read_b128 v[144:147], v167 offset:16384
	ds_read_b128 v[148:151], v167 offset:17408
	ds_read_b128 v[200:203], v167 offset:18432
	ds_read_b128 v[204:207], v167 offset:19456
	ds_read_b128 v[208:211], v167 offset:20480
	ds_read_b128 v[212:215], v167 offset:21504
	ds_read_b128 v[220:223], v167 offset:22528
	ds_read_b128 v[224:227], v167 offset:23552
	global_load_lds_dwordx4 v168, s[30:31]
	s_mov_b32 m0, s35
	s_nop 0
	global_load_lds_dwordx4 v172, s[30:31]
	s_barrier
	s_waitcnt lgkmcnt(0)
	s_setprio 1
	s_waitcnt lgkmcnt(0)
	v_mfma_f32_16x16x32_bf16 v[64:67], v[20:23], v[144:147], v[64:67]
	v_mfma_f32_16x16x32_bf16 v[68:71], v[136:139], v[144:147], v[68:71]
	v_mfma_f32_16x16x32_bf16 v[108:111], v[20:23], v[200:203], v[108:111]
	v_mfma_f32_16x16x32_bf16 v[100:103], v[136:139], v[200:203], v[100:103]
	v_mfma_f32_16x16x32_bf16 v[116:119], v[20:23], v[208:211], v[116:119]
	v_mfma_f32_16x16x32_bf16 v[112:115], v[136:139], v[208:211], v[112:115]
	v_mfma_f32_16x16x32_bf16 v[20:23], v[20:23], v[220:223], v[132:135]
	v_mfma_f32_16x16x32_bf16 v[64:67], v[28:31], v[148:151], v[64:67]
	v_mfma_f32_16x16x32_bf16 v[68:71], v[140:143], v[148:151], v[68:71]
	v_mfma_f32_16x16x32_bf16 v[108:111], v[28:31], v[204:207], v[108:111]
	v_mfma_f32_16x16x32_bf16 v[100:103], v[140:143], v[204:207], v[100:103]
	v_mfma_f32_16x16x32_bf16 v[116:119], v[28:31], v[212:215], v[116:119]
	v_mfma_f32_16x16x32_bf16 v[112:115], v[140:143], v[212:215], v[112:115]
	v_mfma_f32_16x16x32_bf16 v[20:23], v[28:31], v[224:227], v[20:23]
	v_mfma_f32_16x16x32_bf16 v[28:31], v[136:139], v[220:223], v[128:131]
	v_mfma_f32_16x16x32_bf16 v[28:31], v[140:143], v[224:227], v[28:31]
	s_setprio 0
	s_barrier
	s_add_u32 s64, s26, 0x158000
	s_addc_u32 s65, s27, 0
	s_add_i32 s63, s53, s33
	s_mov_b32 m0, s63
	s_nop 0
	global_load_lds_dwordx4 v170, s[64:65]
	s_add_i32 m0, s63, 0x2000
	s_nop 0
	global_load_lds_dwordx4 v174, s[64:65]
	s_waitcnt vmcnt(6)
	s_barrier
; #define PG8_STAGE(bufoff, gbase, voff) do { _Pragma("unroll") for (int _i = 0; _i < 2; ++_i) \
;         __builtin_amdgcn_global_load_lds((const unsigned*)((const char*)(gbase) + (voff)[_i]), (LAS unsigned*)(lds + (bufoff) + ldsw + _i * 8192), 16, 0, 0); } while (0)
; #define PG8_LDA(dst, b, h) do { _Pragma("unroll") for (int m = 0; m < 4; ++m) _Pragma("unroll") for (int k = 0; k < 2; ++k) dst[m][k] = *(const LAS bf16x8*)(lds + PG8_SA(b, h) + aoff + m * 2048 + k * 1024); } while (0)
; #define PG8_LDB(dst, b, h) do { _Pragma("unroll") for (int n = 0; n < 2; ++n) _Pragma("unroll") for (int k = 0; k < 2; ++k) dst[n][k] = *(const LAS bf16x8*)(lds + PG8_SB(b, h) + boff + n * 2048 + k * 1024); } while (0)
; #define PG8_MMA(ai, bj, At, Bt) do { __builtin_amdgcn_s_setprio(1); _Pragma("unroll") for (int m = 0; m < 4; ++m) _Pragma("unroll") for (int n = 0; n < 2; ++n) _Pragma("unroll") for (int k = 0; k < 2; ++k) \
;         acc[ai][bj][m][n] = __builtin_amdgcn_mfma_f32_16x16x32_bf16(Bt[n][k], At[m][k], acc[ai][bj][m][n], 0, 0, 0); __builtin_amdgcn_s_setprio(0); } while (0)
; #define PG8_WAIT_V(n) asm volatile("s_waitcnt vmcnt(" #n ")" ::: "memory")
; #define PG8_WAIT_L(n) asm volatile("s_waitcnt lgkmcnt(" #n ")" ::: "memory")
; #define PG8_BAR __builtin_amdgcn_s_barrier()
; #define PG8_SCHED __builtin_amdgcn_sched_barrier(0)
; template <class Epi, class Sched, bool ATILE = false>
; __device__ __forceinline__ void gemm_phase(LAS unsigned char* lds, const Gemm g, const Sched& S, const Epi& E) {
;     ...
;             PG8_WAIT_V(6); PG8_BAR; PG8_MMA(1, 1, At, B1); PG8_BAR;
;             PG8_LDB(B0, 1, 0); PG8_SCHED; PG8_LDA(At, 1, 0); PG8_STAGE(PG8_SA(0, 1), a2 + hstepA, voffA);
;             PG8_WAIT_L(8); PG8_BAR; PG8_WAIT_L(0); PG8_MMA(0, 0, At, B0); PG8_BAR; PG8_SCHED;
;             PG8_LDB(B1, 1, 1); PG8_STAGE(PG8_SB(1, 0), b3, voffB);
;             PG8_BAR; PG8_WAIT_L(0); PG8_MMA(0, 1, At, B1); PG8_BAR;
;             PG8_LDA(At, 1, 1); PG8_STAGE(PG8_SA(1, 0), a3, voffA);
	s_setprio 1
	v_mfma_f32_16x16x32_bf16 v[76:79], v[228:231], v[144:147], v[76:79]
	v_mfma_f32_16x16x32_bf16 v[72:75], v[236:239], v[144:147], v[72:75]
	v_mfma_f32_16x16x32_bf16 v[88:91], v[228:231], v[200:203], v[88:91]
	v_mfma_f32_16x16x32_bf16 v[80:83], v[236:239], v[200:203], v[80:83]
	v_mfma_f32_16x16x32_bf16 v[104:107], v[228:231], v[208:211], v[104:107]
	v_mfma_f32_16x16x32_bf16 v[96:99], v[236:239], v[208:211], v[96:99]
	v_mfma_f32_16x16x32_bf16 v[120:123], v[228:231], v[220:223], v[120:123]
	v_mfma_f32_16x16x32_bf16 v[124:127], v[236:239], v[220:223], v[124:127]
	v_mfma_f32_16x16x32_bf16 v[76:79], v[232:235], v[148:151], v[76:79]
	v_mfma_f32_16x16x32_bf16 v[72:75], v[240:243], v[148:151], v[72:75]
	v_mfma_f32_16x16x32_bf16 v[88:91], v[232:235], v[204:207], v[88:91]
	v_mfma_f32_16x16x32_bf16 v[80:83], v[240:243], v[204:207], v[80:83]
	v_mfma_f32_16x16x32_bf16 v[104:107], v[232:235], v[212:215], v[104:107]
	v_mfma_f32_16x16x32_bf16 v[96:99], v[240:243], v[212:215], v[96:99]
	v_mfma_f32_16x16x32_bf16 v[120:123], v[232:235], v[224:227], v[120:123]
	v_mfma_f32_16x16x32_bf16 v[124:127], v[240:243], v[224:227], v[124:127]
	s_setprio 0
	s_barrier
	s_add_i32 s63, 0, 0x18000
	v_add_u32_e32 v140, s63, v161
	ds_read_b128 v[128:131], v140
	ds_read_b128 v[132:135], v140 offset:1024
	ds_read_b128 v[136:139], v140 offset:2048
	ds_read_b128 v[140:143], v140 offset:3072
	s_add_u32 s30, s30, 0x4000
	s_addc_u32 s31, s31, 0
	s_mov_b32 m0, s36
	ds_read_b128 v[144:147], v167 offset:32768
	ds_read_b128 v[148:151], v167 offset:33792
	ds_read_b128 v[200:203], v167 offset:34816
	ds_read_b128 v[204:207], v167 offset:35840
	ds_read_b128 v[208:211], v167 offset:36864
	ds_read_b128 v[212:215], v167 offset:37888
	ds_read_b128 v[220:223], v167 offset:38912
	ds_read_b128 v[224:227], v167 offset:39936
	global_load_lds_dwordx4 v168, s[30:31]
	s_mov_b32 m0, s37
	s_nop 0
	global_load_lds_dwordx4 v172, s[30:31]
	s_waitcnt lgkmcnt(8)
	s_barrier
	s_waitcnt lgkmcnt(0)
	s_setprio 1
	s_waitcnt lgkmcnt(0)
	v_mfma_f32_16x16x32_bf16 v[0:3], v[128:131], v[144:147], v[0:3]
	v_mfma_f32_16x16x32_bf16 v[4:7], v[136:139], v[144:147], v[4:7]
	v_mfma_f32_16x16x32_bf16 v[44:47], v[128:131], v[200:203], v[44:47]
	v_mfma_f32_16x16x32_bf16 v[36:39], v[136:139], v[200:203], v[36:39]
	v_mfma_f32_16x16x32_bf16 v[52:55], v[128:131], v[208:211], v[52:55]
	v_mfma_f32_16x16x32_bf16 v[48:51], v[136:139], v[208:211], v[48:51]
	v_mfma_f32_16x16x32_bf16 v[92:95], v[128:131], v[220:223], v[92:95]
	v_mfma_f32_16x16x32_bf16 v[84:87], v[136:139], v[220:223], v[84:87]
	v_mfma_f32_16x16x32_bf16 v[0:3], v[132:135], v[148:151], v[0:3]
	v_mfma_f32_16x16x32_bf16 v[4:7], v[140:143], v[148:151], v[4:7]
	v_mfma_f32_16x16x32_bf16 v[44:47], v[132:135], v[204:207], v[44:47]
	v_mfma_f32_16x16x32_bf16 v[36:39], v[140:143], v[204:207], v[36:39]
	v_mfma_f32_16x16x32_bf16 v[52:55], v[132:135], v[212:215], v[52:55]
	v_mfma_f32_16x16x32_bf16 v[48:51], v[140:143], v[212:215], v[48:51]
	v_mfma_f32_16x16x32_bf16 v[92:95], v[132:135], v[224:227], v[92:95]
	v_mfma_f32_16x16x32_bf16 v[84:87], v[140:143], v[224:227], v[84:87]
	s_setprio 0
	s_barrier
	s_add_i32 s30, 0, 0x1c000
	s_add_i32 s31, s63, s33
	v_add_u32_e32 v219, s30, v161
	v_lshl_add_u64 v[216:217], v[216:217], 0, s[6:7]
	s_mov_b32 m0, s31
	ds_read_b128 v[228:231], v219
	ds_read_b128 v[232:235], v219 offset:1024
	ds_read_b128 v[236:239], v219 offset:2048
	ds_read_b128 v[240:243], v219 offset:3072
	global_load_lds_dwordx4 v[216:217], off
	v_lshl_add_u64 v[216:217], v[244:245], 0, s[6:7]
	s_add_i32 m0, s31, 0x2000
	s_nop 0
	global_load_lds_dwordx4 v[216:217], off
	s_barrier
	s_waitcnt lgkmcnt(0)
	s_setprio 1
	s_waitcnt lgkmcnt(0)
	v_mfma_f32_16x16x32_bf16 v[12:15], v[228:231], v[144:147], v[12:15]
	v_mfma_f32_16x16x32_bf16 v[8:11], v[236:239], v[144:147], v[8:11]
	v_mfma_f32_16x16x32_bf16 v[24:27], v[228:231], v[200:203], v[24:27]
	v_mfma_f32_16x16x32_bf16 v[16:19], v[236:239], v[200:203], v[16:19]
	v_mfma_f32_16x16x32_bf16 v[40:43], v[228:231], v[208:211], v[40:43]
	v_mfma_f32_16x16x32_bf16 v[32:35], v[236:239], v[208:211], v[32:35]
	v_mfma_f32_16x16x32_bf16 v[56:59], v[228:231], v[220:223], v[56:59]
	v_mfma_f32_16x16x32_bf16 v[60:63], v[236:239], v[220:223], v[60:63]
	v_mfma_f32_16x16x32_bf16 v[12:15], v[232:235], v[148:151], v[12:15]
	v_mfma_f32_16x16x32_bf16 v[8:11], v[240:243], v[148:151], v[8:11]
	v_mfma_f32_16x16x32_bf16 v[24:27], v[232:235], v[204:207], v[24:27]
	v_mfma_f32_16x16x32_bf16 v[16:19], v[240:243], v[204:207], v[16:19]
	v_mfma_f32_16x16x32_bf16 v[40:43], v[232:235], v[212:215], v[40:43]
	v_mfma_f32_16x16x32_bf16 v[32:35], v[240:243], v[212:215], v[32:35]
	v_mfma_f32_16x16x32_bf16 v[56:59], v[232:235], v[224:227], v[56:59]
	v_mfma_f32_16x16x32_bf16 v[60:63], v[240:243], v[224:227], v[60:63]
	s_setprio 0
	s_barrier
	s_mov_b32 m0, s39
	ds_read_b128 v[144:147], v167 offset:49152
	ds_read_b128 v[148:151], v167 offset:50176
	ds_read_b128 v[200:203], v167 offset:51200
	ds_read_b128 v[204:207], v167 offset:52224
	ds_read_b128 v[208:211], v167 offset:53248
	ds_read_b128 v[212:215], v167 offset:54272
	ds_read_b128 v[220:223], v167 offset:55296
	ds_read_b128 v[224:227], v167 offset:56320
	global_load_lds_dwordx4 v168, s[28:29]
	s_mov_b32 m0, s40
	s_nop 0
	global_load_lds_dwordx4 v172, s[28:29]
	s_barrier
; __device__ __forceinline__ float bflo(unsigned w) { return __uint_as_float(w << 16); }
; __device__ __forceinline__ float bfhi(unsigned w) { return __uint_as_float(w & 0xffff0000u); }
; #define PG8_STAGE(bufoff, gbase, voff) do { _Pragma("unroll") for (int _i = 0; _i < 2; ++_i) \
;         __builtin_amdgcn_global_load_lds((const unsigned*)((const char*)(gbase) + (voff)[_i]), (LAS unsigned*)(lds + (bufoff) + ldsw + _i * 8192), 16, 0, 0); } while (0)
; #define PG8_MMA(ai, bj, At, Bt) do { __builtin_amdgcn_s_setprio(1); _Pragma("unroll") for (int m = 0; m < 4; ++m) _Pragma("unroll") for (int n = 0; n < 2; ++n) _Pragma("unroll") for (int k = 0; k < 2; ++k) \
;         acc[ai][bj][m][n] = __builtin_amdgcn_mfma_f32_16x16x32_bf16(Bt[n][k], At[m][k], acc[ai][bj][m][n], 0, 0, 0); __builtin_amdgcn_s_setprio(0); } while (0)
; #define PG8_WAIT_V(n) asm volatile("s_waitcnt vmcnt(" #n ")" ::: "memory")
; #define PG8_WAIT_L(n) asm volatile("s_waitcnt lgkmcnt(" #n ")" ::: "memory")
; #define PG8_BAR __builtin_amdgcn_s_barrier()
; #define PG8_SCHED __builtin_amdgcn_sched_barrier(0)
; template <class Epi, class Sched, bool ATILE = false>
; __device__ __forceinline__ void gemm_phase(LAS unsigned char* lds, const Gemm g, const Sched& S, const Epi& E) {
;     ...
;             PG8_BAR; PG8_WAIT_L(0); PG8_MMA(1, 0, At, B0); PG8_BAR; PG8_SCHED;
;             PG8_STAGE(PG8_SB(1, 1), b3 + hstepB, voffB);
;             PG8_WAIT_V(6); PG8_BAR; PG8_MMA(1, 1, At, B1); PG8_BAR;
;     __device__ __forceinline__ void operator()(const f32x4 (&acc)[2][2][4][2], const Unit& u, int wr, int wc, int fr, int fq) const {
;     ...
;                     const f32x4 v0 = (f32x4){bflo(x.x), bfhi(x.x), bflo(x.y), bfhi(x.y)} + alpha * acc[ai][bj][m][0];
;                     const f32x4 v1 = (f32x4){bflo(x.z), bfhi(x.z), bflo(x.w), bfhi(x.w)} + alpha * acc[ai][bj][m][1];
	s_waitcnt lgkmcnt(0)
	s_setprio 1
	s_waitcnt lgkmcnt(0)
	v_mfma_f32_16x16x32_bf16 v[64:67], v[128:131], v[144:147], v[64:67]
	v_mfma_f32_16x16x32_bf16 v[108:111], v[128:131], v[200:203], v[108:111]
	v_mfma_f32_16x16x32_bf16 v[116:119], v[128:131], v[208:211], v[116:119]
	v_mfma_f32_16x16x32_bf16 v[20:23], v[128:131], v[220:223], v[20:23]
	v_mfma_f32_16x16x32_bf16 v[64:67], v[132:135], v[148:151], v[64:67]
	v_mfma_f32_16x16x32_bf16 v[68:71], v[136:139], v[144:147], v[68:71]
	v_mfma_f32_16x16x32_bf16 v[108:111], v[132:135], v[204:207], v[108:111]
	v_mfma_f32_16x16x32_bf16 v[100:103], v[136:139], v[200:203], v[100:103]
	v_mfma_f32_16x16x32_bf16 v[116:119], v[132:135], v[212:215], v[116:119]
	v_mfma_f32_16x16x32_bf16 v[112:115], v[136:139], v[208:211], v[112:115]
	v_mfma_f32_16x16x32_bf16 v[132:135], v[132:135], v[224:227], v[20:23]
	v_mfma_f32_16x16x32_bf16 v[20:23], v[136:139], v[220:223], v[28:31]
	v_mfma_f32_16x16x32_bf16 v[68:71], v[140:143], v[148:151], v[68:71]
	v_mfma_f32_16x16x32_bf16 v[100:103], v[140:143], v[204:207], v[100:103]
	v_mfma_f32_16x16x32_bf16 v[112:115], v[140:143], v[212:215], v[112:115]
	v_mfma_f32_16x16x32_bf16 v[128:131], v[140:143], v[224:227], v[20:23]
	s_setprio 0
	s_barrier
	s_add_u32 s26, s26, 0x158080
	s_addc_u32 s27, s27, 0
	s_add_i32 s28, s30, s33
	s_mov_b32 m0, s28
	s_nop 0
	global_load_lds_dwordx4 v170, s[26:27]
	v_lshl_add_u64 v[20:21], s[26:27], 0, v[174:175]
	s_add_i32 m0, s28, 0x2000
	s_nop 0
	global_load_lds_dwordx4 v[20:21], off
	s_waitcnt vmcnt(6)
	s_barrier
	s_setprio 1
	v_mfma_f32_16x16x32_bf16 v[20:23], v[228:231], v[144:147], v[76:79]
	v_mfma_f32_16x16x32_bf16 v[76:79], v[232:235], v[148:151], v[20:23]
	v_mfma_f32_16x16x32_bf16 v[20:23], v[236:239], v[144:147], v[72:75]
	v_mfma_f32_16x16x32_bf16 v[72:75], v[240:243], v[148:151], v[20:23]
	v_mfma_f32_16x16x32_bf16 v[20:23], v[228:231], v[200:203], v[88:91]
	v_mfma_f32_16x16x32_bf16 v[88:91], v[232:235], v[204:207], v[20:23]
	v_mfma_f32_16x16x32_bf16 v[20:23], v[236:239], v[200:203], v[80:83]
	v_mfma_f32_16x16x32_bf16 v[80:83], v[240:243], v[204:207], v[20:23]
	v_mfma_f32_16x16x32_bf16 v[20:23], v[228:231], v[208:211], v[104:107]
	v_mfma_f32_16x16x32_bf16 v[104:107], v[232:235], v[212:215], v[20:23]
	v_mfma_f32_16x16x32_bf16 v[20:23], v[236:239], v[208:211], v[96:99]
	v_mfma_f32_16x16x32_bf16 v[96:99], v[240:243], v[212:215], v[20:23]
	v_mfma_f32_16x16x32_bf16 v[20:23], v[228:231], v[220:223], v[120:123]
	v_mfma_f32_16x16x32_bf16 v[120:123], v[232:235], v[224:227], v[20:23]
	v_mfma_f32_16x16x32_bf16 v[20:23], v[236:239], v[220:223], v[124:127]
	v_mfma_f32_16x16x32_bf16 v[124:127], v[240:243], v[224:227], v[20:23]
	s_setprio 0
	s_barrier
	s_add_u32 s60, s60, 0x100
	s_addc_u32 s61, s61, 0
	s_add_u32 s24, s24, 0x10000
	s_addc_u32 s25, s25, 0
	s_cmp_ge_i32 s62, s59
	s_mov_b32 s26, s62
	s_cbranch_scc0 .LBB0_739
	v_pk_mul_f32 v[2:3], v[2:3], 0.5 op_sel_hi:[1,0]
	v_pk_mul_f32 v[0:1], v[0:1], 0.5 op_sel_hi:[1,0]
	v_pk_mul_f32 v[6:7], v[6:7], 0.5 op_sel_hi:[1,0]
	v_pk_mul_f32 v[4:5], v[4:5], 0.5 op_sel_hi:[1,0]
	v_pk_mul_f32 v[22:23], v[14:15], 0.5 op_sel_hi:[1,0]
	v_pk_mul_f32 v[20:21], v[12:13], 0.5 op_sel_hi:[1,0]
	v_pk_mul_f32 v[30:31], v[10:11], 0.5 op_sel_hi:[1,0]
	v_pk_mul_f32 v[28:29], v[8:9], 0.5 op_sel_hi:[1,0]
	v_pk_mul_f32 v[10:11], v[46:47], 0.5 op_sel_hi:[1,0]
	v_pk_mul_f32 v[8:9], v[44:45], 0.5 op_sel_hi:[1,0]
	v_pk_mul_f32 v[14:15], v[38:39], 0.5 op_sel_hi:[1,0]
	v_pk_mul_f32 v[12:13], v[36:37], 0.5 op_sel_hi:[1,0]
	v_pk_mul_f32 v[38:39], v[26:27], 0.5 op_sel_hi:[1,0]
	v_pk_mul_f32 v[36:37], v[24:25], 0.5 op_sel_hi:[1,0]
	v_pk_mul_f32 v[46:47], v[18:19], 0.5 op_sel_hi:[1,0]
	v_pk_mul_f32 v[44:45], v[16:17], 0.5 op_sel_hi:[1,0]
	v_pk_mul_f32 v[18:19], v[54:55], 0.5 op_sel_hi:[1,0]
	v_pk_mul_f32 v[16:17], v[52:53], 0.5 op_sel_hi:[1,0]
	v_pk_mul_f32 v[26:27], v[50:51], 0.5 op_sel_hi:[1,0]
	v_pk_mul_f32 v[24:25], v[48:49], 0.5 op_sel_hi:[1,0]
	v_pk_mul_f32 v[50:51], v[42:43], 0.5 op_sel_hi:[1,0]
	v_pk_mul_f32 v[48:49], v[40:41], 0.5 op_sel_hi:[1,0]
	v_pk_mul_f32 v[54:55], v[34:35], 0.5 op_sel_hi:[1,0]
	v_pk_mul_f32 v[52:53], v[32:33], 0.5 op_sel_hi:[1,0]
	v_pk_mul_f32 v[34:35], v[94:95], 0.5 op_sel_hi:[1,0]
	v_pk_mul_f32 v[32:33], v[92:93], 0.5 op_sel_hi:[1,0]
	v_pk_mul_f32 v[42:43], v[86:87], 0.5 op_sel_hi:[1,0]
	v_pk_mul_f32 v[40:41], v[84:85], 0.5 op_sel_hi:[1,0]
	v_pk_mul_f32 v[58:59], v[58:59], 0.5 op_sel_hi:[1,0]
	v_pk_mul_f32 v[56:57], v[56:57], 0.5 op_sel_hi:[1,0]
	v_pk_mul_f32 v[62:63], v[62:63], 0.5 op_sel_hi:[1,0]
	v_pk_mul_f32 v[60:61], v[60:61], 0.5 op_sel_hi:[1,0]
	v_pk_mul_f32 v[66:67], v[66:67], 0.5 op_sel_hi:[1,0]
	v_pk_mul_f32 v[64:65], v[64:65], 0.5 op_sel_hi:[1,0]
	v_pk_mul_f32 v[70:71], v[70:71], 0.5 op_sel_hi:[1,0]
	v_pk_mul_f32 v[68:69], v[68:69], 0.5 op_sel_hi:[1,0]
	v_pk_mul_f32 v[86:87], v[78:79], 0.5 op_sel_hi:[1,0]
	v_pk_mul_f32 v[84:85], v[76:77], 0.5 op_sel_hi:[1,0]
	v_pk_mul_f32 v[94:95], v[74:75], 0.5 op_sel_hi:[1,0]
	v_pk_mul_f32 v[92:93], v[72:73], 0.5 op_sel_hi:[1,0]
	v_pk_mul_f32 v[74:75], v[110:111], 0.5 op_sel_hi:[1,0]
	v_pk_mul_f32 v[72:73], v[108:109], 0.5 op_sel_hi:[1,0]
	v_pk_mul_f32 v[78:79], v[102:103], 0.5 op_sel_hi:[1,0]
	v_pk_mul_f32 v[76:77], v[100:101], 0.5 op_sel_hi:[1,0]
	v_pk_mul_f32 v[102:103], v[90:91], 0.5 op_sel_hi:[1,0]
	v_pk_mul_f32 v[100:101], v[88:89], 0.5 op_sel_hi:[1,0]
	v_pk_mul_f32 v[110:111], v[82:83], 0.5 op_sel_hi:[1,0]
	v_pk_mul_f32 v[108:109], v[80:81], 0.5 op_sel_hi:[1,0]
	v_pk_mul_f32 v[82:83], v[118:119], 0.5 op_sel_hi:[1,0]
	v_pk_mul_f32 v[80:81], v[116:117], 0.5 op_sel_hi:[1,0]
	v_pk_mul_f32 v[90:91], v[114:115], 0.5 op_sel_hi:[1,0]
	v_pk_mul_f32 v[88:89], v[112:113], 0.5 op_sel_hi:[1,0]
	v_pk_mul_f32 v[114:115], v[106:107], 0.5 op_sel_hi:[1,0]
	v_pk_mul_f32 v[112:113], v[104:105], 0.5 op_sel_hi:[1,0]
	v_pk_mul_f32 v[118:119], v[98:99], 0.5 op_sel_hi:[1,0]
	v_pk_mul_f32 v[116:117], v[96:97], 0.5 op_sel_hi:[1,0]
	v_pk_mul_f32 v[98:99], v[134:135], 0.5 op_sel_hi:[1,0]
	v_pk_mul_f32 v[96:97], v[132:133], 0.5 op_sel_hi:[1,0]
	v_pk_mul_f32 v[106:107], v[130:131], 0.5 op_sel_hi:[1,0]
	v_pk_mul_f32 v[104:105], v[128:129], 0.5 op_sel_hi:[1,0]
	v_pk_mul_f32 v[122:123], v[122:123], 0.5 op_sel_hi:[1,0]
	v_pk_mul_f32 v[120:121], v[120:121], 0.5 op_sel_hi:[1,0]
	v_pk_mul_f32 v[126:127], v[126:127], 0.5 op_sel_hi:[1,0]
	v_pk_mul_f32 v[124:125], v[124:125], 0.5 op_sel_hi:[1,0]
	s_branch .LBB0_744

; #define PG8_STAGE(bufoff, gbase, voff) do { _Pragma("unroll") for (int _i = 0; _i < 2; ++_i) \
;         __builtin_amdgcn_global_load_lds((const unsigned*)((const char*)(gbase) + (voff)[_i]), (LAS unsigned*)(lds + (bufoff) + ldsw + _i * 8192), 16, 0, 0); } while (0)
; #define PG8_LDA(dst, b, h) do { _Pragma("unroll") for (int m = 0; m < 4; ++m) _Pragma("unroll") for (int k = 0; k < 2; ++k) dst[m][k] = *(const LAS bf16x8*)(lds + PG8_SA(b, h) + aoff + m * 2048 + k * 1024); } while (0)
; #define PG8_LDB(dst, b, h) do { _Pragma("unroll") for (int n = 0; n < 2; ++n) _Pragma("unroll") for (int k = 0; k < 2; ++k) dst[n][k] = *(const LAS bf16x8*)(lds + PG8_SB(b, h) + boff + n * 2048 + k * 1024); } while (0)
; #define PG8_MMA(ai, bj, At, Bt) do { __builtin_amdgcn_s_setprio(1); _Pragma("unroll") for (int m = 0; m < 4; ++m) _Pragma("unroll") for (int n = 0; n < 2; ++n) _Pragma("unroll") for (int k = 0; k < 2; ++k) \
;         acc[ai][bj][m][n] = __builtin_amdgcn_mfma_f32_16x16x32_bf16(Bt[n][k], At[m][k], acc[ai][bj][m][n], 0, 0, 0); __builtin_amdgcn_s_setprio(0); } while (0)
; #define PG8_WAIT_L(n) asm volatile("s_waitcnt lgkmcnt(" #n ")" ::: "memory")
; #define PG8_BAR __builtin_amdgcn_s_barrier()
; #define PG8_SCHED __builtin_amdgcn_sched_barrier(0)
; template <class Epi, class Sched, bool ATILE = false>
; __device__ __forceinline__ void gemm_phase(LAS unsigned char* lds, const Gemm g, const Sched& S, const Epi& E) {
;     ...
;         for (int t = 0; t < nt; t += 2) {
;             const bool last = (t == nt - 2);
;             const char* a1 = cA + (size_t)(t + 1) * kstepA;
;             const char* a2 = last ? nA : cA + (size_t)(t + 2) * kstepA; const char* b2 = last ? nB : cB + (size_t)(t + 2) * kstep;
;             const char* a3 = a2 + kstepA; const char* b3 = b2 + kstep;
;             PG8_LDB(B0, 0, 0); PG8_SCHED; PG8_LDA(At, 0, 0); PG8_STAGE(PG8_SA(1, 1), a1 + hstepA, voffA);
;             PG8_WAIT_L(8); PG8_BAR; PG8_WAIT_L(0); PG8_MMA(0, 0, At, B0); PG8_BAR; PG8_SCHED;
;             PG8_LDB(B1, 0, 1); PG8_STAGE(PG8_SB(0, 0), b2, voffB);
;             PG8_BAR; PG8_WAIT_L(0); PG8_MMA(0, 1, At, B1); PG8_BAR;
;             PG8_LDA(At, 0, 1); PG8_STAGE(PG8_SA(0, 0), a2, voffA);
;             PG8_BAR; PG8_WAIT_L(0); PG8_MMA(1, 0, At, B0); PG8_BAR; PG8_SCHED;
.LBB0_895:
	ds_read_b128 v[32:35], v165
	ds_read_b128 v[36:39], v165 offset:1024
	ds_read_b128 v[178:181], v165 offset:2048
	ds_read_b128 v[182:185], v165 offset:3072
	s_add_i32 s88, s73, 2
	s_add_u32 s84, s12, 0xfff80080
	s_addc_u32 s85, s13, -1
	s_cmp_eq_u32 s53, s73
	s_cselect_b32 s87, s11, s85
	s_cselect_b32 s86, s20, s84
	s_cselect_b32 s85, s41, s63
	s_cselect_b32 s84, s52, s62
	s_add_i32 m0, s35, 0xc000
	ds_read_b128 v[192:195], v167
	ds_read_b128 v[196:199], v167 offset:1024
	ds_read_b128 v[200:203], v167 offset:2048
	ds_read_b128 v[204:207], v167 offset:3072
	ds_read_b128 v[208:211], v167 offset:4096
	ds_read_b128 v[212:215], v167 offset:5120
	ds_read_b128 v[216:219], v167 offset:6144
	ds_read_b128 v[220:223], v167 offset:7168
	global_load_lds_dwordx4 v170, s[12:13]
	s_add_i32 m0, s35, 0xe000
	s_nop 0
	global_load_lds_dwordx4 v172, s[12:13]
	s_waitcnt lgkmcnt(8)
	s_barrier
	s_waitcnt lgkmcnt(0)
	s_setprio 1
	s_waitcnt lgkmcnt(0)
	v_mfma_f32_16x16x32_bf16 v[132:135], v[32:35], v[192:195], v[132:135]
	v_mfma_f32_16x16x32_bf16 v[128:131], v[178:181], v[192:195], v[128:131]
	v_mfma_f32_16x16x32_bf16 v[116:119], v[32:35], v[200:203], v[116:119]
	v_mfma_f32_16x16x32_bf16 v[112:115], v[178:181], v[200:203], v[112:115]
	v_mfma_f32_16x16x32_bf16 v[100:103], v[32:35], v[208:211], v[100:103]
	v_mfma_f32_16x16x32_bf16 v[96:99], v[178:181], v[208:211], v[96:99]
	v_mfma_f32_16x16x32_bf16 v[84:87], v[32:35], v[216:219], v[84:87]
	v_mfma_f32_16x16x32_bf16 v[80:83], v[178:181], v[216:219], v[80:83]
	v_mfma_f32_16x16x32_bf16 v[132:135], v[36:39], v[196:199], v[132:135]
	v_mfma_f32_16x16x32_bf16 v[128:131], v[182:185], v[196:199], v[128:131]
	v_mfma_f32_16x16x32_bf16 v[116:119], v[36:39], v[204:207], v[116:119]
	v_mfma_f32_16x16x32_bf16 v[112:115], v[182:185], v[204:207], v[112:115]
	v_mfma_f32_16x16x32_bf16 v[100:103], v[36:39], v[212:215], v[100:103]
	v_mfma_f32_16x16x32_bf16 v[96:99], v[182:185], v[212:215], v[96:99]
	v_mfma_f32_16x16x32_bf16 v[84:87], v[36:39], v[220:223], v[84:87]
	v_mfma_f32_16x16x32_bf16 v[80:83], v[182:185], v[220:223], v[80:83]
	s_setprio 0
	s_barrier
	s_add_i32 s73, s43, s31
	v_lshl_add_u64 v[240:241], s[84:85], 0, v[138:139]
	s_mov_b32 m0, s73
	ds_read_b128 v[224:227], v186
	ds_read_b128 v[228:231], v186 offset:1024
	ds_read_b128 v[232:235], v186 offset:2048
	ds_read_b128 v[236:239], v186 offset:3072
	global_load_lds_dwordx4 v[240:241], off
	v_lshl_add_u64 v[242:243], s[84:85], 0, v[142:143]
	s_add_i32 m0, s73, 0x2000
	s_nop 0
	global_load_lds_dwordx4 v[242:243], off
	s_barrier
	s_waitcnt lgkmcnt(0)
	s_setprio 1
	s_waitcnt lgkmcnt(0)
	v_mfma_f32_16x16x32_bf16 v[124:127], v[224:227], v[192:195], v[124:127]
	v_mfma_f32_16x16x32_bf16 v[120:123], v[232:235], v[192:195], v[120:123]
	v_mfma_f32_16x16x32_bf16 v[108:111], v[224:227], v[200:203], v[108:111]
	v_mfma_f32_16x16x32_bf16 v[104:107], v[232:235], v[200:203], v[104:107]
	v_mfma_f32_16x16x32_bf16 v[92:95], v[224:227], v[208:211], v[92:95]
	v_mfma_f32_16x16x32_bf16 v[88:91], v[232:235], v[208:211], v[88:91]
	v_mfma_f32_16x16x32_bf16 v[76:79], v[224:227], v[216:219], v[76:79]
	v_mfma_f32_16x16x32_bf16 v[72:75], v[232:235], v[216:219], v[72:75]
	v_mfma_f32_16x16x32_bf16 v[124:127], v[228:231], v[196:199], v[124:127]
	v_mfma_f32_16x16x32_bf16 v[120:123], v[236:239], v[196:199], v[120:123]
	v_mfma_f32_16x16x32_bf16 v[108:111], v[228:231], v[204:207], v[108:111]
	v_mfma_f32_16x16x32_bf16 v[104:107], v[236:239], v[204:207], v[104:107]
	v_mfma_f32_16x16x32_bf16 v[92:95], v[228:231], v[212:215], v[92:95]
	v_mfma_f32_16x16x32_bf16 v[88:91], v[236:239], v[212:215], v[88:91]
	v_mfma_f32_16x16x32_bf16 v[76:79], v[228:231], v[220:223], v[76:79]
	v_mfma_f32_16x16x32_bf16 v[72:75], v[236:239], v[220:223], v[72:75]
	s_setprio 0
	s_barrier
	s_mov_b32 m0, s35
	v_lshl_add_u64 v[244:245], s[86:87], 0, v[136:137]
	ds_read_b128 v[192:195], v167 offset:16384
	ds_read_b128 v[196:199], v167 offset:17408
	ds_read_b128 v[200:203], v167 offset:18432
	ds_read_b128 v[204:207], v167 offset:19456
	ds_read_b128 v[208:211], v167 offset:20480
	ds_read_b128 v[212:215], v167 offset:21504
	ds_read_b128 v[216:219], v167 offset:22528
	ds_read_b128 v[220:223], v167 offset:23552
	global_load_lds_dwordx4 v[244:245], off
	v_lshl_add_u64 v[246:247], s[86:87], 0, v[140:141]
	s_mov_b32 m0, s37
	s_nop 0
	global_load_lds_dwordx4 v[246:247], off
	s_barrier
	s_waitcnt lgkmcnt(0)
	s_setprio 1
	s_waitcnt lgkmcnt(0)
	v_mfma_f32_16x16x32_bf16 v[68:71], v[32:35], v[192:195], v[68:71]
	v_mfma_f32_16x16x32_bf16 v[64:67], v[178:181], v[192:195], v[64:67]
	v_mfma_f32_16x16x32_bf16 v[52:55], v[32:35], v[200:203], v[52:55]
	v_mfma_f32_16x16x32_bf16 v[48:51], v[178:181], v[200:203], v[48:51]
	v_mfma_f32_16x16x32_bf16 v[28:31], v[32:35], v[208:211], v[28:31]
	v_mfma_f32_16x16x32_bf16 v[24:27], v[178:181], v[208:211], v[24:27]
	v_mfma_f32_16x16x32_bf16 v[12:15], v[32:35], v[216:219], v[12:15]
	v_mfma_f32_16x16x32_bf16 v[8:11], v[178:181], v[216:219], v[8:11]
	v_mfma_f32_16x16x32_bf16 v[68:71], v[36:39], v[196:199], v[68:71]
	v_mfma_f32_16x16x32_bf16 v[64:67], v[182:185], v[196:199], v[64:67]
	v_mfma_f32_16x16x32_bf16 v[52:55], v[36:39], v[204:207], v[52:55]
	v_mfma_f32_16x16x32_bf16 v[48:51], v[182:185], v[204:207], v[48:51]
	v_mfma_f32_16x16x32_bf16 v[28:31], v[36:39], v[212:215], v[28:31]
	v_mfma_f32_16x16x32_bf16 v[24:27], v[182:185], v[212:215], v[24:27]
	v_mfma_f32_16x16x32_bf16 v[12:15], v[36:39], v[220:223], v[12:15]
	v_mfma_f32_16x16x32_bf16 v[8:11], v[182:185], v[220:223], v[8:11]
	s_setprio 0
	s_barrier
; #define PG8_STAGE(bufoff, gbase, voff) do { _Pragma("unroll") for (int _i = 0; _i < 2; ++_i) \
;         __builtin_amdgcn_global_load_lds((const unsigned*)((const char*)(gbase) + (voff)[_i]), (LAS unsigned*)(lds + (bufoff) + ldsw + _i * 8192), 16, 0, 0); } while (0)
; #define PG8_LDA(dst, b, h) do { _Pragma("unroll") for (int m = 0; m < 4; ++m) _Pragma("unroll") for (int k = 0; k < 2; ++k) dst[m][k] = *(const LAS bf16x8*)(lds + PG8_SA(b, h) + aoff + m * 2048 + k * 1024); } while (0)
; #define PG8_LDB(dst, b, h) do { _Pragma("unroll") for (int n = 0; n < 2; ++n) _Pragma("unroll") for (int k = 0; k < 2; ++k) dst[n][k] = *(const LAS bf16x8*)(lds + PG8_SB(b, h) + boff + n * 2048 + k * 1024); } while (0)
; #define PG8_MMA(ai, bj, At, Bt) do { __builtin_amdgcn_s_setprio(1); _Pragma("unroll") for (int m = 0; m < 4; ++m) _Pragma("unroll") for (int n = 0; n < 2; ++n) _Pragma("unroll") for (int k = 0; k < 2; ++k) \
;         acc[ai][bj][m][n] = __builtin_amdgcn_mfma_f32_16x16x32_bf16(Bt[n][k], At[m][k], acc[ai][bj][m][n], 0, 0, 0); __builtin_amdgcn_s_setprio(0); } while (0)
; #define PG8_WAIT_V(n) asm volatile("s_waitcnt vmcnt(" #n ")" ::: "memory")
; #define PG8_WAIT_L(n) asm volatile("s_waitcnt lgkmcnt(" #n ")" ::: "memory")
; #define PG8_BAR __builtin_amdgcn_s_barrier()
; #define PG8_SCHED __builtin_amdgcn_sched_barrier(0)
; template <class Epi, class Sched, bool ATILE = false>
; __device__ __forceinline__ void gemm_phase(LAS unsigned char* lds, const Gemm g, const Sched& S, const Epi& E) {
;     ...
;             PG8_BAR; PG8_WAIT_L(0); PG8_MMA(1, 0, At, B0); PG8_BAR; PG8_SCHED;
;             PG8_STAGE(PG8_SB(0, 1), b2 + hstepB, voffB);
;             PG8_WAIT_V(6); PG8_BAR; PG8_MMA(1, 1, At, B1); PG8_BAR;
;             PG8_LDB(B0, 1, 0); PG8_SCHED; PG8_LDA(At, 1, 0); PG8_STAGE(PG8_SA(0, 1), a2 + hstepA, voffA);
;             PG8_WAIT_L(8); PG8_BAR; PG8_WAIT_L(0); PG8_MMA(0, 0, At, B0); PG8_BAR; PG8_SCHED;
;             PG8_LDB(B1, 1, 1); PG8_STAGE(PG8_SB(1, 0), b3, voffB);
;             PG8_BAR; PG8_WAIT_L(0); PG8_MMA(0, 1, At, B1); PG8_BAR;
	s_add_u32 vcc_lo, s84, 0x80000
	s_addc_u32 vcc_hi, s85, 0
	s_add_i32 s73, s56, s31
	v_lshl_add_u64 v[32:33], vcc, 0, v[138:139]
	s_mov_b32 m0, s73
	s_nop 0
	global_load_lds_dwordx4 v[32:33], off
	v_lshl_add_u64 v[32:33], vcc, 0, v[142:143]
	s_add_i32 m0, s73, 0x2000
	s_nop 0
	global_load_lds_dwordx4 v[32:33], off
	s_waitcnt vmcnt(6)
	s_barrier
	s_setprio 1
	v_mfma_f32_16x16x32_bf16 v[44:47], v[224:227], v[200:203], v[44:47]
	v_mfma_f32_16x16x32_bf16 v[40:43], v[232:235], v[200:203], v[40:43]
	v_mfma_f32_16x16x32_bf16 v[20:23], v[224:227], v[208:211], v[20:23]
	v_mfma_f32_16x16x32_bf16 v[16:19], v[232:235], v[208:211], v[16:19]
	v_mfma_f32_16x16x32_bf16 v[4:7], v[224:227], v[216:219], v[4:7]
	v_mfma_f32_16x16x32_bf16 v[0:3], v[232:235], v[216:219], v[0:3]
	v_mfma_f32_16x16x32_bf16 v[32:35], v[224:227], v[192:195], v[60:63]
	v_mfma_f32_16x16x32_bf16 v[36:39], v[232:235], v[192:195], v[56:59]
	v_mfma_f32_16x16x32_bf16 v[44:47], v[228:231], v[204:207], v[44:47]
	v_mfma_f32_16x16x32_bf16 v[40:43], v[236:239], v[204:207], v[40:43]
	v_mfma_f32_16x16x32_bf16 v[20:23], v[228:231], v[212:215], v[20:23]
	v_mfma_f32_16x16x32_bf16 v[16:19], v[236:239], v[212:215], v[16:19]
	v_mfma_f32_16x16x32_bf16 v[4:7], v[228:231], v[220:223], v[4:7]
	v_mfma_f32_16x16x32_bf16 v[0:3], v[236:239], v[220:223], v[0:3]
	v_mfma_f32_16x16x32_bf16 v[32:35], v[228:231], v[196:199], v[32:35]
	v_mfma_f32_16x16x32_bf16 v[36:39], v[236:239], v[196:199], v[36:39]
	s_setprio 0
	s_barrier
	s_add_i32 s73, 0, 0x18000
	v_add_u32_e32 v144, s73, v161
	ds_read_b128 v[56:59], v144
	ds_read_b128 v[60:63], v144 offset:1024
	ds_read_b128 v[178:181], v144 offset:2048
	ds_read_b128 v[182:185], v144 offset:3072
	s_add_u32 s86, s86, 0x80000
	s_addc_u32 s87, s87, 0
	s_mov_b32 m0, s39
	ds_read_b128 v[192:195], v167 offset:32768
	ds_read_b128 v[196:199], v167 offset:33792
	ds_read_b128 v[200:203], v167 offset:34816
	ds_read_b128 v[204:207], v167 offset:35840
	ds_read_b128 v[208:211], v167 offset:36864
	ds_read_b128 v[212:215], v167 offset:37888
	ds_read_b128 v[216:219], v167 offset:38912
	ds_read_b128 v[220:223], v167 offset:39936
	global_load_lds_dwordx4 v136, s[86:87]
	s_mov_b32 m0, s97
	s_nop 0
	global_load_lds_dwordx4 v140, s[86:87]
	s_waitcnt lgkmcnt(8)
	s_barrier
	s_waitcnt lgkmcnt(0)
	s_setprio 1
	s_waitcnt lgkmcnt(0)
	v_mfma_f32_16x16x32_bf16 v[132:135], v[56:59], v[192:195], v[132:135]
	v_mfma_f32_16x16x32_bf16 v[128:131], v[178:181], v[192:195], v[128:131]
	v_mfma_f32_16x16x32_bf16 v[116:119], v[56:59], v[200:203], v[116:119]
	v_mfma_f32_16x16x32_bf16 v[112:115], v[178:181], v[200:203], v[112:115]
	v_mfma_f32_16x16x32_bf16 v[100:103], v[56:59], v[208:211], v[100:103]
	v_mfma_f32_16x16x32_bf16 v[96:99], v[178:181], v[208:211], v[96:99]
	v_mfma_f32_16x16x32_bf16 v[84:87], v[56:59], v[216:219], v[84:87]
	v_mfma_f32_16x16x32_bf16 v[80:83], v[178:181], v[216:219], v[80:83]
	v_mfma_f32_16x16x32_bf16 v[132:135], v[60:63], v[196:199], v[132:135]
	v_mfma_f32_16x16x32_bf16 v[128:131], v[182:185], v[196:199], v[128:131]
	v_mfma_f32_16x16x32_bf16 v[116:119], v[60:63], v[204:207], v[116:119]
	v_mfma_f32_16x16x32_bf16 v[112:115], v[182:185], v[204:207], v[112:115]
	v_mfma_f32_16x16x32_bf16 v[100:103], v[60:63], v[212:215], v[100:103]
	v_mfma_f32_16x16x32_bf16 v[96:99], v[182:185], v[212:215], v[96:99]
	v_mfma_f32_16x16x32_bf16 v[84:87], v[60:63], v[220:223], v[84:87]
	v_mfma_f32_16x16x32_bf16 v[80:83], v[182:185], v[220:223], v[80:83]
	s_setprio 0
	s_barrier
	s_add_i32 s86, 0, 0x1c000
	s_add_i32 s73, s73, s31
	v_add_u32_e32 v144, s86, v161
	v_lshl_add_u64 v[240:241], v[240:241], 0, s[22:23]
	s_mov_b32 m0, s73
	ds_read_b128 v[224:227], v144
	ds_read_b128 v[228:231], v144 offset:1024
	ds_read_b128 v[232:235], v144 offset:2048
	ds_read_b128 v[236:239], v144 offset:3072
	global_load_lds_dwordx4 v[240:241], off
	v_lshl_add_u64 v[240:241], v[242:243], 0, s[22:23]
	s_add_i32 m0, s73, 0x2000
	s_nop 0
	global_load_lds_dwordx4 v[240:241], off
	s_barrier
; #define PG8_STAGE(bufoff, gbase, voff) do { _Pragma("unroll") for (int _i = 0; _i < 2; ++_i) \
;         __builtin_amdgcn_global_load_lds((const unsigned*)((const char*)(gbase) + (voff)[_i]), (LAS unsigned*)(lds + (bufoff) + ldsw + _i * 8192), 16, 0, 0); } while (0)
; #define PG8_LDA(dst, b, h) do { _Pragma("unroll") for (int m = 0; m < 4; ++m) _Pragma("unroll") for (int k = 0; k < 2; ++k) dst[m][k] = *(const LAS bf16x8*)(lds + PG8_SA(b, h) + aoff + m * 2048 + k * 1024); } while (0)
; #define PG8_MMA(ai, bj, At, Bt) do { __builtin_amdgcn_s_setprio(1); _Pragma("unroll") for (int m = 0; m < 4; ++m) _Pragma("unroll") for (int n = 0; n < 2; ++n) _Pragma("unroll") for (int k = 0; k < 2; ++k) \
;         acc[ai][bj][m][n] = __builtin_amdgcn_mfma_f32_16x16x32_bf16(Bt[n][k], At[m][k], acc[ai][bj][m][n], 0, 0, 0); __builtin_amdgcn_s_setprio(0); } while (0)
; #define PG8_WAIT_V(n) asm volatile("s_waitcnt vmcnt(" #n ")" ::: "memory")
; #define PG8_WAIT_L(n) asm volatile("s_waitcnt lgkmcnt(" #n ")" ::: "memory")
; #define PG8_BAR __builtin_amdgcn_s_barrier()
; #define PG8_SCHED __builtin_amdgcn_sched_barrier(0)
; template <class Epi, class Sched, bool ATILE = false>
; __device__ __forceinline__ void gemm_phase(LAS unsigned char* lds, const Gemm g, const Sched& S, const Epi& E) {
;     ...
;             PG8_BAR; PG8_WAIT_L(0); PG8_MMA(0, 1, At, B1); PG8_BAR;
;             PG8_LDA(At, 1, 1); PG8_STAGE(PG8_SA(1, 0), a3, voffA);
;             PG8_BAR; PG8_WAIT_L(0); PG8_MMA(1, 0, At, B0); PG8_BAR; PG8_SCHED;
;             PG8_STAGE(PG8_SB(1, 1), b3 + hstepB, voffB);
;             PG8_WAIT_V(6); PG8_BAR; PG8_MMA(1, 1, At, B1); PG8_BAR;
;         }
	s_waitcnt lgkmcnt(0)
	s_setprio 1
	s_waitcnt lgkmcnt(0)
	v_mfma_f32_16x16x32_bf16 v[124:127], v[224:227], v[192:195], v[124:127]
	v_mfma_f32_16x16x32_bf16 v[120:123], v[232:235], v[192:195], v[120:123]
	v_mfma_f32_16x16x32_bf16 v[108:111], v[224:227], v[200:203], v[108:111]
	v_mfma_f32_16x16x32_bf16 v[104:107], v[232:235], v[200:203], v[104:107]
	v_mfma_f32_16x16x32_bf16 v[92:95], v[224:227], v[208:211], v[92:95]
	v_mfma_f32_16x16x32_bf16 v[88:91], v[232:235], v[208:211], v[88:91]
	v_mfma_f32_16x16x32_bf16 v[76:79], v[224:227], v[216:219], v[76:79]
	v_mfma_f32_16x16x32_bf16 v[72:75], v[232:235], v[216:219], v[72:75]
	v_mfma_f32_16x16x32_bf16 v[124:127], v[228:231], v[196:199], v[124:127]
	v_mfma_f32_16x16x32_bf16 v[120:123], v[236:239], v[196:199], v[120:123]
	v_mfma_f32_16x16x32_bf16 v[108:111], v[228:231], v[204:207], v[108:111]
	v_mfma_f32_16x16x32_bf16 v[104:107], v[236:239], v[204:207], v[104:107]
	v_mfma_f32_16x16x32_bf16 v[92:95], v[228:231], v[212:215], v[92:95]
	v_mfma_f32_16x16x32_bf16 v[88:91], v[236:239], v[212:215], v[88:91]
	v_mfma_f32_16x16x32_bf16 v[76:79], v[228:231], v[220:223], v[76:79]
	v_mfma_f32_16x16x32_bf16 v[72:75], v[236:239], v[220:223], v[72:75]
	s_setprio 0
	s_barrier
	s_mov_b32 m0, s4
	v_lshl_add_u64 v[240:241], v[244:245], 0, s[22:23]
	ds_read_b128 v[192:195], v167 offset:49152
	ds_read_b128 v[196:199], v167 offset:50176
	ds_read_b128 v[200:203], v167 offset:51200
	ds_read_b128 v[204:207], v167 offset:52224
	ds_read_b128 v[208:211], v167 offset:53248
	ds_read_b128 v[212:215], v167 offset:54272
	ds_read_b128 v[216:219], v167 offset:55296
	ds_read_b128 v[220:223], v167 offset:56320
	global_load_lds_dwordx4 v[240:241], off
	v_lshl_add_u64 v[240:241], v[246:247], 0, s[22:23]
	s_mov_b32 m0, s5
	s_nop 0
	global_load_lds_dwordx4 v[240:241], off
	s_barrier
	s_waitcnt lgkmcnt(0)
	s_setprio 1
	s_waitcnt lgkmcnt(0)
	v_mfma_f32_16x16x32_bf16 v[68:71], v[56:59], v[192:195], v[68:71]
	v_mfma_f32_16x16x32_bf16 v[64:67], v[178:181], v[192:195], v[64:67]
	v_mfma_f32_16x16x32_bf16 v[52:55], v[56:59], v[200:203], v[52:55]
	v_mfma_f32_16x16x32_bf16 v[48:51], v[178:181], v[200:203], v[48:51]
	v_mfma_f32_16x16x32_bf16 v[28:31], v[56:59], v[208:211], v[28:31]
	v_mfma_f32_16x16x32_bf16 v[24:27], v[178:181], v[208:211], v[24:27]
	v_mfma_f32_16x16x32_bf16 v[12:15], v[56:59], v[216:219], v[12:15]
	v_mfma_f32_16x16x32_bf16 v[8:11], v[178:181], v[216:219], v[8:11]
	v_mfma_f32_16x16x32_bf16 v[68:71], v[60:63], v[196:199], v[68:71]
	v_mfma_f32_16x16x32_bf16 v[64:67], v[182:185], v[196:199], v[64:67]
	v_mfma_f32_16x16x32_bf16 v[52:55], v[60:63], v[204:207], v[52:55]
	v_mfma_f32_16x16x32_bf16 v[48:51], v[182:185], v[204:207], v[48:51]
	v_mfma_f32_16x16x32_bf16 v[28:31], v[60:63], v[212:215], v[28:31]
	v_mfma_f32_16x16x32_bf16 v[24:27], v[182:185], v[212:215], v[24:27]
	v_mfma_f32_16x16x32_bf16 v[12:15], v[60:63], v[220:223], v[12:15]
	v_mfma_f32_16x16x32_bf16 v[8:11], v[182:185], v[220:223], v[8:11]
	s_setprio 0
	s_barrier
	s_add_u32 s84, s84, 0x80080
	s_addc_u32 s85, s85, 0
	s_add_i32 s73, s86, s31
	s_mov_b32 m0, s73
	s_nop 0
	global_load_lds_dwordx4 v138, s[84:85]
	v_lshl_add_u64 v[56:57], s[84:85], 0, v[142:143]
	s_add_i32 m0, s73, 0x2000
	s_nop 0
	global_load_lds_dwordx4 v[56:57], off
	s_waitcnt vmcnt(6)
	s_barrier
	s_setprio 1
	v_mfma_f32_16x16x32_bf16 v[32:35], v[224:227], v[192:195], v[32:35]
	v_mfma_f32_16x16x32_bf16 v[60:63], v[228:231], v[196:199], v[32:35]
	v_mfma_f32_16x16x32_bf16 v[32:35], v[232:235], v[192:195], v[36:39]
	v_mfma_f32_16x16x32_bf16 v[56:59], v[236:239], v[196:199], v[32:35]
	v_mfma_f32_16x16x32_bf16 v[32:35], v[224:227], v[200:203], v[44:47]
	v_mfma_f32_16x16x32_bf16 v[44:47], v[228:231], v[204:207], v[32:35]
	v_mfma_f32_16x16x32_bf16 v[32:35], v[232:235], v[200:203], v[40:43]
	v_mfma_f32_16x16x32_bf16 v[20:23], v[224:227], v[208:211], v[20:23]
	v_mfma_f32_16x16x32_bf16 v[16:19], v[232:235], v[208:211], v[16:19]
	v_mfma_f32_16x16x32_bf16 v[4:7], v[224:227], v[216:219], v[4:7]
	v_mfma_f32_16x16x32_bf16 v[0:3], v[232:235], v[216:219], v[0:3]
	v_mfma_f32_16x16x32_bf16 v[40:43], v[236:239], v[204:207], v[32:35]
	v_mfma_f32_16x16x32_bf16 v[20:23], v[228:231], v[212:215], v[20:23]
	v_mfma_f32_16x16x32_bf16 v[16:19], v[236:239], v[212:215], v[16:19]
	v_mfma_f32_16x16x32_bf16 v[4:7], v[228:231], v[220:223], v[4:7]
	v_mfma_f32_16x16x32_bf16 v[0:3], v[236:239], v[220:223], v[0:3]
	s_setprio 0
	s_barrier
	s_add_u32 s12, s12, 0x100
	s_addc_u32 s13, s13, 0
	s_add_u32 s62, s62, 0x100
	s_addc_u32 s63, s63, 0
	s_cmp_ge_i32 s88, s1
	s_mov_b32 s73, s88
	s_cbranch_scc0 .LBB0_895
	s_branch .LBB0_897

; #define PG8_STAGE(bufoff, gbase, voff) do { _Pragma("unroll") for (int _i = 0; _i < 2; ++_i) \
;         __builtin_amdgcn_global_load_lds((const unsigned*)((const char*)(gbase) + (voff)[_i]), (LAS unsigned*)(lds + (bufoff) + ldsw + _i * 8192), 16, 0, 0); } while (0)
; #define PG8_LDA(dst, b, h) do { _Pragma("unroll") for (int m = 0; m < 4; ++m) _Pragma("unroll") for (int k = 0; k < 2; ++k) dst[m][k] = *(const LAS bf16x8*)(lds + PG8_SA(b, h) + aoff + m * 2048 + k * 1024); } while (0)
; #define PG8_LDB(dst, b, h) do { _Pragma("unroll") for (int n = 0; n < 2; ++n) _Pragma("unroll") for (int k = 0; k < 2; ++k) dst[n][k] = *(const LAS bf16x8*)(lds + PG8_SB(b, h) + boff + n * 2048 + k * 1024); } while (0)
; #define PG8_MMA(ai, bj, At, Bt) do { __builtin_amdgcn_s_setprio(1); _Pragma("unroll") for (int m = 0; m < 4; ++m) _Pragma("unroll") for (int n = 0; n < 2; ++n) _Pragma("unroll") for (int k = 0; k < 2; ++k) \
;         acc[ai][bj][m][n] = __builtin_amdgcn_mfma_f32_16x16x32_bf16(Bt[n][k], At[m][k], acc[ai][bj][m][n], 0, 0, 0); __builtin_amdgcn_s_setprio(0); } while (0)
; #define PG8_WAIT_V(n) asm volatile("s_waitcnt vmcnt(" #n ")" ::: "memory")
; #define PG8_WAIT_L(n) asm volatile("s_waitcnt lgkmcnt(" #n ")" ::: "memory")
; template <class Epi, class Sched, bool ATILE = false>
; __device__ __forceinline__ void gemm_phase(LAS unsigned char* lds, const Gemm g, const Sched& S, const Epi& E) {
;     ...
;         for (int t = 0; t < nt; t += 2) {
;             const bool last = (t == nt - 2);
;             const char* a1 = cA + (size_t)(t + 1) * kstepA;
;             const char* a2 = last ? nA : cA + (size_t)(t + 2) * kstepA; const char* b2 = last ? nB : cB + (size_t)(t + 2) * kstep;
;             const char* a3 = a2 + kstepA; const char* b3 = b2 + kstep;
;             PG8_LDB(B0, 0, 0); PG8_SCHED; PG8_LDA(At, 0, 0); PG8_STAGE(PG8_SA(1, 1), a1 + hstepA, voffA);
;             PG8_WAIT_L(8); PG8_BAR; PG8_WAIT_L(0); PG8_MMA(0, 0, At, B0); PG8_BAR; PG8_SCHED;
;             PG8_LDB(B1, 0, 1); PG8_STAGE(PG8_SB(0, 0), b2, voffB);
;             PG8_BAR; PG8_WAIT_L(0); PG8_MMA(0, 1, At, B1); PG8_BAR;
;             PG8_LDA(At, 0, 1); PG8_STAGE(PG8_SA(0, 0), a2, voffA);
;             PG8_BAR; PG8_WAIT_L(0); PG8_MMA(1, 0, At, B0); PG8_BAR; PG8_SCHED;
;             PG8_STAGE(PG8_SB(0, 1), b2 + hstepB, voffB);
;             PG8_WAIT_V(6); PG8_BAR; PG8_MMA(1, 1, At, B1); PG8_BAR;
.LBB0_1298:
	ds_read_b128 v[82:85], v79
	ds_read_b128 v[86:89], v79 offset:1024
	ds_read_b128 v[90:93], v79 offset:2048
	ds_read_b128 v[94:97], v79 offset:3072
	s_add_i32 s60, s20, 2
	s_add_u32 s18, s16, 0x100
	s_addc_u32 s19, s17, 0
	s_cmp_eq_u32 s57, s20
	s_cselect_b32 s20, s56, s58
	s_cselect_b32 s23, s9, s19
	s_cselect_b32 s22, s8, s18
	s_cselect_b32 s21, s55, s59
	s_mov_b32 m0, s38
	v_lshl_add_u64 v[130:131], s[16:17], 0, v[74:75]
	ds_read_b128 v[98:101], v80
	ds_read_b128 v[102:105], v80 offset:1024
	ds_read_b128 v[106:109], v80 offset:2048
	ds_read_b128 v[110:113], v80 offset:3072
	ds_read_b128 v[114:117], v80 offset:4096
	ds_read_b128 v[118:121], v80 offset:5120
	ds_read_b128 v[122:125], v80 offset:6144
	ds_read_b128 v[126:129], v80 offset:7168
	global_load_lds_dwordx4 v[130:131], off
	v_lshl_add_u64 v[130:131], s[16:17], 0, v[76:77]
	s_mov_b32 m0, s39
	s_nop 0
	global_load_lds_dwordx4 v[130:131], off
	s_waitcnt lgkmcnt(8)
	s_barrier
	s_waitcnt lgkmcnt(0)
	s_setprio 1
	s_waitcnt lgkmcnt(0)
	v_mfma_f32_16x16x32_bf16 v[60:63], v[82:85], v[98:101], v[60:63]
	v_mfma_f32_16x16x32_bf16 v[56:59], v[90:93], v[98:101], v[56:59]
	v_mfma_f32_16x16x32_bf16 v[52:55], v[82:85], v[106:109], v[52:55]
	v_mfma_f32_16x16x32_bf16 v[48:51], v[90:93], v[106:109], v[48:51]
	v_mfma_f32_16x16x32_bf16 v[44:47], v[82:85], v[114:117], v[44:47]
	v_mfma_f32_16x16x32_bf16 v[40:43], v[90:93], v[114:117], v[40:43]
	v_mfma_f32_16x16x32_bf16 v[36:39], v[82:85], v[122:125], v[36:39]
	v_mfma_f32_16x16x32_bf16 v[32:35], v[90:93], v[122:125], v[32:35]
	v_mfma_f32_16x16x32_bf16 v[60:63], v[86:89], v[102:105], v[60:63]
	v_mfma_f32_16x16x32_bf16 v[56:59], v[94:97], v[102:105], v[56:59]
	v_mfma_f32_16x16x32_bf16 v[52:55], v[86:89], v[110:113], v[52:55]
	v_mfma_f32_16x16x32_bf16 v[48:51], v[94:97], v[110:113], v[48:51]
	v_mfma_f32_16x16x32_bf16 v[44:47], v[86:89], v[118:121], v[44:47]
	v_mfma_f32_16x16x32_bf16 v[40:43], v[94:97], v[118:121], v[40:43]
	v_mfma_f32_16x16x32_bf16 v[36:39], v[86:89], v[126:129], v[36:39]
	v_mfma_f32_16x16x32_bf16 v[32:35], v[94:97], v[126:129], v[32:35]
	s_setprio 0
	s_barrier
	s_mov_b32 m0, s40
	v_lshl_add_u64 v[130:131], s[20:21], 0, v[68:69]
	global_load_lds_dwordx4 v[130:131], off
	v_lshl_add_u64 v[132:133], s[20:21], 0, v[64:65]
	s_mov_b32 m0, s41
	s_nop 0
	global_load_lds_dwordx4 v[132:133], off
	s_barrier
	s_waitcnt lgkmcnt(0)
	s_setprio 1
	s_setprio 0
	s_mov_b32 m0, s25
	v_lshl_add_u64 v[134:135], s[22:23], 0, v[70:71]
	s_barrier
	ds_read_b128 v[98:101], v80 offset:16384
	ds_read_b128 v[102:105], v80 offset:17408
	ds_read_b128 v[106:109], v80 offset:18432
	ds_read_b128 v[110:113], v80 offset:19456
	ds_read_b128 v[114:117], v80 offset:20480
	ds_read_b128 v[118:121], v80 offset:21504
	ds_read_b128 v[122:125], v80 offset:22528
	ds_read_b128 v[126:129], v80 offset:23552
	global_load_lds_dwordx4 v[134:135], off
	v_lshl_add_u64 v[136:137], s[22:23], 0, v[66:67]
	s_mov_b32 m0, s26
	s_nop 0
	global_load_lds_dwordx4 v[136:137], off
	s_barrier
	s_waitcnt lgkmcnt(0)
	s_setprio 1
	s_waitcnt lgkmcnt(0)
	v_mfma_f32_16x16x32_bf16 v[28:31], v[82:85], v[98:101], v[28:31]
	v_mfma_f32_16x16x32_bf16 v[24:27], v[90:93], v[98:101], v[24:27]
	v_mfma_f32_16x16x32_bf16 v[20:23], v[82:85], v[106:109], v[20:23]
	v_mfma_f32_16x16x32_bf16 v[16:19], v[90:93], v[106:109], v[16:19]
	v_mfma_f32_16x16x32_bf16 v[12:15], v[82:85], v[114:117], v[12:15]
	v_mfma_f32_16x16x32_bf16 v[8:11], v[90:93], v[114:117], v[8:11]
	v_mfma_f32_16x16x32_bf16 v[4:7], v[82:85], v[122:125], v[4:7]
	v_mfma_f32_16x16x32_bf16 v[0:3], v[90:93], v[122:125], v[0:3]
	v_mfma_f32_16x16x32_bf16 v[28:31], v[86:89], v[102:105], v[28:31]
	v_mfma_f32_16x16x32_bf16 v[24:27], v[94:97], v[102:105], v[24:27]
	v_mfma_f32_16x16x32_bf16 v[20:23], v[86:89], v[110:113], v[20:23]
	v_mfma_f32_16x16x32_bf16 v[16:19], v[94:97], v[110:113], v[16:19]
	v_mfma_f32_16x16x32_bf16 v[12:15], v[86:89], v[118:121], v[12:15]
	v_mfma_f32_16x16x32_bf16 v[8:11], v[94:97], v[118:121], v[8:11]
	v_mfma_f32_16x16x32_bf16 v[4:7], v[86:89], v[126:129], v[4:7]
	v_mfma_f32_16x16x32_bf16 v[0:3], v[94:97], v[126:129], v[0:3]
	s_setprio 0
	s_barrier
	s_add_u32 s16, s20, 0x10000
	s_addc_u32 s17, s21, 0
	s_mov_b32 m0, s27
	s_nop 0
	global_load_lds_dwordx4 v68, s[16:17]
	s_mov_b32 m0, s28
	s_nop 0
	global_load_lds_dwordx4 v64, s[16:17]
	s_waitcnt vmcnt(6)
	s_barrier
; #define PG8_STAGE(bufoff, gbase, voff) do { _Pragma("unroll") for (int _i = 0; _i < 2; ++_i) \
;         __builtin_amdgcn_global_load_lds((const unsigned*)((const char*)(gbase) + (voff)[_i]), (LAS unsigned*)(lds + (bufoff) + ldsw + _i * 8192), 16, 0, 0); } while (0)
; #define PG8_LDA(dst, b, h) do { _Pragma("unroll") for (int m = 0; m < 4; ++m) _Pragma("unroll") for (int k = 0; k < 2; ++k) dst[m][k] = *(const LAS bf16x8*)(lds + PG8_SA(b, h) + aoff + m * 2048 + k * 1024); } while (0)
; #define PG8_LDB(dst, b, h) do { _Pragma("unroll") for (int n = 0; n < 2; ++n) _Pragma("unroll") for (int k = 0; k < 2; ++k) dst[n][k] = *(const LAS bf16x8*)(lds + PG8_SB(b, h) + boff + n * 2048 + k * 1024); } while (0)
; #define PG8_MMA(ai, bj, At, Bt) do { __builtin_amdgcn_s_setprio(1); _Pragma("unroll") for (int m = 0; m < 4; ++m) _Pragma("unroll") for (int n = 0; n < 2; ++n) _Pragma("unroll") for (int k = 0; k < 2; ++k) \
;         acc[ai][bj][m][n] = __builtin_amdgcn_mfma_f32_16x16x32_bf16(Bt[n][k], At[m][k], acc[ai][bj][m][n], 0, 0, 0); __builtin_amdgcn_s_setprio(0); } while (0)
; #define PG8_WAIT_V(n) asm volatile("s_waitcnt vmcnt(" #n ")" ::: "memory")
; #define PG8_WAIT_L(n) asm volatile("s_waitcnt lgkmcnt(" #n ")" ::: "memory")
; #define PG8_BAR __builtin_amdgcn_s_barrier()
; #define PG8_SCHED __builtin_amdgcn_sched_barrier(0)
; template <class Epi, class Sched, bool ATILE = false>
; __device__ __forceinline__ void gemm_phase(LAS unsigned char* lds, const Gemm g, const Sched& S, const Epi& E) {
;     ...
;             PG8_WAIT_V(6); PG8_BAR; PG8_MMA(1, 1, At, B1); PG8_BAR;
;             PG8_LDB(B0, 1, 0); PG8_SCHED; PG8_LDA(At, 1, 0); PG8_STAGE(PG8_SA(0, 1), a2 + hstepA, voffA);
;             PG8_WAIT_L(8); PG8_BAR; PG8_WAIT_L(0); PG8_MMA(0, 0, At, B0); PG8_BAR; PG8_SCHED;
;             PG8_LDB(B1, 1, 1); PG8_STAGE(PG8_SB(1, 0), b3, voffB);
;             PG8_BAR; PG8_WAIT_L(0); PG8_MMA(0, 1, At, B1); PG8_BAR;
;             PG8_LDA(At, 1, 1); PG8_STAGE(PG8_SA(1, 0), a3, voffA);
;             PG8_BAR; PG8_WAIT_L(0); PG8_MMA(1, 0, At, B0); PG8_BAR; PG8_SCHED;
;             PG8_STAGE(PG8_SB(1, 1), b3 + hstepB, voffB);
;             PG8_WAIT_V(6); PG8_BAR; PG8_MMA(1, 1, At, B1); PG8_BAR;
;         }
	s_setprio 1
	s_setprio 0
	s_barrier
	ds_read_b128 v[82:85], v81
	ds_read_b128 v[86:89], v81 offset:1024
	ds_read_b128 v[90:93], v81 offset:2048
	ds_read_b128 v[94:97], v81 offset:3072
	s_add_u32 s16, s22, 0x18000
	s_addc_u32 s17, s23, 0
	s_mov_b32 m0, s29
	ds_read_b128 v[98:101], v80 offset:32768
	ds_read_b128 v[102:105], v80 offset:33792
	ds_read_b128 v[106:109], v80 offset:34816
	ds_read_b128 v[110:113], v80 offset:35840
	ds_read_b128 v[114:117], v80 offset:36864
	ds_read_b128 v[118:121], v80 offset:37888
	ds_read_b128 v[122:125], v80 offset:38912
	ds_read_b128 v[126:129], v80 offset:39936
	global_load_lds_dwordx4 v70, s[16:17]
	s_mov_b32 m0, s30
	s_nop 0
	global_load_lds_dwordx4 v66, s[16:17]
	s_waitcnt lgkmcnt(8)
	s_barrier
	s_waitcnt lgkmcnt(0)
	s_setprio 1
	s_waitcnt lgkmcnt(0)
	v_mfma_f32_16x16x32_bf16 v[60:63], v[82:85], v[98:101], v[60:63]
	v_mfma_f32_16x16x32_bf16 v[56:59], v[90:93], v[98:101], v[56:59]
	v_mfma_f32_16x16x32_bf16 v[52:55], v[82:85], v[106:109], v[52:55]
	v_mfma_f32_16x16x32_bf16 v[48:51], v[90:93], v[106:109], v[48:51]
	v_mfma_f32_16x16x32_bf16 v[44:47], v[82:85], v[114:117], v[44:47]
	v_mfma_f32_16x16x32_bf16 v[40:43], v[90:93], v[114:117], v[40:43]
	v_mfma_f32_16x16x32_bf16 v[36:39], v[82:85], v[122:125], v[36:39]
	v_mfma_f32_16x16x32_bf16 v[32:35], v[90:93], v[122:125], v[32:35]
	v_mfma_f32_16x16x32_bf16 v[60:63], v[86:89], v[102:105], v[60:63]
	v_mfma_f32_16x16x32_bf16 v[56:59], v[94:97], v[102:105], v[56:59]
	v_mfma_f32_16x16x32_bf16 v[52:55], v[86:89], v[110:113], v[52:55]
	v_mfma_f32_16x16x32_bf16 v[48:51], v[94:97], v[110:113], v[48:51]
	v_mfma_f32_16x16x32_bf16 v[44:47], v[86:89], v[118:121], v[44:47]
	v_mfma_f32_16x16x32_bf16 v[40:43], v[94:97], v[118:121], v[40:43]
	v_mfma_f32_16x16x32_bf16 v[36:39], v[86:89], v[126:129], v[36:39]
	v_mfma_f32_16x16x32_bf16 v[32:35], v[94:97], v[126:129], v[32:35]
	s_setprio 0
	s_barrier
	s_mov_b32 m0, s43
	v_lshl_add_u64 v[98:99], v[130:131], 0, s[6:7]
	global_load_lds_dwordx4 v[98:99], off
	v_lshl_add_u64 v[98:99], v[132:133], 0, s[6:7]
	s_mov_b32 m0, s44
	s_nop 0
	global_load_lds_dwordx4 v[98:99], off
	s_barrier
	s_waitcnt lgkmcnt(0)
	s_setprio 1
	s_setprio 0
	s_mov_b32 m0, s34
	v_lshl_add_u64 v[130:131], v[134:135], 0, s[6:7]
	s_barrier
	ds_read_b128 v[98:101], v80 offset:49152
	ds_read_b128 v[102:105], v80 offset:50176
	ds_read_b128 v[106:109], v80 offset:51200
	ds_read_b128 v[110:113], v80 offset:52224
	ds_read_b128 v[114:117], v80 offset:53248
	ds_read_b128 v[118:121], v80 offset:54272
	ds_read_b128 v[122:125], v80 offset:55296
	ds_read_b128 v[126:129], v80 offset:56320
	global_load_lds_dwordx4 v[130:131], off
	v_lshl_add_u64 v[130:131], v[136:137], 0, s[6:7]
	s_mov_b32 m0, s35
	s_nop 0
	global_load_lds_dwordx4 v[130:131], off
	s_barrier
	s_waitcnt lgkmcnt(0)
	s_setprio 1
	s_waitcnt lgkmcnt(0)
	v_mfma_f32_16x16x32_bf16 v[28:31], v[82:85], v[98:101], v[28:31]
	v_mfma_f32_16x16x32_bf16 v[24:27], v[90:93], v[98:101], v[24:27]
	v_mfma_f32_16x16x32_bf16 v[20:23], v[82:85], v[106:109], v[20:23]
	v_mfma_f32_16x16x32_bf16 v[16:19], v[90:93], v[106:109], v[16:19]
	v_mfma_f32_16x16x32_bf16 v[12:15], v[82:85], v[114:117], v[12:15]
	v_mfma_f32_16x16x32_bf16 v[8:11], v[90:93], v[114:117], v[8:11]
	v_mfma_f32_16x16x32_bf16 v[4:7], v[82:85], v[122:125], v[4:7]
	v_mfma_f32_16x16x32_bf16 v[0:3], v[90:93], v[122:125], v[0:3]
	v_mfma_f32_16x16x32_bf16 v[28:31], v[86:89], v[102:105], v[28:31]
	v_mfma_f32_16x16x32_bf16 v[24:27], v[94:97], v[102:105], v[24:27]
	v_mfma_f32_16x16x32_bf16 v[20:23], v[86:89], v[110:113], v[20:23]
	v_mfma_f32_16x16x32_bf16 v[16:19], v[94:97], v[110:113], v[16:19]
	v_mfma_f32_16x16x32_bf16 v[12:15], v[86:89], v[118:121], v[12:15]
	v_mfma_f32_16x16x32_bf16 v[8:11], v[94:97], v[118:121], v[8:11]
	v_mfma_f32_16x16x32_bf16 v[4:7], v[86:89], v[126:129], v[4:7]
	v_mfma_f32_16x16x32_bf16 v[0:3], v[94:97], v[126:129], v[0:3]
	s_setprio 0
	s_barrier
	s_add_u32 s16, s20, 0x10080
	s_addc_u32 s17, s21, 0
	s_mov_b32 m0, s36
	s_nop 0
	global_load_lds_dwordx4 v68, s[16:17]
	s_mov_b32 m0, s37
	s_nop 0
	global_load_lds_dwordx4 v64, s[16:17]
	s_waitcnt vmcnt(6)
	s_barrier
	s_setprio 1
	s_setprio 0
	s_add_u32 s58, s58, 0x100
	s_addc_u32 s59, s59, 0
	s_cmp_ge_i32 s60, s54
	s_mov_b64 s[16:17], s[18:19]
	s_mov_b32 s20, s60
	s_barrier
	s_cbranch_scc0 .LBB0_1298
	s_branch .LBB0_1293

; #define PG8_STAGE(bufoff, gbase, voff) do { _Pragma("unroll") for (int _i = 0; _i < 2; ++_i) \
;         __builtin_amdgcn_global_load_lds((const unsigned*)((const char*)(gbase) + (voff)[_i]), (LAS unsigned*)(lds + (bufoff) + ldsw + _i * 8192), 16, 0, 0); } while (0)
; #define PG8_LDA(dst, b, h) do { _Pragma("unroll") for (int m = 0; m < 4; ++m) _Pragma("unroll") for (int k = 0; k < 2; ++k) dst[m][k] = *(const LAS bf16x8*)(lds + PG8_SA(b, h) + aoff + m * 2048 + k * 1024); } while (0)
; #define PG8_LDB(dst, b, h) do { _Pragma("unroll") for (int n = 0; n < 2; ++n) _Pragma("unroll") for (int k = 0; k < 2; ++k) dst[n][k] = *(const LAS bf16x8*)(lds + PG8_SB(b, h) + boff + n * 2048 + k * 1024); } while (0)
; #define PG8_MMA(ai, bj, At, Bt) do { __builtin_amdgcn_s_setprio(1); _Pragma("unroll") for (int m = 0; m < 4; ++m) _Pragma("unroll") for (int n = 0; n < 2; ++n) _Pragma("unroll") for (int k = 0; k < 2; ++k) \
;         acc[ai][bj][m][n] = __builtin_amdgcn_mfma_f32_16x16x32_bf16(Bt[n][k], At[m][k], acc[ai][bj][m][n], 0, 0, 0); __builtin_amdgcn_s_setprio(0); } while (0)
; #define PG8_WAIT_L(n) asm volatile("s_waitcnt lgkmcnt(" #n ")" ::: "memory")
; #define PG8_BAR __builtin_amdgcn_s_barrier()
; #define PG8_SCHED __builtin_amdgcn_sched_barrier(0)
; template <class Epi, class Sched, bool ATILE = false>
; __device__ __forceinline__ void gemm_phase(LAS unsigned char* lds, const Gemm g, const Sched& S, const Epi& E) {
;     ...
;         for (int t = 0; t < nt; t += 2) {
;             const bool last = (t == nt - 2);
;             const char* a1 = cA + (size_t)(t + 1) * kstepA;
;             const char* a2 = last ? nA : cA + (size_t)(t + 2) * kstepA; const char* b2 = last ? nB : cB + (size_t)(t + 2) * kstep;
;             const char* a3 = a2 + kstepA; const char* b3 = b2 + kstep;
;             PG8_LDB(B0, 0, 0); PG8_SCHED; PG8_LDA(At, 0, 0); PG8_STAGE(PG8_SA(1, 1), a1 + hstepA, voffA);
;             PG8_WAIT_L(8); PG8_BAR; PG8_WAIT_L(0); PG8_MMA(0, 0, At, B0); PG8_BAR; PG8_SCHED;
;             PG8_LDB(B1, 0, 1); PG8_STAGE(PG8_SB(0, 0), b2, voffB);
;             PG8_BAR; PG8_WAIT_L(0); PG8_MMA(0, 1, At, B1); PG8_BAR;
;             PG8_LDA(At, 0, 1); PG8_STAGE(PG8_SA(0, 0), a2, voffA);
;             PG8_BAR; PG8_WAIT_L(0); PG8_MMA(1, 0, At, B0); PG8_BAR; PG8_SCHED;
.LBB0_1426:
	ds_read_b128 v[162:165], v147
	ds_read_b128 v[166:169], v147 offset:1024
	ds_read_b128 v[170:173], v147 offset:2048
	ds_read_b128 v[174:177], v147 offset:3072
	s_add_i32 s58, s18, 2
	s_add_u32 s16, s12, 0x100
	s_addc_u32 s17, s13, 0
	s_cmp_eq_u32 s55, s18
	s_cselect_b32 s18, s10, s56
	s_cselect_b32 s21, s7, s17
	s_cselect_b32 s20, s6, s16
	s_cselect_b32 s19, s11, s57
	s_mov_b32 m0, s30
	v_lshl_add_u64 v[144:145], s[12:13], 0, v[140:141]
	ds_read_b128 v[178:181], v148
	ds_read_b128 v[182:185], v148 offset:1024
	ds_read_b128 v[186:189], v148 offset:2048
	ds_read_b128 v[190:193], v148 offset:3072
	ds_read_b128 v[194:197], v148 offset:4096
	ds_read_b128 v[198:201], v148 offset:5120
	ds_read_b128 v[202:205], v148 offset:6144
	ds_read_b128 v[206:209], v148 offset:7168
	global_load_lds_dwordx4 v[144:145], off
	v_lshl_add_u64 v[144:145], s[12:13], 0, v[142:143]
	s_mov_b32 m0, s31
	s_nop 0
	global_load_lds_dwordx4 v[144:145], off
	s_waitcnt lgkmcnt(8)
	s_barrier
	s_waitcnt lgkmcnt(0)
	s_setprio 1
	s_waitcnt lgkmcnt(0)
	v_mfma_f32_16x16x32_bf16 v[124:127], v[162:165], v[178:181], v[124:127]
	v_mfma_f32_16x16x32_bf16 v[120:123], v[170:173], v[178:181], v[120:123]
	v_mfma_f32_16x16x32_bf16 v[108:111], v[162:165], v[186:189], v[108:111]
	v_mfma_f32_16x16x32_bf16 v[104:107], v[170:173], v[186:189], v[104:107]
	v_mfma_f32_16x16x32_bf16 v[92:95], v[162:165], v[194:197], v[92:95]
	v_mfma_f32_16x16x32_bf16 v[88:91], v[170:173], v[194:197], v[88:91]
	v_mfma_f32_16x16x32_bf16 v[76:79], v[162:165], v[202:205], v[76:79]
	v_mfma_f32_16x16x32_bf16 v[72:75], v[170:173], v[202:205], v[72:75]
	v_mfma_f32_16x16x32_bf16 v[124:127], v[166:169], v[182:185], v[124:127]
	v_mfma_f32_16x16x32_bf16 v[120:123], v[174:177], v[182:185], v[120:123]
	v_mfma_f32_16x16x32_bf16 v[108:111], v[166:169], v[190:193], v[108:111]
	v_mfma_f32_16x16x32_bf16 v[104:107], v[174:177], v[190:193], v[104:107]
	v_mfma_f32_16x16x32_bf16 v[92:95], v[166:169], v[198:201], v[92:95]
	v_mfma_f32_16x16x32_bf16 v[88:91], v[174:177], v[198:201], v[88:91]
	v_mfma_f32_16x16x32_bf16 v[76:79], v[166:169], v[206:209], v[76:79]
	v_mfma_f32_16x16x32_bf16 v[72:75], v[174:177], v[206:209], v[72:75]
	s_setprio 0
	s_barrier
	s_mov_b32 m0, s33
	v_lshl_add_u64 v[144:145], s[18:19], 0, v[132:133]
	ds_read_b128 v[210:213], v149
	ds_read_b128 v[214:217], v149 offset:1024
	ds_read_b128 v[218:221], v149 offset:2048
	ds_read_b128 v[222:225], v149 offset:3072
	global_load_lds_dwordx4 v[144:145], off
	v_lshl_add_u64 v[226:227], s[18:19], 0, v[128:129]
	s_mov_b32 m0, s34
	s_nop 0
	global_load_lds_dwordx4 v[226:227], off
	s_barrier
	s_waitcnt lgkmcnt(0)
	s_setprio 1
	s_waitcnt lgkmcnt(0)
	v_mfma_f32_16x16x32_bf16 v[116:119], v[210:213], v[178:181], v[116:119]
	v_mfma_f32_16x16x32_bf16 v[112:115], v[218:221], v[178:181], v[112:115]
	v_mfma_f32_16x16x32_bf16 v[100:103], v[210:213], v[186:189], v[100:103]
	v_mfma_f32_16x16x32_bf16 v[96:99], v[218:221], v[186:189], v[96:99]
	v_mfma_f32_16x16x32_bf16 v[84:87], v[210:213], v[194:197], v[84:87]
	v_mfma_f32_16x16x32_bf16 v[80:83], v[218:221], v[194:197], v[80:83]
	v_mfma_f32_16x16x32_bf16 v[68:71], v[210:213], v[202:205], v[68:71]
	v_mfma_f32_16x16x32_bf16 v[64:67], v[218:221], v[202:205], v[64:67]
	v_mfma_f32_16x16x32_bf16 v[116:119], v[214:217], v[182:185], v[116:119]
	v_mfma_f32_16x16x32_bf16 v[112:115], v[222:225], v[182:185], v[112:115]
	v_mfma_f32_16x16x32_bf16 v[100:103], v[214:217], v[190:193], v[100:103]
	v_mfma_f32_16x16x32_bf16 v[96:99], v[222:225], v[190:193], v[96:99]
	v_mfma_f32_16x16x32_bf16 v[84:87], v[214:217], v[198:201], v[84:87]
	v_mfma_f32_16x16x32_bf16 v[80:83], v[222:225], v[198:201], v[80:83]
	v_mfma_f32_16x16x32_bf16 v[68:71], v[214:217], v[206:209], v[68:71]
	v_mfma_f32_16x16x32_bf16 v[64:67], v[222:225], v[206:209], v[64:67]
	s_setprio 0
	s_barrier
	s_mov_b32 m0, s22
	v_lshl_add_u64 v[228:229], s[20:21], 0, v[134:135]
	ds_read_b128 v[178:181], v148 offset:16384
	ds_read_b128 v[182:185], v148 offset:17408
	ds_read_b128 v[186:189], v148 offset:18432
	ds_read_b128 v[190:193], v148 offset:19456
	ds_read_b128 v[194:197], v148 offset:20480
	ds_read_b128 v[198:201], v148 offset:21504
	ds_read_b128 v[202:205], v148 offset:22528
	ds_read_b128 v[206:209], v148 offset:23552
	global_load_lds_dwordx4 v[228:229], off
	v_lshl_add_u64 v[230:231], s[20:21], 0, v[130:131]
	s_mov_b32 m0, s23
	s_nop 0
	global_load_lds_dwordx4 v[230:231], off
	s_barrier
	s_waitcnt lgkmcnt(0)
	s_setprio 1
	s_waitcnt lgkmcnt(0)
	v_mfma_f32_16x16x32_bf16 v[60:63], v[162:165], v[178:181], v[60:63]
	v_mfma_f32_16x16x32_bf16 v[56:59], v[170:173], v[178:181], v[56:59]
	v_mfma_f32_16x16x32_bf16 v[44:47], v[162:165], v[186:189], v[44:47]
	v_mfma_f32_16x16x32_bf16 v[40:43], v[170:173], v[186:189], v[40:43]
	v_mfma_f32_16x16x32_bf16 v[28:31], v[162:165], v[194:197], v[28:31]
	v_mfma_f32_16x16x32_bf16 v[24:27], v[170:173], v[194:197], v[24:27]
	v_mfma_f32_16x16x32_bf16 v[12:15], v[162:165], v[202:205], v[12:15]
	v_mfma_f32_16x16x32_bf16 v[8:11], v[170:173], v[202:205], v[8:11]
	v_mfma_f32_16x16x32_bf16 v[60:63], v[166:169], v[182:185], v[60:63]
	v_mfma_f32_16x16x32_bf16 v[56:59], v[174:177], v[182:185], v[56:59]
	v_mfma_f32_16x16x32_bf16 v[44:47], v[166:169], v[190:193], v[44:47]
	v_mfma_f32_16x16x32_bf16 v[40:43], v[174:177], v[190:193], v[40:43]
	v_mfma_f32_16x16x32_bf16 v[28:31], v[166:169], v[198:201], v[28:31]
	v_mfma_f32_16x16x32_bf16 v[24:27], v[174:177], v[198:201], v[24:27]
	v_mfma_f32_16x16x32_bf16 v[12:15], v[166:169], v[206:209], v[12:15]
	v_mfma_f32_16x16x32_bf16 v[8:11], v[174:177], v[206:209], v[8:11]
	s_setprio 0
	s_barrier
; #define PG8_STAGE(bufoff, gbase, voff) do { _Pragma("unroll") for (int _i = 0; _i < 2; ++_i) \
;         __builtin_amdgcn_global_load_lds((const unsigned*)((const char*)(gbase) + (voff)[_i]), (LAS unsigned*)(lds + (bufoff) + ldsw + _i * 8192), 16, 0, 0); } while (0)
; #define PG8_LDA(dst, b, h) do { _Pragma("unroll") for (int m = 0; m < 4; ++m) _Pragma("unroll") for (int k = 0; k < 2; ++k) dst[m][k] = *(const LAS bf16x8*)(lds + PG8_SA(b, h) + aoff + m * 2048 + k * 1024); } while (0)
; #define PG8_LDB(dst, b, h) do { _Pragma("unroll") for (int n = 0; n < 2; ++n) _Pragma("unroll") for (int k = 0; k < 2; ++k) dst[n][k] = *(const LAS bf16x8*)(lds + PG8_SB(b, h) + boff + n * 2048 + k * 1024); } while (0)
; #define PG8_MMA(ai, bj, At, Bt) do { __builtin_amdgcn_s_setprio(1); _Pragma("unroll") for (int m = 0; m < 4; ++m) _Pragma("unroll") for (int n = 0; n < 2; ++n) _Pragma("unroll") for (int k = 0; k < 2; ++k) \
;         acc[ai][bj][m][n] = __builtin_amdgcn_mfma_f32_16x16x32_bf16(Bt[n][k], At[m][k], acc[ai][bj][m][n], 0, 0, 0); __builtin_amdgcn_s_setprio(0); } while (0)
; #define PG8_WAIT_V(n) asm volatile("s_waitcnt vmcnt(" #n ")" ::: "memory")
; #define PG8_WAIT_L(n) asm volatile("s_waitcnt lgkmcnt(" #n ")" ::: "memory")
; #define PG8_BAR __builtin_amdgcn_s_barrier()
; #define PG8_SCHED __builtin_amdgcn_sched_barrier(0)
; template <class Epi, class Sched, bool ATILE = false>
; __device__ __forceinline__ void gemm_phase(LAS unsigned char* lds, const Gemm g, const Sched& S, const Epi& E) {
;     ...
;             PG8_BAR; PG8_WAIT_L(0); PG8_MMA(1, 0, At, B0); PG8_BAR; PG8_SCHED;
;             PG8_STAGE(PG8_SB(0, 1), b2 + hstepB, voffB);
;             PG8_WAIT_V(6); PG8_BAR; PG8_MMA(1, 1, At, B1); PG8_BAR;
;             PG8_LDB(B0, 1, 0); PG8_SCHED; PG8_LDA(At, 1, 0); PG8_STAGE(PG8_SA(0, 1), a2 + hstepA, voffA);
;             PG8_WAIT_L(8); PG8_BAR; PG8_WAIT_L(0); PG8_MMA(0, 0, At, B0); PG8_BAR; PG8_SCHED;
;             PG8_LDB(B1, 1, 1); PG8_STAGE(PG8_SB(1, 0), b3, voffB);
;             PG8_BAR; PG8_WAIT_L(0); PG8_MMA(0, 1, At, B1); PG8_BAR;
	s_add_u32 s12, s18, 0x18000
	s_addc_u32 s13, s19, 0
	s_mov_b32 m0, s35
	s_nop 0
	global_load_lds_dwordx4 v132, s[12:13]
	s_mov_b32 m0, s36
	s_nop 0
	global_load_lds_dwordx4 v128, s[12:13]
	s_waitcnt vmcnt(6)
	s_barrier
	s_setprio 1
	v_mfma_f32_16x16x32_bf16 v[52:55], v[210:213], v[178:181], v[52:55]
	v_mfma_f32_16x16x32_bf16 v[48:51], v[218:221], v[178:181], v[48:51]
	v_mfma_f32_16x16x32_bf16 v[36:39], v[210:213], v[186:189], v[36:39]
	v_mfma_f32_16x16x32_bf16 v[32:35], v[218:221], v[186:189], v[32:35]
	v_mfma_f32_16x16x32_bf16 v[20:23], v[210:213], v[194:197], v[20:23]
	v_mfma_f32_16x16x32_bf16 v[16:19], v[218:221], v[194:197], v[16:19]
	v_mfma_f32_16x16x32_bf16 v[4:7], v[210:213], v[202:205], v[4:7]
	v_mfma_f32_16x16x32_bf16 v[0:3], v[218:221], v[202:205], v[0:3]
	v_mfma_f32_16x16x32_bf16 v[52:55], v[214:217], v[182:185], v[52:55]
	v_mfma_f32_16x16x32_bf16 v[48:51], v[222:225], v[182:185], v[48:51]
	v_mfma_f32_16x16x32_bf16 v[36:39], v[214:217], v[190:193], v[36:39]
	v_mfma_f32_16x16x32_bf16 v[32:35], v[222:225], v[190:193], v[32:35]
	v_mfma_f32_16x16x32_bf16 v[20:23], v[214:217], v[198:201], v[20:23]
	v_mfma_f32_16x16x32_bf16 v[16:19], v[222:225], v[198:201], v[16:19]
	v_mfma_f32_16x16x32_bf16 v[4:7], v[214:217], v[206:209], v[4:7]
	v_mfma_f32_16x16x32_bf16 v[0:3], v[222:225], v[206:209], v[0:3]
	s_setprio 0
	s_barrier
	ds_read_b128 v[162:165], v150
	ds_read_b128 v[166:169], v150 offset:1024
	ds_read_b128 v[170:173], v150 offset:2048
	ds_read_b128 v[174:177], v150 offset:3072
	s_add_u32 s12, s20, 0x18000
	s_addc_u32 s13, s21, 0
	s_mov_b32 m0, s24
	ds_read_b128 v[178:181], v148 offset:32768
	ds_read_b128 v[182:185], v148 offset:33792
	ds_read_b128 v[186:189], v148 offset:34816
	ds_read_b128 v[190:193], v148 offset:35840
	ds_read_b128 v[194:197], v148 offset:36864
	ds_read_b128 v[198:201], v148 offset:37888
	ds_read_b128 v[202:205], v148 offset:38912
	ds_read_b128 v[206:209], v148 offset:39936
	global_load_lds_dwordx4 v134, s[12:13]
	s_mov_b32 m0, s25
	s_nop 0
	global_load_lds_dwordx4 v130, s[12:13]
	s_waitcnt lgkmcnt(8)
	s_barrier
	s_waitcnt lgkmcnt(0)
	s_setprio 1
	s_waitcnt lgkmcnt(0)
	v_mfma_f32_16x16x32_bf16 v[124:127], v[162:165], v[178:181], v[124:127]
	v_mfma_f32_16x16x32_bf16 v[120:123], v[170:173], v[178:181], v[120:123]
	v_mfma_f32_16x16x32_bf16 v[108:111], v[162:165], v[186:189], v[108:111]
	v_mfma_f32_16x16x32_bf16 v[104:107], v[170:173], v[186:189], v[104:107]
	v_mfma_f32_16x16x32_bf16 v[92:95], v[162:165], v[194:197], v[92:95]
	v_mfma_f32_16x16x32_bf16 v[88:91], v[170:173], v[194:197], v[88:91]
	v_mfma_f32_16x16x32_bf16 v[76:79], v[162:165], v[202:205], v[76:79]
	v_mfma_f32_16x16x32_bf16 v[72:75], v[170:173], v[202:205], v[72:75]
	v_mfma_f32_16x16x32_bf16 v[124:127], v[166:169], v[182:185], v[124:127]
	v_mfma_f32_16x16x32_bf16 v[120:123], v[174:177], v[182:185], v[120:123]
	v_mfma_f32_16x16x32_bf16 v[108:111], v[166:169], v[190:193], v[108:111]
	v_mfma_f32_16x16x32_bf16 v[104:107], v[174:177], v[190:193], v[104:107]
	v_mfma_f32_16x16x32_bf16 v[92:95], v[166:169], v[198:201], v[92:95]
	v_mfma_f32_16x16x32_bf16 v[88:91], v[174:177], v[198:201], v[88:91]
	v_mfma_f32_16x16x32_bf16 v[76:79], v[166:169], v[206:209], v[76:79]
	v_mfma_f32_16x16x32_bf16 v[72:75], v[174:177], v[206:209], v[72:75]
	s_setprio 0
	s_barrier
	s_mov_b32 m0, s40
	v_lshl_add_u64 v[144:145], v[144:145], 0, s[0:1]
	ds_read_b128 v[210:213], v157
	ds_read_b128 v[214:217], v157 offset:1024
	ds_read_b128 v[218:221], v157 offset:2048
	ds_read_b128 v[222:225], v157 offset:3072
	global_load_lds_dwordx4 v[144:145], off
	v_lshl_add_u64 v[144:145], v[226:227], 0, s[0:1]
	s_mov_b32 m0, s41
	s_nop 0
	global_load_lds_dwordx4 v[144:145], off
	s_barrier
; #define PG8_STAGE(bufoff, gbase, voff) do { _Pragma("unroll") for (int _i = 0; _i < 2; ++_i) \
;         __builtin_amdgcn_global_load_lds((const unsigned*)((const char*)(gbase) + (voff)[_i]), (LAS unsigned*)(lds + (bufoff) + ldsw + _i * 8192), 16, 0, 0); } while (0)
; #define PG8_LDA(dst, b, h) do { _Pragma("unroll") for (int m = 0; m < 4; ++m) _Pragma("unroll") for (int k = 0; k < 2; ++k) dst[m][k] = *(const LAS bf16x8*)(lds + PG8_SA(b, h) + aoff + m * 2048 + k * 1024); } while (0)
; #define PG8_MMA(ai, bj, At, Bt) do { __builtin_amdgcn_s_setprio(1); _Pragma("unroll") for (int m = 0; m < 4; ++m) _Pragma("unroll") for (int n = 0; n < 2; ++n) _Pragma("unroll") for (int k = 0; k < 2; ++k) \
;         acc[ai][bj][m][n] = __builtin_amdgcn_mfma_f32_16x16x32_bf16(Bt[n][k], At[m][k], acc[ai][bj][m][n], 0, 0, 0); __builtin_amdgcn_s_setprio(0); } while (0)
; #define PG8_WAIT_V(n) asm volatile("s_waitcnt vmcnt(" #n ")" ::: "memory")
; #define PG8_WAIT_L(n) asm volatile("s_waitcnt lgkmcnt(" #n ")" ::: "memory")
; #define PG8_BAR __builtin_amdgcn_s_barrier()
; #define PG8_SCHED __builtin_amdgcn_sched_barrier(0)
; template <class Epi, class Sched, bool ATILE = false>
; __device__ __forceinline__ void gemm_phase(LAS unsigned char* lds, const Gemm g, const Sched& S, const Epi& E) {
;     ...
;             PG8_BAR; PG8_WAIT_L(0); PG8_MMA(0, 1, At, B1); PG8_BAR;
;             PG8_LDA(At, 1, 1); PG8_STAGE(PG8_SA(1, 0), a3, voffA);
;             PG8_BAR; PG8_WAIT_L(0); PG8_MMA(1, 0, At, B0); PG8_BAR; PG8_SCHED;
;             PG8_STAGE(PG8_SB(1, 1), b3 + hstepB, voffB);
;             PG8_WAIT_V(6); PG8_BAR; PG8_MMA(1, 1, At, B1); PG8_BAR;
;         }
	s_waitcnt lgkmcnt(0)
	s_setprio 1
	s_waitcnt lgkmcnt(0)
	v_mfma_f32_16x16x32_bf16 v[116:119], v[210:213], v[178:181], v[116:119]
	v_mfma_f32_16x16x32_bf16 v[112:115], v[218:221], v[178:181], v[112:115]
	v_mfma_f32_16x16x32_bf16 v[100:103], v[210:213], v[186:189], v[100:103]
	v_mfma_f32_16x16x32_bf16 v[96:99], v[218:221], v[186:189], v[96:99]
	v_mfma_f32_16x16x32_bf16 v[84:87], v[210:213], v[194:197], v[84:87]
	v_mfma_f32_16x16x32_bf16 v[80:83], v[218:221], v[194:197], v[80:83]
	v_mfma_f32_16x16x32_bf16 v[68:71], v[210:213], v[202:205], v[68:71]
	v_mfma_f32_16x16x32_bf16 v[64:67], v[218:221], v[202:205], v[64:67]
	v_mfma_f32_16x16x32_bf16 v[116:119], v[214:217], v[182:185], v[116:119]
	v_mfma_f32_16x16x32_bf16 v[112:115], v[222:225], v[182:185], v[112:115]
	v_mfma_f32_16x16x32_bf16 v[100:103], v[214:217], v[190:193], v[100:103]
	v_mfma_f32_16x16x32_bf16 v[96:99], v[222:225], v[190:193], v[96:99]
	v_mfma_f32_16x16x32_bf16 v[84:87], v[214:217], v[198:201], v[84:87]
	v_mfma_f32_16x16x32_bf16 v[80:83], v[222:225], v[198:201], v[80:83]
	v_mfma_f32_16x16x32_bf16 v[68:71], v[214:217], v[206:209], v[68:71]
	v_mfma_f32_16x16x32_bf16 v[64:67], v[222:225], v[206:209], v[64:67]
	s_setprio 0
	s_barrier
	s_mov_b32 m0, s28
	v_lshl_add_u64 v[144:145], v[228:229], 0, s[0:1]
	ds_read_b128 v[178:181], v148 offset:49152
	ds_read_b128 v[182:185], v148 offset:50176
	ds_read_b128 v[186:189], v148 offset:51200
	ds_read_b128 v[190:193], v148 offset:52224
	ds_read_b128 v[194:197], v148 offset:53248
	ds_read_b128 v[198:201], v148 offset:54272
	ds_read_b128 v[202:205], v148 offset:55296
	ds_read_b128 v[206:209], v148 offset:56320
	global_load_lds_dwordx4 v[144:145], off
	v_lshl_add_u64 v[144:145], v[230:231], 0, s[0:1]
	s_mov_b32 m0, s29
	s_nop 0
	global_load_lds_dwordx4 v[144:145], off
	s_barrier
	s_waitcnt lgkmcnt(0)
	s_setprio 1
	s_waitcnt lgkmcnt(0)
	v_mfma_f32_16x16x32_bf16 v[60:63], v[162:165], v[178:181], v[60:63]
	v_mfma_f32_16x16x32_bf16 v[56:59], v[170:173], v[178:181], v[56:59]
	v_mfma_f32_16x16x32_bf16 v[44:47], v[162:165], v[186:189], v[44:47]
	v_mfma_f32_16x16x32_bf16 v[40:43], v[170:173], v[186:189], v[40:43]
	v_mfma_f32_16x16x32_bf16 v[28:31], v[162:165], v[194:197], v[28:31]
	v_mfma_f32_16x16x32_bf16 v[24:27], v[170:173], v[194:197], v[24:27]
	v_mfma_f32_16x16x32_bf16 v[12:15], v[162:165], v[202:205], v[12:15]
	v_mfma_f32_16x16x32_bf16 v[8:11], v[170:173], v[202:205], v[8:11]
	v_mfma_f32_16x16x32_bf16 v[60:63], v[166:169], v[182:185], v[60:63]
	v_mfma_f32_16x16x32_bf16 v[56:59], v[174:177], v[182:185], v[56:59]
	v_mfma_f32_16x16x32_bf16 v[44:47], v[166:169], v[190:193], v[44:47]
	v_mfma_f32_16x16x32_bf16 v[40:43], v[174:177], v[190:193], v[40:43]
	v_mfma_f32_16x16x32_bf16 v[28:31], v[166:169], v[198:201], v[28:31]
	v_mfma_f32_16x16x32_bf16 v[24:27], v[174:177], v[198:201], v[24:27]
	v_mfma_f32_16x16x32_bf16 v[12:15], v[166:169], v[206:209], v[12:15]
	v_mfma_f32_16x16x32_bf16 v[8:11], v[174:177], v[206:209], v[8:11]
	s_setprio 0
	s_barrier
	s_add_u32 s12, s18, 0x18080
	s_addc_u32 s13, s19, 0
	s_mov_b32 m0, s42
	s_nop 0
	global_load_lds_dwordx4 v132, s[12:13]
	s_mov_b32 m0, s43
	s_nop 0
	global_load_lds_dwordx4 v128, s[12:13]
	s_waitcnt vmcnt(6)
	s_barrier
	s_setprio 1
	v_mfma_f32_16x16x32_bf16 v[52:55], v[210:213], v[178:181], v[52:55]
	v_mfma_f32_16x16x32_bf16 v[48:51], v[218:221], v[178:181], v[48:51]
	v_mfma_f32_16x16x32_bf16 v[36:39], v[210:213], v[186:189], v[36:39]
	v_mfma_f32_16x16x32_bf16 v[32:35], v[218:221], v[186:189], v[32:35]
	v_mfma_f32_16x16x32_bf16 v[20:23], v[210:213], v[194:197], v[20:23]
	v_mfma_f32_16x16x32_bf16 v[16:19], v[218:221], v[194:197], v[16:19]
	v_mfma_f32_16x16x32_bf16 v[4:7], v[210:213], v[202:205], v[4:7]
	v_mfma_f32_16x16x32_bf16 v[0:3], v[218:221], v[202:205], v[0:3]
	v_mfma_f32_16x16x32_bf16 v[52:55], v[214:217], v[182:185], v[52:55]
	v_mfma_f32_16x16x32_bf16 v[48:51], v[222:225], v[182:185], v[48:51]
	v_mfma_f32_16x16x32_bf16 v[36:39], v[214:217], v[190:193], v[36:39]
	v_mfma_f32_16x16x32_bf16 v[32:35], v[222:225], v[190:193], v[32:35]
	v_mfma_f32_16x16x32_bf16 v[20:23], v[214:217], v[198:201], v[20:23]
	v_mfma_f32_16x16x32_bf16 v[16:19], v[222:225], v[198:201], v[16:19]
	v_mfma_f32_16x16x32_bf16 v[4:7], v[214:217], v[206:209], v[4:7]
	v_mfma_f32_16x16x32_bf16 v[0:3], v[222:225], v[206:209], v[0:3]
	s_setprio 0
	s_barrier
	s_add_u32 s56, s56, 0x100
	s_addc_u32 s57, s57, 0
	s_cmp_ge_i32 s58, s54
	s_mov_b64 s[12:13], s[16:17]
	s_mov_b32 s18, s58
	s_cbranch_scc0 .LBB0_1426
	s_branch .LBB0_1428

; #define PG8_STAGE(bufoff, gbase, voff) do { _Pragma("unroll") for (int _i = 0; _i < 2; ++_i) \
;         __builtin_amdgcn_global_load_lds((const unsigned*)((const char*)(gbase) + (voff)[_i]), (LAS unsigned*)(lds + (bufoff) + ldsw + _i * 8192), 16, 0, 0); } while (0)
; #define PG8_LDA(dst, b, h) do { _Pragma("unroll") for (int m = 0; m < 4; ++m) _Pragma("unroll") for (int k = 0; k < 2; ++k) dst[m][k] = *(const LAS bf16x8*)(lds + PG8_SA(b, h) + aoff + m * 2048 + k * 1024); } while (0)
; #define PG8_LDB(dst, b, h) do { _Pragma("unroll") for (int n = 0; n < 2; ++n) _Pragma("unroll") for (int k = 0; k < 2; ++k) dst[n][k] = *(const LAS bf16x8*)(lds + PG8_SB(b, h) + boff + n * 2048 + k * 1024); } while (0)
; #define PG8_MMA(ai, bj, At, Bt) do { __builtin_amdgcn_s_setprio(1); _Pragma("unroll") for (int m = 0; m < 4; ++m) _Pragma("unroll") for (int n = 0; n < 2; ++n) _Pragma("unroll") for (int k = 0; k < 2; ++k) \
;         acc[ai][bj][m][n] = __builtin_amdgcn_mfma_f32_16x16x32_bf16(Bt[n][k], At[m][k], acc[ai][bj][m][n], 0, 0, 0); __builtin_amdgcn_s_setprio(0); } while (0)
; #define PG8_WAIT_L(n) asm volatile("s_waitcnt lgkmcnt(" #n ")" ::: "memory")
; #define PG8_BAR __builtin_amdgcn_s_barrier()
; #define PG8_SCHED __builtin_amdgcn_sched_barrier(0)
; template <class Epi, class Sched, bool ATILE = false>
; __device__ __forceinline__ void gemm_phase(LAS unsigned char* lds, const Gemm g, const Sched& S, const Epi& E) {
;     ...
;         for (int t = 0; t < nt; t += 2) {
;             const bool last = (t == nt - 2);
;             const char* a1 = cA + (size_t)(t + 1) * kstepA;
;             const char* a2 = last ? nA : cA + (size_t)(t + 2) * kstepA; const char* b2 = last ? nB : cB + (size_t)(t + 2) * kstep;
;             const char* a3 = a2 + kstepA; const char* b3 = b2 + kstep;
;             PG8_LDB(B0, 0, 0); PG8_SCHED; PG8_LDA(At, 0, 0); PG8_STAGE(PG8_SA(1, 1), a1 + hstepA, voffA);
;             PG8_WAIT_L(8); PG8_BAR; PG8_WAIT_L(0); PG8_MMA(0, 0, At, B0); PG8_BAR; PG8_SCHED;
;             PG8_LDB(B1, 0, 1); PG8_STAGE(PG8_SB(0, 0), b2, voffB);
;             PG8_BAR; PG8_WAIT_L(0); PG8_MMA(0, 1, At, B1); PG8_BAR;
;             PG8_LDA(At, 0, 1); PG8_STAGE(PG8_SA(0, 0), a2, voffA);
;             PG8_BAR; PG8_WAIT_L(0); PG8_MMA(1, 0, At, B0); PG8_BAR; PG8_SCHED;
.LBB0_1517:
	ds_read_b128 v[96:99], v182
	ds_read_b128 v[100:103], v182 offset:1024
	ds_read_b128 v[112:115], v182 offset:2048
	ds_read_b128 v[116:119], v182 offset:3072
	s_add_i32 s54, s26, 2
	s_add_u32 s27, s24, 0xfffc0080
	s_addc_u32 s28, s25, -1
	s_cmp_eq_u32 s45, s26
	s_cselect_b32 s26, s44, s52
	s_cselect_b32 s29, s17, s28
	s_cselect_b32 s28, s42, s27
	s_cselect_b32 s27, s43, s53
	s_add_i32 m0, s23, 0xc000
	ds_read_b128 v[144:147], v183
	ds_read_b128 v[174:177], v183 offset:1024
	ds_read_b128 v[178:181], v183 offset:2048
	ds_read_b128 v[186:189], v183 offset:3072
	ds_read_b128 v[190:193], v183 offset:4096
	ds_read_b128 v[194:197], v183 offset:5120
	ds_read_b128 v[198:201], v183 offset:6144
	ds_read_b128 v[202:205], v183 offset:7168
	global_load_lds_dwordx4 v166, s[24:25]
	s_add_i32 m0, s23, 0xe000
	s_nop 0
	global_load_lds_dwordx4 v168, s[24:25]
	s_waitcnt lgkmcnt(8)
	s_barrier
	s_waitcnt lgkmcnt(0)
	s_setprio 1
	s_waitcnt lgkmcnt(0)
	v_mfma_f32_16x16x32_bf16 v[140:143], v[96:99], v[144:147], v[140:143]
	v_mfma_f32_16x16x32_bf16 v[136:139], v[112:115], v[144:147], v[136:139]
	v_mfma_f32_16x16x32_bf16 v[124:127], v[96:99], v[178:181], v[124:127]
	v_mfma_f32_16x16x32_bf16 v[120:123], v[112:115], v[178:181], v[120:123]
	v_mfma_f32_16x16x32_bf16 v[92:95], v[96:99], v[190:193], v[92:95]
	v_mfma_f32_16x16x32_bf16 v[88:91], v[112:115], v[190:193], v[88:91]
	v_mfma_f32_16x16x32_bf16 v[76:79], v[96:99], v[198:201], v[76:79]
	v_mfma_f32_16x16x32_bf16 v[72:75], v[112:115], v[198:201], v[72:75]
	v_mfma_f32_16x16x32_bf16 v[140:143], v[100:103], v[174:177], v[140:143]
	v_mfma_f32_16x16x32_bf16 v[136:139], v[116:119], v[174:177], v[136:139]
	v_mfma_f32_16x16x32_bf16 v[124:127], v[100:103], v[186:189], v[124:127]
	v_mfma_f32_16x16x32_bf16 v[120:123], v[116:119], v[186:189], v[120:123]
	v_mfma_f32_16x16x32_bf16 v[92:95], v[100:103], v[194:197], v[92:95]
	v_mfma_f32_16x16x32_bf16 v[88:91], v[116:119], v[194:197], v[88:91]
	v_mfma_f32_16x16x32_bf16 v[76:79], v[100:103], v[202:205], v[76:79]
	v_mfma_f32_16x16x32_bf16 v[72:75], v[116:119], v[202:205], v[72:75]
	s_setprio 0
	s_barrier
	s_add_i32 s55, s39, s5
	v_lshl_add_u64 v[222:223], s[26:27], 0, v[150:151]
	s_mov_b32 m0, s55
	ds_read_b128 v[206:209], v184
	ds_read_b128 v[210:213], v184 offset:1024
	ds_read_b128 v[214:217], v184 offset:2048
	ds_read_b128 v[218:221], v184 offset:3072
	global_load_lds_dwordx4 v[222:223], off
	v_lshl_add_u64 v[224:225], s[26:27], 0, v[164:165]
	s_add_i32 m0, s55, 0x2000
	s_nop 0
	global_load_lds_dwordx4 v[224:225], off
	s_barrier
	s_waitcnt lgkmcnt(0)
	s_setprio 1
	s_waitcnt lgkmcnt(0)
	v_mfma_f32_16x16x32_bf16 v[132:135], v[206:209], v[144:147], v[132:135]
	v_mfma_f32_16x16x32_bf16 v[128:131], v[214:217], v[144:147], v[128:131]
	v_mfma_f32_16x16x32_bf16 v[108:111], v[206:209], v[178:181], v[108:111]
	v_mfma_f32_16x16x32_bf16 v[104:107], v[214:217], v[178:181], v[104:107]
	v_mfma_f32_16x16x32_bf16 v[84:87], v[206:209], v[190:193], v[84:87]
	v_mfma_f32_16x16x32_bf16 v[80:83], v[214:217], v[190:193], v[80:83]
	v_mfma_f32_16x16x32_bf16 v[68:71], v[206:209], v[198:201], v[68:71]
	v_mfma_f32_16x16x32_bf16 v[64:67], v[214:217], v[198:201], v[64:67]
	v_mfma_f32_16x16x32_bf16 v[132:135], v[210:213], v[174:177], v[132:135]
	v_mfma_f32_16x16x32_bf16 v[128:131], v[218:221], v[174:177], v[128:131]
	v_mfma_f32_16x16x32_bf16 v[108:111], v[210:213], v[186:189], v[108:111]
	v_mfma_f32_16x16x32_bf16 v[104:107], v[218:221], v[186:189], v[104:107]
	v_mfma_f32_16x16x32_bf16 v[84:87], v[210:213], v[194:197], v[84:87]
	v_mfma_f32_16x16x32_bf16 v[80:83], v[218:221], v[194:197], v[80:83]
	v_mfma_f32_16x16x32_bf16 v[68:71], v[210:213], v[202:205], v[68:71]
	v_mfma_f32_16x16x32_bf16 v[64:67], v[218:221], v[202:205], v[64:67]
	s_setprio 0
	s_barrier
	s_mov_b32 m0, s23
	v_lshl_add_u64 v[226:227], s[28:29], 0, v[148:149]
	ds_read_b128 v[144:147], v183 offset:16384
	ds_read_b128 v[174:177], v183 offset:17408
	ds_read_b128 v[178:181], v183 offset:18432
	ds_read_b128 v[186:189], v183 offset:19456
	ds_read_b128 v[190:193], v183 offset:20480
	ds_read_b128 v[194:197], v183 offset:21504
	ds_read_b128 v[198:201], v183 offset:22528
	ds_read_b128 v[202:205], v183 offset:23552
	global_load_lds_dwordx4 v[226:227], off
	v_lshl_add_u64 v[228:229], s[28:29], 0, v[162:163]
	s_mov_b32 m0, s30
	s_nop 0
	global_load_lds_dwordx4 v[228:229], off
	s_barrier
	s_waitcnt lgkmcnt(0)
	s_setprio 1
	s_waitcnt lgkmcnt(0)
	v_mfma_f32_16x16x32_bf16 v[60:63], v[96:99], v[144:147], v[60:63]
	v_mfma_f32_16x16x32_bf16 v[56:59], v[112:115], v[144:147], v[56:59]
	v_mfma_f32_16x16x32_bf16 v[44:47], v[96:99], v[178:181], v[44:47]
	v_mfma_f32_16x16x32_bf16 v[40:43], v[112:115], v[178:181], v[40:43]
	v_mfma_f32_16x16x32_bf16 v[28:31], v[96:99], v[190:193], v[28:31]
	v_mfma_f32_16x16x32_bf16 v[24:27], v[112:115], v[190:193], v[24:27]
	v_mfma_f32_16x16x32_bf16 v[12:15], v[96:99], v[198:201], v[12:15]
	v_mfma_f32_16x16x32_bf16 v[8:11], v[112:115], v[198:201], v[8:11]
	v_mfma_f32_16x16x32_bf16 v[60:63], v[100:103], v[174:177], v[60:63]
	v_mfma_f32_16x16x32_bf16 v[56:59], v[116:119], v[174:177], v[56:59]
	v_mfma_f32_16x16x32_bf16 v[44:47], v[100:103], v[186:189], v[44:47]
	v_mfma_f32_16x16x32_bf16 v[40:43], v[116:119], v[186:189], v[40:43]
	v_mfma_f32_16x16x32_bf16 v[28:31], v[100:103], v[194:197], v[28:31]
	v_mfma_f32_16x16x32_bf16 v[24:27], v[116:119], v[194:197], v[24:27]
	v_mfma_f32_16x16x32_bf16 v[12:15], v[100:103], v[202:205], v[12:15]
	v_mfma_f32_16x16x32_bf16 v[8:11], v[116:119], v[202:205], v[8:11]
	s_setprio 0
	s_barrier
; #define PG8_STAGE(bufoff, gbase, voff) do { _Pragma("unroll") for (int _i = 0; _i < 2; ++_i) \
;         __builtin_amdgcn_global_load_lds((const unsigned*)((const char*)(gbase) + (voff)[_i]), (LAS unsigned*)(lds + (bufoff) + ldsw + _i * 8192), 16, 0, 0); } while (0)
; #define PG8_LDA(dst, b, h) do { _Pragma("unroll") for (int m = 0; m < 4; ++m) _Pragma("unroll") for (int k = 0; k < 2; ++k) dst[m][k] = *(const LAS bf16x8*)(lds + PG8_SA(b, h) + aoff + m * 2048 + k * 1024); } while (0)
; #define PG8_LDB(dst, b, h) do { _Pragma("unroll") for (int n = 0; n < 2; ++n) _Pragma("unroll") for (int k = 0; k < 2; ++k) dst[n][k] = *(const LAS bf16x8*)(lds + PG8_SB(b, h) + boff + n * 2048 + k * 1024); } while (0)
; #define PG8_MMA(ai, bj, At, Bt) do { __builtin_amdgcn_s_setprio(1); _Pragma("unroll") for (int m = 0; m < 4; ++m) _Pragma("unroll") for (int n = 0; n < 2; ++n) _Pragma("unroll") for (int k = 0; k < 2; ++k) \
;         acc[ai][bj][m][n] = __builtin_amdgcn_mfma_f32_16x16x32_bf16(Bt[n][k], At[m][k], acc[ai][bj][m][n], 0, 0, 0); __builtin_amdgcn_s_setprio(0); } while (0)
; #define PG8_WAIT_V(n) asm volatile("s_waitcnt vmcnt(" #n ")" ::: "memory")
; #define PG8_WAIT_L(n) asm volatile("s_waitcnt lgkmcnt(" #n ")" ::: "memory")
; #define PG8_BAR __builtin_amdgcn_s_barrier()
; #define PG8_SCHED __builtin_amdgcn_sched_barrier(0)
; template <class Epi, class Sched, bool ATILE = false>
; __device__ __forceinline__ void gemm_phase(LAS unsigned char* lds, const Gemm g, const Sched& S, const Epi& E) {
;     ...
;             PG8_BAR; PG8_WAIT_L(0); PG8_MMA(1, 0, At, B0); PG8_BAR; PG8_SCHED;
;             PG8_STAGE(PG8_SB(0, 1), b2 + hstepB, voffB);
;             PG8_WAIT_V(6); PG8_BAR; PG8_MMA(1, 1, At, B1); PG8_BAR;
;             PG8_LDB(B0, 1, 0); PG8_SCHED; PG8_LDA(At, 1, 0); PG8_STAGE(PG8_SA(0, 1), a2 + hstepA, voffA);
;             PG8_WAIT_L(8); PG8_BAR; PG8_WAIT_L(0); PG8_MMA(0, 0, At, B0); PG8_BAR; PG8_SCHED;
;             PG8_LDB(B1, 1, 1); PG8_STAGE(PG8_SB(1, 0), b3, voffB);
;             PG8_BAR; PG8_WAIT_L(0); PG8_MMA(0, 1, At, B1); PG8_BAR;
	s_add_u32 s56, s26, 0x40000
	s_addc_u32 s57, s27, 0
	s_add_i32 s55, s40, s5
	s_mov_b32 m0, s55
	s_nop 0
	global_load_lds_dwordx4 v150, s[56:57]
	s_add_i32 m0, s55, 0x2000
	s_nop 0
	global_load_lds_dwordx4 v164, s[56:57]
	s_waitcnt vmcnt(6)
	s_barrier
	s_setprio 1
	v_mfma_f32_16x16x32_bf16 v[52:55], v[206:209], v[144:147], v[52:55]
	v_mfma_f32_16x16x32_bf16 v[48:51], v[214:217], v[144:147], v[48:51]
	v_mfma_f32_16x16x32_bf16 v[36:39], v[206:209], v[178:181], v[36:39]
	v_mfma_f32_16x16x32_bf16 v[32:35], v[214:217], v[178:181], v[32:35]
	v_mfma_f32_16x16x32_bf16 v[20:23], v[206:209], v[190:193], v[20:23]
	v_mfma_f32_16x16x32_bf16 v[16:19], v[214:217], v[190:193], v[16:19]
	v_mfma_f32_16x16x32_bf16 v[4:7], v[206:209], v[198:201], v[4:7]
	v_mfma_f32_16x16x32_bf16 v[0:3], v[214:217], v[198:201], v[0:3]
	v_mfma_f32_16x16x32_bf16 v[52:55], v[210:213], v[174:177], v[52:55]
	v_mfma_f32_16x16x32_bf16 v[48:51], v[218:221], v[174:177], v[48:51]
	v_mfma_f32_16x16x32_bf16 v[36:39], v[210:213], v[186:189], v[36:39]
	v_mfma_f32_16x16x32_bf16 v[32:35], v[218:221], v[186:189], v[32:35]
	v_mfma_f32_16x16x32_bf16 v[20:23], v[210:213], v[194:197], v[20:23]
	v_mfma_f32_16x16x32_bf16 v[16:19], v[218:221], v[194:197], v[16:19]
	v_mfma_f32_16x16x32_bf16 v[4:7], v[210:213], v[202:205], v[4:7]
	v_mfma_f32_16x16x32_bf16 v[0:3], v[218:221], v[202:205], v[0:3]
	s_setprio 0
	s_barrier
	s_add_i32 s55, 0, 0x18000
	v_add_u32_e32 v116, s55, v159
	ds_read_b128 v[96:99], v116
	ds_read_b128 v[100:103], v116 offset:1024
	ds_read_b128 v[112:115], v116 offset:2048
	ds_read_b128 v[116:119], v116 offset:3072
	s_add_u32 s28, s28, 0x40000
	s_addc_u32 s29, s29, 0
	s_mov_b32 m0, s31
	ds_read_b128 v[144:147], v183 offset:32768
	ds_read_b128 v[174:177], v183 offset:33792
	ds_read_b128 v[178:181], v183 offset:34816
	ds_read_b128 v[186:189], v183 offset:35840
	ds_read_b128 v[190:193], v183 offset:36864
	ds_read_b128 v[194:197], v183 offset:37888
	ds_read_b128 v[198:201], v183 offset:38912
	ds_read_b128 v[202:205], v183 offset:39936
	global_load_lds_dwordx4 v148, s[28:29]
	s_mov_b32 m0, s33
	s_nop 0
	global_load_lds_dwordx4 v162, s[28:29]
	s_waitcnt lgkmcnt(8)
	s_barrier
	s_waitcnt lgkmcnt(0)
	s_setprio 1
	s_waitcnt lgkmcnt(0)
	v_mfma_f32_16x16x32_bf16 v[140:143], v[96:99], v[144:147], v[140:143]
	v_mfma_f32_16x16x32_bf16 v[136:139], v[112:115], v[144:147], v[136:139]
	v_mfma_f32_16x16x32_bf16 v[124:127], v[96:99], v[178:181], v[124:127]
	v_mfma_f32_16x16x32_bf16 v[120:123], v[112:115], v[178:181], v[120:123]
	v_mfma_f32_16x16x32_bf16 v[92:95], v[96:99], v[190:193], v[92:95]
	v_mfma_f32_16x16x32_bf16 v[88:91], v[112:115], v[190:193], v[88:91]
	v_mfma_f32_16x16x32_bf16 v[76:79], v[96:99], v[198:201], v[76:79]
	v_mfma_f32_16x16x32_bf16 v[72:75], v[112:115], v[198:201], v[72:75]
	v_mfma_f32_16x16x32_bf16 v[140:143], v[100:103], v[174:177], v[140:143]
	v_mfma_f32_16x16x32_bf16 v[136:139], v[116:119], v[174:177], v[136:139]
	v_mfma_f32_16x16x32_bf16 v[124:127], v[100:103], v[186:189], v[124:127]
	v_mfma_f32_16x16x32_bf16 v[120:123], v[116:119], v[186:189], v[120:123]
	v_mfma_f32_16x16x32_bf16 v[92:95], v[100:103], v[194:197], v[92:95]
	v_mfma_f32_16x16x32_bf16 v[88:91], v[116:119], v[194:197], v[88:91]
	v_mfma_f32_16x16x32_bf16 v[76:79], v[100:103], v[202:205], v[76:79]
	v_mfma_f32_16x16x32_bf16 v[72:75], v[116:119], v[202:205], v[72:75]
	s_setprio 0
	s_barrier
	s_add_i32 s28, 0, 0x1c000
	s_add_i32 s29, s55, s5
	v_add_u32_e32 v185, s28, v159
	v_lshl_add_u64 v[222:223], v[222:223], 0, s[10:11]
	s_mov_b32 m0, s29
	ds_read_b128 v[206:209], v185
	ds_read_b128 v[210:213], v185 offset:1024
	ds_read_b128 v[214:217], v185 offset:2048
	ds_read_b128 v[218:221], v185 offset:3072
	global_load_lds_dwordx4 v[222:223], off
	v_lshl_add_u64 v[222:223], v[224:225], 0, s[10:11]
	s_add_i32 m0, s29, 0x2000
	s_nop 0
	global_load_lds_dwordx4 v[222:223], off
	s_barrier
; #define PG8_STAGE(bufoff, gbase, voff) do { _Pragma("unroll") for (int _i = 0; _i < 2; ++_i) \
;         __builtin_amdgcn_global_load_lds((const unsigned*)((const char*)(gbase) + (voff)[_i]), (LAS unsigned*)(lds + (bufoff) + ldsw + _i * 8192), 16, 0, 0); } while (0)
; #define PG8_LDA(dst, b, h) do { _Pragma("unroll") for (int m = 0; m < 4; ++m) _Pragma("unroll") for (int k = 0; k < 2; ++k) dst[m][k] = *(const LAS bf16x8*)(lds + PG8_SA(b, h) + aoff + m * 2048 + k * 1024); } while (0)
; #define PG8_MMA(ai, bj, At, Bt) do { __builtin_amdgcn_s_setprio(1); _Pragma("unroll") for (int m = 0; m < 4; ++m) _Pragma("unroll") for (int n = 0; n < 2; ++n) _Pragma("unroll") for (int k = 0; k < 2; ++k) \
;         acc[ai][bj][m][n] = __builtin_amdgcn_mfma_f32_16x16x32_bf16(Bt[n][k], At[m][k], acc[ai][bj][m][n], 0, 0, 0); __builtin_amdgcn_s_setprio(0); } while (0)
; #define PG8_WAIT_V(n) asm volatile("s_waitcnt vmcnt(" #n ")" ::: "memory")
; #define PG8_WAIT_L(n) asm volatile("s_waitcnt lgkmcnt(" #n ")" ::: "memory")
; #define PG8_BAR __builtin_amdgcn_s_barrier()
; #define PG8_SCHED __builtin_amdgcn_sched_barrier(0)
; template <class Epi, class Sched, bool ATILE = false>
; __device__ __forceinline__ void gemm_phase(LAS unsigned char* lds, const Gemm g, const Sched& S, const Epi& E) {
;     ...
;             PG8_BAR; PG8_WAIT_L(0); PG8_MMA(0, 1, At, B1); PG8_BAR;
;             PG8_LDA(At, 1, 1); PG8_STAGE(PG8_SA(1, 0), a3, voffA);
;             PG8_BAR; PG8_WAIT_L(0); PG8_MMA(1, 0, At, B0); PG8_BAR; PG8_SCHED;
;             PG8_STAGE(PG8_SB(1, 1), b3 + hstepB, voffB);
;             PG8_WAIT_V(6); PG8_BAR; PG8_MMA(1, 1, At, B1); PG8_BAR;
;         }
	s_waitcnt lgkmcnt(0)
	s_setprio 1
	s_waitcnt lgkmcnt(0)
	v_mfma_f32_16x16x32_bf16 v[132:135], v[206:209], v[144:147], v[132:135]
	v_mfma_f32_16x16x32_bf16 v[128:131], v[214:217], v[144:147], v[128:131]
	v_mfma_f32_16x16x32_bf16 v[108:111], v[206:209], v[178:181], v[108:111]
	v_mfma_f32_16x16x32_bf16 v[104:107], v[214:217], v[178:181], v[104:107]
	v_mfma_f32_16x16x32_bf16 v[84:87], v[206:209], v[190:193], v[84:87]
	v_mfma_f32_16x16x32_bf16 v[80:83], v[214:217], v[190:193], v[80:83]
	v_mfma_f32_16x16x32_bf16 v[68:71], v[206:209], v[198:201], v[68:71]
	v_mfma_f32_16x16x32_bf16 v[64:67], v[214:217], v[198:201], v[64:67]
	v_mfma_f32_16x16x32_bf16 v[132:135], v[210:213], v[174:177], v[132:135]
	v_mfma_f32_16x16x32_bf16 v[128:131], v[218:221], v[174:177], v[128:131]
	v_mfma_f32_16x16x32_bf16 v[108:111], v[210:213], v[186:189], v[108:111]
	v_mfma_f32_16x16x32_bf16 v[104:107], v[218:221], v[186:189], v[104:107]
	v_mfma_f32_16x16x32_bf16 v[84:87], v[210:213], v[194:197], v[84:87]
	v_mfma_f32_16x16x32_bf16 v[80:83], v[218:221], v[194:197], v[80:83]
	v_mfma_f32_16x16x32_bf16 v[68:71], v[210:213], v[202:205], v[68:71]
	v_mfma_f32_16x16x32_bf16 v[64:67], v[218:221], v[202:205], v[64:67]
	s_setprio 0
	s_barrier
	s_mov_b32 m0, s35
	v_lshl_add_u64 v[222:223], v[226:227], 0, s[10:11]
	ds_read_b128 v[144:147], v183 offset:49152
	ds_read_b128 v[174:177], v183 offset:50176
	ds_read_b128 v[178:181], v183 offset:51200
	ds_read_b128 v[186:189], v183 offset:52224
	ds_read_b128 v[190:193], v183 offset:53248
	ds_read_b128 v[194:197], v183 offset:54272
	ds_read_b128 v[198:201], v183 offset:55296
	ds_read_b128 v[202:205], v183 offset:56320
	global_load_lds_dwordx4 v[222:223], off
	v_lshl_add_u64 v[222:223], v[228:229], 0, s[10:11]
	s_mov_b32 m0, s36
	s_nop 0
	global_load_lds_dwordx4 v[222:223], off
	s_barrier
	s_waitcnt lgkmcnt(0)
	s_setprio 1
	s_waitcnt lgkmcnt(0)
	v_mfma_f32_16x16x32_bf16 v[60:63], v[96:99], v[144:147], v[60:63]
	v_mfma_f32_16x16x32_bf16 v[56:59], v[112:115], v[144:147], v[56:59]
	v_mfma_f32_16x16x32_bf16 v[44:47], v[96:99], v[178:181], v[44:47]
	v_mfma_f32_16x16x32_bf16 v[40:43], v[112:115], v[178:181], v[40:43]
	v_mfma_f32_16x16x32_bf16 v[28:31], v[96:99], v[190:193], v[28:31]
	v_mfma_f32_16x16x32_bf16 v[24:27], v[112:115], v[190:193], v[24:27]
	v_mfma_f32_16x16x32_bf16 v[12:15], v[96:99], v[198:201], v[12:15]
	v_mfma_f32_16x16x32_bf16 v[8:11], v[112:115], v[198:201], v[8:11]
	v_mfma_f32_16x16x32_bf16 v[60:63], v[100:103], v[174:177], v[60:63]
	v_mfma_f32_16x16x32_bf16 v[56:59], v[116:119], v[174:177], v[56:59]
	v_mfma_f32_16x16x32_bf16 v[44:47], v[100:103], v[186:189], v[44:47]
	v_mfma_f32_16x16x32_bf16 v[40:43], v[116:119], v[186:189], v[40:43]
	v_mfma_f32_16x16x32_bf16 v[28:31], v[100:103], v[194:197], v[28:31]
	v_mfma_f32_16x16x32_bf16 v[24:27], v[116:119], v[194:197], v[24:27]
	v_mfma_f32_16x16x32_bf16 v[12:15], v[100:103], v[202:205], v[12:15]
	v_mfma_f32_16x16x32_bf16 v[8:11], v[116:119], v[202:205], v[8:11]
	s_setprio 0
	s_barrier
	s_add_u32 s26, s26, 0x40080
	s_addc_u32 s27, s27, 0
	s_add_i32 s28, s28, s5
	s_mov_b32 m0, s28
	s_nop 0
	global_load_lds_dwordx4 v150, s[26:27]
	s_add_i32 m0, s28, 0x2000
	s_nop 0
	global_load_lds_dwordx4 v164, s[26:27]
	s_waitcnt vmcnt(6)
	s_barrier
	s_setprio 1
	v_mfma_f32_16x16x32_bf16 v[52:55], v[206:209], v[144:147], v[52:55]
	v_mfma_f32_16x16x32_bf16 v[48:51], v[214:217], v[144:147], v[48:51]
	v_mfma_f32_16x16x32_bf16 v[36:39], v[206:209], v[178:181], v[36:39]
	v_mfma_f32_16x16x32_bf16 v[32:35], v[214:217], v[178:181], v[32:35]
	v_mfma_f32_16x16x32_bf16 v[20:23], v[206:209], v[190:193], v[20:23]
	v_mfma_f32_16x16x32_bf16 v[16:19], v[214:217], v[190:193], v[16:19]
	v_mfma_f32_16x16x32_bf16 v[4:7], v[206:209], v[198:201], v[4:7]
	v_mfma_f32_16x16x32_bf16 v[0:3], v[214:217], v[198:201], v[0:3]
	v_mfma_f32_16x16x32_bf16 v[52:55], v[210:213], v[174:177], v[52:55]
	v_mfma_f32_16x16x32_bf16 v[48:51], v[218:221], v[174:177], v[48:51]
	v_mfma_f32_16x16x32_bf16 v[36:39], v[210:213], v[186:189], v[36:39]
	v_mfma_f32_16x16x32_bf16 v[32:35], v[218:221], v[186:189], v[32:35]
	v_mfma_f32_16x16x32_bf16 v[20:23], v[210:213], v[194:197], v[20:23]
	v_mfma_f32_16x16x32_bf16 v[16:19], v[218:221], v[194:197], v[16:19]
	v_mfma_f32_16x16x32_bf16 v[4:7], v[210:213], v[202:205], v[4:7]
	v_mfma_f32_16x16x32_bf16 v[0:3], v[218:221], v[202:205], v[0:3]
	s_setprio 0
	s_barrier
	s_add_u32 s24, s24, 0x100
	s_addc_u32 s25, s25, 0
	s_add_u32 s52, s52, 0x100
	s_addc_u32 s53, s53, 0
	s_cmp_ge_i32 s54, s13
	s_mov_b32 s26, s54
	s_cbranch_scc0 .LBB0_1517
	s_branch .LBB0_1508

; #define PG8_STAGE(bufoff, gbase, voff) do { _Pragma("unroll") for (int _i = 0; _i < 2; ++_i) \
;         __builtin_amdgcn_global_load_lds((const unsigned*)((const char*)(gbase) + (voff)[_i]), (LAS unsigned*)(lds + (bufoff) + ldsw + _i * 8192), 16, 0, 0); } while (0)
; #define PG8_LDA(dst, b, h) do { _Pragma("unroll") for (int m = 0; m < 4; ++m) _Pragma("unroll") for (int k = 0; k < 2; ++k) dst[m][k] = *(const LAS bf16x8*)(lds + PG8_SA(b, h) + aoff + m * 2048 + k * 1024); } while (0)
; #define PG8_LDB(dst, b, h) do { _Pragma("unroll") for (int n = 0; n < 2; ++n) _Pragma("unroll") for (int k = 0; k < 2; ++k) dst[n][k] = *(const LAS bf16x8*)(lds + PG8_SB(b, h) + boff + n * 2048 + k * 1024); } while (0)
; #define PG8_MMA(ai, bj, At, Bt) do { __builtin_amdgcn_s_setprio(1); _Pragma("unroll") for (int m = 0; m < 4; ++m) _Pragma("unroll") for (int n = 0; n < 2; ++n) _Pragma("unroll") for (int k = 0; k < 2; ++k) \
;         acc[ai][bj][m][n] = __builtin_amdgcn_mfma_f32_16x16x32_bf16(Bt[n][k], At[m][k], acc[ai][bj][m][n], 0, 0, 0); __builtin_amdgcn_s_setprio(0); } while (0)
; #define PG8_WAIT_L(n) asm volatile("s_waitcnt lgkmcnt(" #n ")" ::: "memory")
; #define PG8_BAR __builtin_amdgcn_s_barrier()
; #define PG8_SCHED __builtin_amdgcn_sched_barrier(0)
; template <class Epi, class Sched, bool ATILE = false>
; __device__ __forceinline__ void gemm_phase(LAS unsigned char* lds, const Gemm g, const Sched& S, const Epi& E) {
;     ...
;         for (int t = 0; t < nt; t += 2) {
;             const bool last = (t == nt - 2);
;             const char* a1 = cA + (size_t)(t + 1) * kstepA;
;             const char* a2 = last ? nA : cA + (size_t)(t + 2) * kstepA; const char* b2 = last ? nB : cB + (size_t)(t + 2) * kstep;
;             const char* a3 = a2 + kstepA; const char* b3 = b2 + kstep;
;             PG8_LDB(B0, 0, 0); PG8_SCHED; PG8_LDA(At, 0, 0); PG8_STAGE(PG8_SA(1, 1), a1 + hstepA, voffA);
;             PG8_WAIT_L(8); PG8_BAR; PG8_WAIT_L(0); PG8_MMA(0, 0, At, B0); PG8_BAR; PG8_SCHED;
;             PG8_LDB(B1, 0, 1); PG8_STAGE(PG8_SB(0, 0), b2, voffB);
;             PG8_BAR; PG8_WAIT_L(0); PG8_MMA(0, 1, At, B1); PG8_BAR;
;             PG8_LDA(At, 0, 1); PG8_STAGE(PG8_SA(0, 0), a2, voffA);
;             PG8_BAR; PG8_WAIT_L(0); PG8_MMA(1, 0, At, B0); PG8_BAR; PG8_SCHED;
.LBB0_1658:
	s_waitcnt lgkmcnt(0)
	ds_read_b128 v[128:131], v169
	ds_read_b128 v[132:135], v169 offset:1024
	ds_read_b128 v[136:139], v169 offset:2048
	ds_read_b128 v[140:143], v169 offset:3072
	s_add_i32 s29, s27, 2
	s_add_u32 s34, s30, 0x4000
	s_addc_u32 s35, s31, 0
	s_cmp_eq_u32 s11, s27
	s_cselect_b32 s38, s22, s34
	s_cselect_b32 s39, s23, s35
	s_cselect_b32 s34, s24, s13
	s_cselect_b32 s35, s25, s17
	s_add_u32 s36, s38, 0x8000
	s_addc_u32 s37, s39, 0
	s_add_i32 m0, s5, 0xc000
	ds_read_b128 v[144:147], v210
	ds_read_b128 v[148:151], v210 offset:1024
	ds_read_b128 v[192:195], v210 offset:2048
	ds_read_b128 v[196:199], v210 offset:3072
	ds_read_b128 v[200:203], v210 offset:4096
	ds_read_b128 v[204:207], v210 offset:5120
	ds_read_b128 v[214:217], v210 offset:6144
	ds_read_b128 v[218:221], v210 offset:7168
	global_load_lds_dwordx4 v186, s[30:31]
	s_add_i32 m0, s5, 0xe000
	s_nop 0
	global_load_lds_dwordx4 v188, s[30:31]
	s_waitcnt lgkmcnt(8)
	s_barrier
	s_waitcnt lgkmcnt(0)
	s_setprio 1
	s_waitcnt lgkmcnt(0)
	v_mfma_f32_16x16x32_bf16 v[120:123], v[128:131], v[144:147], v[120:123]
	v_mfma_f32_16x16x32_bf16 v[116:119], v[136:139], v[144:147], v[116:119]
	v_mfma_f32_16x16x32_bf16 v[108:111], v[128:131], v[192:195], v[108:111]
	v_mfma_f32_16x16x32_bf16 v[100:103], v[136:139], v[192:195], v[100:103]
	v_mfma_f32_16x16x32_bf16 v[92:95], v[128:131], v[200:203], v[92:95]
	v_mfma_f32_16x16x32_bf16 v[84:87], v[136:139], v[200:203], v[84:87]
	v_mfma_f32_16x16x32_bf16 v[76:79], v[128:131], v[214:217], v[76:79]
	v_mfma_f32_16x16x32_bf16 v[68:71], v[136:139], v[214:217], v[68:71]
	v_mfma_f32_16x16x32_bf16 v[120:123], v[132:135], v[148:151], v[120:123]
	v_mfma_f32_16x16x32_bf16 v[116:119], v[140:143], v[148:151], v[116:119]
	v_mfma_f32_16x16x32_bf16 v[108:111], v[132:135], v[196:199], v[108:111]
	v_mfma_f32_16x16x32_bf16 v[100:103], v[140:143], v[196:199], v[100:103]
	v_mfma_f32_16x16x32_bf16 v[92:95], v[132:135], v[204:207], v[92:95]
	v_mfma_f32_16x16x32_bf16 v[84:87], v[140:143], v[204:207], v[84:87]
	v_mfma_f32_16x16x32_bf16 v[76:79], v[132:135], v[218:221], v[76:79]
	v_mfma_f32_16x16x32_bf16 v[68:71], v[140:143], v[218:221], v[68:71]
	s_setprio 0
	s_barrier
	s_add_i32 s27, s52, s4
	v_lshl_add_u64 v[208:209], s[34:35], 0, v[162:163]
	s_mov_b32 m0, s27
	ds_read_b128 v[222:225], v211
	ds_read_b128 v[226:229], v211 offset:1024
	ds_read_b128 v[230:233], v211 offset:2048
	ds_read_b128 v[234:237], v211 offset:3072
	global_load_lds_dwordx4 v[208:209], off
	v_lshl_add_u64 v[238:239], s[34:35], 0, v[166:167]
	s_add_i32 m0, s27, 0x2000
	s_nop 0
	global_load_lds_dwordx4 v[238:239], off
	s_barrier
	s_waitcnt lgkmcnt(0)
	s_setprio 1
	s_waitcnt lgkmcnt(0)
	v_mfma_f32_16x16x32_bf16 v[124:127], v[222:225], v[144:147], v[124:127]
	v_mfma_f32_16x16x32_bf16 v[112:115], v[230:233], v[144:147], v[112:115]
	v_mfma_f32_16x16x32_bf16 v[104:107], v[222:225], v[192:195], v[104:107]
	v_mfma_f32_16x16x32_bf16 v[96:99], v[230:233], v[192:195], v[96:99]
	v_mfma_f32_16x16x32_bf16 v[88:91], v[222:225], v[200:203], v[88:91]
	v_mfma_f32_16x16x32_bf16 v[80:83], v[230:233], v[200:203], v[80:83]
	v_mfma_f32_16x16x32_bf16 v[72:75], v[222:225], v[214:217], v[72:75]
	v_mfma_f32_16x16x32_bf16 v[64:67], v[230:233], v[214:217], v[64:67]
	v_mfma_f32_16x16x32_bf16 v[124:127], v[226:229], v[148:151], v[124:127]
	v_mfma_f32_16x16x32_bf16 v[112:115], v[234:237], v[148:151], v[112:115]
	v_mfma_f32_16x16x32_bf16 v[104:107], v[226:229], v[196:199], v[104:107]
	v_mfma_f32_16x16x32_bf16 v[96:99], v[234:237], v[196:199], v[96:99]
	v_mfma_f32_16x16x32_bf16 v[88:91], v[226:229], v[204:207], v[88:91]
	v_mfma_f32_16x16x32_bf16 v[80:83], v[234:237], v[204:207], v[80:83]
	v_mfma_f32_16x16x32_bf16 v[72:75], v[226:229], v[218:221], v[72:75]
	v_mfma_f32_16x16x32_bf16 v[64:67], v[234:237], v[218:221], v[64:67]
	s_setprio 0
	s_barrier
	s_mov_b32 m0, s5
	ds_read_b128 v[144:147], v210 offset:16384
	ds_read_b128 v[148:151], v210 offset:17408
	ds_read_b128 v[192:195], v210 offset:18432
	ds_read_b128 v[196:199], v210 offset:19456
	ds_read_b128 v[200:203], v210 offset:20480
	ds_read_b128 v[204:207], v210 offset:21504
	ds_read_b128 v[214:217], v210 offset:22528
	ds_read_b128 v[218:221], v210 offset:23552
	global_load_lds_dwordx4 v160, s[38:39]
	s_mov_b32 m0, s33
	s_nop 0
	global_load_lds_dwordx4 v164, s[38:39]
	s_barrier
	s_waitcnt lgkmcnt(0)
	s_setprio 1
	s_waitcnt lgkmcnt(0)
	v_mfma_f32_16x16x32_bf16 v[60:63], v[128:131], v[144:147], v[60:63]
	v_mfma_f32_16x16x32_bf16 v[56:59], v[136:139], v[144:147], v[56:59]
	v_mfma_f32_16x16x32_bf16 v[44:47], v[128:131], v[192:195], v[44:47]
	v_mfma_f32_16x16x32_bf16 v[40:43], v[136:139], v[192:195], v[40:43]
	v_mfma_f32_16x16x32_bf16 v[28:31], v[128:131], v[200:203], v[28:31]
	v_mfma_f32_16x16x32_bf16 v[24:27], v[136:139], v[200:203], v[24:27]
	v_mfma_f32_16x16x32_bf16 v[12:15], v[128:131], v[214:217], v[12:15]
	v_mfma_f32_16x16x32_bf16 v[8:11], v[136:139], v[214:217], v[8:11]
	v_mfma_f32_16x16x32_bf16 v[60:63], v[132:135], v[148:151], v[60:63]
	v_mfma_f32_16x16x32_bf16 v[56:59], v[140:143], v[148:151], v[56:59]
	v_mfma_f32_16x16x32_bf16 v[44:47], v[132:135], v[196:199], v[44:47]
	v_mfma_f32_16x16x32_bf16 v[40:43], v[140:143], v[196:199], v[40:43]
	v_mfma_f32_16x16x32_bf16 v[28:31], v[132:135], v[204:207], v[28:31]
	v_mfma_f32_16x16x32_bf16 v[24:27], v[140:143], v[204:207], v[24:27]
	v_mfma_f32_16x16x32_bf16 v[12:15], v[132:135], v[218:221], v[12:15]
	v_mfma_f32_16x16x32_bf16 v[8:11], v[140:143], v[218:221], v[8:11]
	s_setprio 0
	s_barrier
	s_add_u32 s56, s34, 0x80000
	s_addc_u32 s57, s35, 0
	s_add_i32 s27, s53, s4
	s_mov_b32 m0, s27
	s_nop 0
	global_load_lds_dwordx4 v162, s[56:57]
	s_add_i32 m0, s27, 0x2000
	s_nop 0
	global_load_lds_dwordx4 v166, s[56:57]
	s_waitcnt vmcnt(6)
	s_barrier
; #define PG8_STAGE(bufoff, gbase, voff) do { _Pragma("unroll") for (int _i = 0; _i < 2; ++_i) \
;         __builtin_amdgcn_global_load_lds((const unsigned*)((const char*)(gbase) + (voff)[_i]), (LAS unsigned*)(lds + (bufoff) + ldsw + _i * 8192), 16, 0, 0); } while (0)
; #define PG8_LDA(dst, b, h) do { _Pragma("unroll") for (int m = 0; m < 4; ++m) _Pragma("unroll") for (int k = 0; k < 2; ++k) dst[m][k] = *(const LAS bf16x8*)(lds + PG8_SA(b, h) + aoff + m * 2048 + k * 1024); } while (0)
; #define PG8_LDB(dst, b, h) do { _Pragma("unroll") for (int n = 0; n < 2; ++n) _Pragma("unroll") for (int k = 0; k < 2; ++k) dst[n][k] = *(const LAS bf16x8*)(lds + PG8_SB(b, h) + boff + n * 2048 + k * 1024); } while (0)
; #define PG8_MMA(ai, bj, At, Bt) do { __builtin_amdgcn_s_setprio(1); _Pragma("unroll") for (int m = 0; m < 4; ++m) _Pragma("unroll") for (int n = 0; n < 2; ++n) _Pragma("unroll") for (int k = 0; k < 2; ++k) \
;         acc[ai][bj][m][n] = __builtin_amdgcn_mfma_f32_16x16x32_bf16(Bt[n][k], At[m][k], acc[ai][bj][m][n], 0, 0, 0); __builtin_amdgcn_s_setprio(0); } while (0)
; #define PG8_WAIT_V(n) asm volatile("s_waitcnt vmcnt(" #n ")" ::: "memory")
; #define PG8_WAIT_L(n) asm volatile("s_waitcnt lgkmcnt(" #n ")" ::: "memory")
; #define PG8_BAR __builtin_amdgcn_s_barrier()
; #define PG8_SCHED __builtin_amdgcn_sched_barrier(0)
; template <class Epi, class Sched, bool ATILE = false>
; __device__ __forceinline__ void gemm_phase(LAS unsigned char* lds, const Gemm g, const Sched& S, const Epi& E) {
;     ...
;             PG8_WAIT_V(6); PG8_BAR; PG8_MMA(1, 1, At, B1); PG8_BAR;
;             PG8_LDB(B0, 1, 0); PG8_SCHED; PG8_LDA(At, 1, 0); PG8_STAGE(PG8_SA(0, 1), a2 + hstepA, voffA);
;             PG8_WAIT_L(8); PG8_BAR; PG8_WAIT_L(0); PG8_MMA(0, 0, At, B0); PG8_BAR; PG8_SCHED;
;             PG8_LDB(B1, 1, 1); PG8_STAGE(PG8_SB(1, 0), b3, voffB);
;             PG8_BAR; PG8_WAIT_L(0); PG8_MMA(0, 1, At, B1); PG8_BAR;
;             PG8_LDA(At, 1, 1); PG8_STAGE(PG8_SA(1, 0), a3, voffA);
	s_setprio 1
	v_mfma_f32_16x16x32_bf16 v[52:55], v[222:225], v[144:147], v[52:55]
	v_mfma_f32_16x16x32_bf16 v[48:51], v[230:233], v[144:147], v[48:51]
	v_mfma_f32_16x16x32_bf16 v[36:39], v[222:225], v[192:195], v[36:39]
	v_mfma_f32_16x16x32_bf16 v[32:35], v[230:233], v[192:195], v[32:35]
	v_mfma_f32_16x16x32_bf16 v[20:23], v[222:225], v[200:203], v[20:23]
	v_mfma_f32_16x16x32_bf16 v[16:19], v[230:233], v[200:203], v[16:19]
	v_mfma_f32_16x16x32_bf16 v[4:7], v[222:225], v[214:217], v[4:7]
	v_mfma_f32_16x16x32_bf16 v[0:3], v[230:233], v[214:217], v[0:3]
	v_mfma_f32_16x16x32_bf16 v[52:55], v[226:229], v[148:151], v[52:55]
	v_mfma_f32_16x16x32_bf16 v[48:51], v[234:237], v[148:151], v[48:51]
	v_mfma_f32_16x16x32_bf16 v[36:39], v[226:229], v[196:199], v[36:39]
	v_mfma_f32_16x16x32_bf16 v[32:35], v[234:237], v[196:199], v[32:35]
	v_mfma_f32_16x16x32_bf16 v[20:23], v[226:229], v[204:207], v[20:23]
	v_mfma_f32_16x16x32_bf16 v[16:19], v[234:237], v[204:207], v[16:19]
	v_mfma_f32_16x16x32_bf16 v[4:7], v[226:229], v[218:221], v[4:7]
	v_mfma_f32_16x16x32_bf16 v[0:3], v[234:237], v[218:221], v[0:3]
	s_setprio 0
	s_barrier
	s_add_i32 s27, 0, 0x18000
	v_add_u32_e32 v140, s27, v157
	ds_read_b128 v[128:131], v140
	ds_read_b128 v[132:135], v140 offset:1024
	ds_read_b128 v[136:139], v140 offset:2048
	ds_read_b128 v[140:143], v140 offset:3072
	s_add_u32 s38, s38, 0x4000
	s_addc_u32 s39, s39, 0
	s_mov_b32 m0, s40
	ds_read_b128 v[144:147], v210 offset:32768
	ds_read_b128 v[148:151], v210 offset:33792
	ds_read_b128 v[192:195], v210 offset:34816
	ds_read_b128 v[196:199], v210 offset:35840
	ds_read_b128 v[200:203], v210 offset:36864
	ds_read_b128 v[204:207], v210 offset:37888
	ds_read_b128 v[214:217], v210 offset:38912
	ds_read_b128 v[218:221], v210 offset:39936
	global_load_lds_dwordx4 v160, s[38:39]
	s_mov_b32 m0, s41
	s_nop 0
	global_load_lds_dwordx4 v164, s[38:39]
	s_waitcnt lgkmcnt(8)
	s_barrier
	s_waitcnt lgkmcnt(0)
	s_setprio 1
	s_waitcnt lgkmcnt(0)
	v_mfma_f32_16x16x32_bf16 v[120:123], v[128:131], v[144:147], v[120:123]
	v_mfma_f32_16x16x32_bf16 v[116:119], v[136:139], v[144:147], v[116:119]
	v_mfma_f32_16x16x32_bf16 v[108:111], v[128:131], v[192:195], v[108:111]
	v_mfma_f32_16x16x32_bf16 v[100:103], v[136:139], v[192:195], v[100:103]
	v_mfma_f32_16x16x32_bf16 v[92:95], v[128:131], v[200:203], v[92:95]
	v_mfma_f32_16x16x32_bf16 v[84:87], v[136:139], v[200:203], v[84:87]
	v_mfma_f32_16x16x32_bf16 v[76:79], v[128:131], v[214:217], v[76:79]
	v_mfma_f32_16x16x32_bf16 v[68:71], v[136:139], v[214:217], v[68:71]
	v_mfma_f32_16x16x32_bf16 v[120:123], v[132:135], v[148:151], v[120:123]
	v_mfma_f32_16x16x32_bf16 v[116:119], v[140:143], v[148:151], v[116:119]
	v_mfma_f32_16x16x32_bf16 v[108:111], v[132:135], v[196:199], v[108:111]
	v_mfma_f32_16x16x32_bf16 v[100:103], v[140:143], v[196:199], v[100:103]
	v_mfma_f32_16x16x32_bf16 v[92:95], v[132:135], v[204:207], v[92:95]
	v_mfma_f32_16x16x32_bf16 v[84:87], v[140:143], v[204:207], v[84:87]
	v_mfma_f32_16x16x32_bf16 v[76:79], v[132:135], v[218:221], v[76:79]
	v_mfma_f32_16x16x32_bf16 v[68:71], v[140:143], v[218:221], v[68:71]
	s_setprio 0
	s_barrier
	s_add_i32 s38, 0, 0x1c000
	s_add_i32 s27, s27, s4
	v_add_u32_e32 v213, s38, v157
	v_lshl_add_u64 v[208:209], v[208:209], 0, s[8:9]
	s_mov_b32 m0, s27
	ds_read_b128 v[222:225], v213
	ds_read_b128 v[226:229], v213 offset:1024
	ds_read_b128 v[230:233], v213 offset:2048
	ds_read_b128 v[234:237], v213 offset:3072
	global_load_lds_dwordx4 v[208:209], off
	v_lshl_add_u64 v[208:209], v[238:239], 0, s[8:9]
	s_add_i32 m0, s27, 0x2000
	s_nop 0
	global_load_lds_dwordx4 v[208:209], off
	s_barrier
; #define PG8_STAGE(bufoff, gbase, voff) do { _Pragma("unroll") for (int _i = 0; _i < 2; ++_i) \
;         __builtin_amdgcn_global_load_lds((const unsigned*)((const char*)(gbase) + (voff)[_i]), (LAS unsigned*)(lds + (bufoff) + ldsw + _i * 8192), 16, 0, 0); } while (0)
; #define PG8_LDA(dst, b, h) do { _Pragma("unroll") for (int m = 0; m < 4; ++m) _Pragma("unroll") for (int k = 0; k < 2; ++k) dst[m][k] = *(const LAS bf16x8*)(lds + PG8_SA(b, h) + aoff + m * 2048 + k * 1024); } while (0)
; #define PG8_MMA(ai, bj, At, Bt) do { __builtin_amdgcn_s_setprio(1); _Pragma("unroll") for (int m = 0; m < 4; ++m) _Pragma("unroll") for (int n = 0; n < 2; ++n) _Pragma("unroll") for (int k = 0; k < 2; ++k) \
;         acc[ai][bj][m][n] = __builtin_amdgcn_mfma_f32_16x16x32_bf16(Bt[n][k], At[m][k], acc[ai][bj][m][n], 0, 0, 0); __builtin_amdgcn_s_setprio(0); } while (0)
; #define PG8_WAIT_V(n) asm volatile("s_waitcnt vmcnt(" #n ")" ::: "memory")
; #define PG8_WAIT_L(n) asm volatile("s_waitcnt lgkmcnt(" #n ")" ::: "memory")
; #define PG8_BAR __builtin_amdgcn_s_barrier()
; #define PG8_SCHED __builtin_amdgcn_sched_barrier(0)
; template <class Epi, class Sched, bool ATILE = false>
; __device__ __forceinline__ void gemm_phase(LAS unsigned char* lds, const Gemm g, const Sched& S, const Epi& E) {
;     ...
;             PG8_BAR; PG8_WAIT_L(0); PG8_MMA(0, 1, At, B1); PG8_BAR;
;             PG8_LDA(At, 1, 1); PG8_STAGE(PG8_SA(1, 0), a3, voffA);
;             PG8_BAR; PG8_WAIT_L(0); PG8_MMA(1, 0, At, B0); PG8_BAR; PG8_SCHED;
;             PG8_STAGE(PG8_SB(1, 1), b3 + hstepB, voffB);
;             PG8_WAIT_V(6); PG8_BAR; PG8_MMA(1, 1, At, B1); PG8_BAR;
;         }
	s_waitcnt lgkmcnt(0)
	s_setprio 1
	s_waitcnt lgkmcnt(0)
	v_mfma_f32_16x16x32_bf16 v[124:127], v[222:225], v[144:147], v[124:127]
	v_mfma_f32_16x16x32_bf16 v[112:115], v[230:233], v[144:147], v[112:115]
	v_mfma_f32_16x16x32_bf16 v[104:107], v[222:225], v[192:195], v[104:107]
	v_mfma_f32_16x16x32_bf16 v[96:99], v[230:233], v[192:195], v[96:99]
	v_mfma_f32_16x16x32_bf16 v[88:91], v[222:225], v[200:203], v[88:91]
	v_mfma_f32_16x16x32_bf16 v[80:83], v[230:233], v[200:203], v[80:83]
	v_mfma_f32_16x16x32_bf16 v[72:75], v[222:225], v[214:217], v[72:75]
	v_mfma_f32_16x16x32_bf16 v[64:67], v[230:233], v[214:217], v[64:67]
	v_mfma_f32_16x16x32_bf16 v[124:127], v[226:229], v[148:151], v[124:127]
	v_mfma_f32_16x16x32_bf16 v[112:115], v[234:237], v[148:151], v[112:115]
	v_mfma_f32_16x16x32_bf16 v[104:107], v[226:229], v[196:199], v[104:107]
	v_mfma_f32_16x16x32_bf16 v[96:99], v[234:237], v[196:199], v[96:99]
	v_mfma_f32_16x16x32_bf16 v[88:91], v[226:229], v[204:207], v[88:91]
	v_mfma_f32_16x16x32_bf16 v[80:83], v[234:237], v[204:207], v[80:83]
	v_mfma_f32_16x16x32_bf16 v[72:75], v[226:229], v[218:221], v[72:75]
	v_mfma_f32_16x16x32_bf16 v[64:67], v[234:237], v[218:221], v[64:67]
	s_setprio 0
	s_barrier
	s_mov_b32 m0, s43
	ds_read_b128 v[144:147], v210 offset:49152
	ds_read_b128 v[148:151], v210 offset:50176
	ds_read_b128 v[192:195], v210 offset:51200
	ds_read_b128 v[196:199], v210 offset:52224
	ds_read_b128 v[200:203], v210 offset:53248
	ds_read_b128 v[204:207], v210 offset:54272
	ds_read_b128 v[214:217], v210 offset:55296
	ds_read_b128 v[218:221], v210 offset:56320
	global_load_lds_dwordx4 v160, s[36:37]
	s_mov_b32 m0, s44
	s_nop 0
	global_load_lds_dwordx4 v164, s[36:37]
	s_barrier
	s_waitcnt lgkmcnt(0)
	s_setprio 1
	s_waitcnt lgkmcnt(0)
	v_mfma_f32_16x16x32_bf16 v[60:63], v[128:131], v[144:147], v[60:63]
	v_mfma_f32_16x16x32_bf16 v[56:59], v[136:139], v[144:147], v[56:59]
	v_mfma_f32_16x16x32_bf16 v[44:47], v[128:131], v[192:195], v[44:47]
	v_mfma_f32_16x16x32_bf16 v[40:43], v[136:139], v[192:195], v[40:43]
	v_mfma_f32_16x16x32_bf16 v[28:31], v[128:131], v[200:203], v[28:31]
	v_mfma_f32_16x16x32_bf16 v[24:27], v[136:139], v[200:203], v[24:27]
	v_mfma_f32_16x16x32_bf16 v[12:15], v[128:131], v[214:217], v[12:15]
	v_mfma_f32_16x16x32_bf16 v[8:11], v[136:139], v[214:217], v[8:11]
	v_mfma_f32_16x16x32_bf16 v[60:63], v[132:135], v[148:151], v[60:63]
	v_mfma_f32_16x16x32_bf16 v[56:59], v[140:143], v[148:151], v[56:59]
	v_mfma_f32_16x16x32_bf16 v[44:47], v[132:135], v[196:199], v[44:47]
	v_mfma_f32_16x16x32_bf16 v[40:43], v[140:143], v[196:199], v[40:43]
	v_mfma_f32_16x16x32_bf16 v[28:31], v[132:135], v[204:207], v[28:31]
	v_mfma_f32_16x16x32_bf16 v[24:27], v[140:143], v[204:207], v[24:27]
	v_mfma_f32_16x16x32_bf16 v[12:15], v[132:135], v[218:221], v[12:15]
	v_mfma_f32_16x16x32_bf16 v[8:11], v[140:143], v[218:221], v[8:11]
	s_setprio 0
	s_barrier
	s_add_u32 s34, s34, 0x80080
	s_addc_u32 s35, s35, 0
	s_add_i32 s27, s38, s4
	s_mov_b32 m0, s27
	s_nop 0
	global_load_lds_dwordx4 v162, s[34:35]
	s_add_i32 m0, s27, 0x2000
	s_nop 0
	global_load_lds_dwordx4 v166, s[34:35]
	s_waitcnt vmcnt(6)
	s_barrier
	s_setprio 1
	v_mfma_f32_16x16x32_bf16 v[52:55], v[222:225], v[144:147], v[52:55]
	v_mfma_f32_16x16x32_bf16 v[48:51], v[230:233], v[144:147], v[48:51]
	v_mfma_f32_16x16x32_bf16 v[36:39], v[222:225], v[192:195], v[36:39]
	v_mfma_f32_16x16x32_bf16 v[32:35], v[230:233], v[192:195], v[32:35]
	v_mfma_f32_16x16x32_bf16 v[20:23], v[222:225], v[200:203], v[20:23]
	v_mfma_f32_16x16x32_bf16 v[16:19], v[230:233], v[200:203], v[16:19]
	v_mfma_f32_16x16x32_bf16 v[4:7], v[222:225], v[214:217], v[4:7]
	v_mfma_f32_16x16x32_bf16 v[0:3], v[230:233], v[214:217], v[0:3]
	v_mfma_f32_16x16x32_bf16 v[52:55], v[226:229], v[148:151], v[52:55]
	v_mfma_f32_16x16x32_bf16 v[48:51], v[234:237], v[148:151], v[48:51]
	v_mfma_f32_16x16x32_bf16 v[36:39], v[226:229], v[196:199], v[36:39]
	v_mfma_f32_16x16x32_bf16 v[32:35], v[234:237], v[196:199], v[32:35]
	v_mfma_f32_16x16x32_bf16 v[20:23], v[226:229], v[204:207], v[20:23]
	v_mfma_f32_16x16x32_bf16 v[16:19], v[234:237], v[204:207], v[16:19]
	v_mfma_f32_16x16x32_bf16 v[4:7], v[226:229], v[218:221], v[4:7]
	v_mfma_f32_16x16x32_bf16 v[0:3], v[234:237], v[218:221], v[0:3]
	s_setprio 0
	s_barrier
	s_add_u32 s13, s13, 0x100
	s_addc_u32 s17, s17, 0
	s_add_u32 s30, s30, 0x10000
	s_addc_u32 s31, s31, 0
	s_cmp_ge_i32 s29, s1
	s_mov_b32 s27, s29
	s_cbranch_scc0 .LBB0_1658
	s_branch .LBB0_1662

; #define PG8_STAGE(bufoff, gbase, voff) do { _Pragma("unroll") for (int _i = 0; _i < 2; ++_i) \
;         __builtin_amdgcn_global_load_lds((const unsigned*)((const char*)(gbase) + (voff)[_i]), (LAS unsigned*)(lds + (bufoff) + ldsw + _i * 8192), 16, 0, 0); } while (0)
; #define PG8_LDA(dst, b, h) do { _Pragma("unroll") for (int m = 0; m < 4; ++m) _Pragma("unroll") for (int k = 0; k < 2; ++k) dst[m][k] = *(const LAS bf16x8*)(lds + PG8_SA(b, h) + aoff + m * 2048 + k * 1024); } while (0)
; #define PG8_LDB(dst, b, h) do { _Pragma("unroll") for (int n = 0; n < 2; ++n) _Pragma("unroll") for (int k = 0; k < 2; ++k) dst[n][k] = *(const LAS bf16x8*)(lds + PG8_SB(b, h) + boff + n * 2048 + k * 1024); } while (0)
; #define PG8_MMA(ai, bj, At, Bt) do { __builtin_amdgcn_s_setprio(1); _Pragma("unroll") for (int m = 0; m < 4; ++m) _Pragma("unroll") for (int n = 0; n < 2; ++n) _Pragma("unroll") for (int k = 0; k < 2; ++k) \
;         acc[ai][bj][m][n] = __builtin_amdgcn_mfma_f32_16x16x32_bf16(Bt[n][k], At[m][k], acc[ai][bj][m][n], 0, 0, 0); __builtin_amdgcn_s_setprio(0); } while (0)
; #define PG8_WAIT_L(n) asm volatile("s_waitcnt lgkmcnt(" #n ")" ::: "memory")
; #define PG8_BAR __builtin_amdgcn_s_barrier()
; #define PG8_SCHED __builtin_amdgcn_sched_barrier(0)
; template <class Epi, class Sched, bool ATILE = false>
; __device__ __forceinline__ void gemm_phase(LAS unsigned char* lds, const Gemm g, const Sched& S, const Epi& E) {
;     ...
;         for (int t = 0; t < nt; t += 2) {
;             const bool last = (t == nt - 2);
;             const char* a1 = cA + (size_t)(t + 1) * kstepA;
;             const char* a2 = last ? nA : cA + (size_t)(t + 2) * kstepA; const char* b2 = last ? nB : cB + (size_t)(t + 2) * kstep;
;             const char* a3 = a2 + kstepA; const char* b3 = b2 + kstep;
;             PG8_LDB(B0, 0, 0); PG8_SCHED; PG8_LDA(At, 0, 0); PG8_STAGE(PG8_SA(1, 1), a1 + hstepA, voffA);
;             PG8_WAIT_L(8); PG8_BAR; PG8_WAIT_L(0); PG8_MMA(0, 0, At, B0); PG8_BAR; PG8_SCHED;
;             PG8_LDB(B1, 0, 1); PG8_STAGE(PG8_SB(0, 0), b2, voffB);
;             PG8_BAR; PG8_WAIT_L(0); PG8_MMA(0, 1, At, B1); PG8_BAR;
;             PG8_LDA(At, 0, 1); PG8_STAGE(PG8_SA(0, 0), a2, voffA);
;             PG8_BAR; PG8_WAIT_L(0); PG8_MMA(1, 0, At, B0); PG8_BAR; PG8_SCHED;
.LBB0_1812:
	ds_read_b128 v[176:179], v139
	ds_read_b128 v[180:183], v139 offset:1024
	ds_read_b128 v[184:187], v139 offset:2048
	ds_read_b128 v[188:191], v139 offset:3072
	s_add_i32 s34, s8, 2
	s_add_u32 s9, s6, 0xfff80080
	s_addc_u32 s10, s7, -1
	s_cmp_eq_u32 s19, s8
	s_cselect_b32 s8, s18, s25
	s_cselect_b32 s11, s13, s10
	s_cselect_b32 s10, s16, s9
	s_cselect_b32 s9, s17, s27
	s_add_i32 m0, s37, 0xc000
	ds_read_b128 v[192:195], v159
	ds_read_b128 v[196:199], v159 offset:1024
	ds_read_b128 v[200:203], v159 offset:2048
	ds_read_b128 v[204:207], v159 offset:3072
	ds_read_b128 v[208:211], v159 offset:4096
	ds_read_b128 v[212:215], v159 offset:5120
	ds_read_b128 v[216:219], v159 offset:6144
	ds_read_b128 v[220:223], v159 offset:7168
	global_load_lds_dwordx4 v164, s[6:7]
	s_add_i32 m0, s37, 0xe000
	s_nop 0
	global_load_lds_dwordx4 v166, s[6:7]
	s_waitcnt lgkmcnt(8)
	s_barrier
	s_waitcnt lgkmcnt(0)
	s_setprio 1
	s_waitcnt lgkmcnt(0)
	v_mfma_f32_16x16x32_bf16 v[120:123], v[176:179], v[192:195], v[120:123]
	v_mfma_f32_16x16x32_bf16 v[112:115], v[184:187], v[192:195], v[112:115]
	v_mfma_f32_16x16x32_bf16 v[104:107], v[176:179], v[200:203], v[104:107]
	v_mfma_f32_16x16x32_bf16 v[96:99], v[184:187], v[200:203], v[96:99]
	v_mfma_f32_16x16x32_bf16 v[88:91], v[176:179], v[208:211], v[88:91]
	v_mfma_f32_16x16x32_bf16 v[80:83], v[184:187], v[208:211], v[80:83]
	v_mfma_f32_16x16x32_bf16 v[72:75], v[176:179], v[216:219], v[72:75]
	v_mfma_f32_16x16x32_bf16 v[64:67], v[184:187], v[216:219], v[64:67]
	v_mfma_f32_16x16x32_bf16 v[120:123], v[180:183], v[196:199], v[120:123]
	v_mfma_f32_16x16x32_bf16 v[112:115], v[188:191], v[196:199], v[112:115]
	v_mfma_f32_16x16x32_bf16 v[104:107], v[180:183], v[204:207], v[104:107]
	v_mfma_f32_16x16x32_bf16 v[96:99], v[188:191], v[204:207], v[96:99]
	v_mfma_f32_16x16x32_bf16 v[88:91], v[180:183], v[212:215], v[88:91]
	v_mfma_f32_16x16x32_bf16 v[80:83], v[188:191], v[212:215], v[80:83]
	v_mfma_f32_16x16x32_bf16 v[72:75], v[180:183], v[220:223], v[72:75]
	v_mfma_f32_16x16x32_bf16 v[64:67], v[188:191], v[220:223], v[64:67]
	s_setprio 0
	s_barrier
	s_add_i32 s35, s51, s36
	v_lshl_add_u64 v[240:241], s[8:9], 0, v[130:131]
	s_mov_b32 m0, s35
	ds_read_b128 v[224:227], v173
	ds_read_b128 v[228:231], v173 offset:1024
	ds_read_b128 v[232:235], v173 offset:2048
	ds_read_b128 v[236:239], v173 offset:3072
	global_load_lds_dwordx4 v[240:241], off
	v_lshl_add_u64 v[242:243], s[8:9], 0, v[134:135]
	s_add_i32 m0, s35, 0x2000
	s_nop 0
	global_load_lds_dwordx4 v[242:243], off
	s_barrier
	s_waitcnt lgkmcnt(0)
	s_setprio 1
	s_waitcnt lgkmcnt(0)
	v_mfma_f32_16x16x32_bf16 v[124:127], v[224:227], v[192:195], v[124:127]
	v_mfma_f32_16x16x32_bf16 v[116:119], v[232:235], v[192:195], v[116:119]
	v_mfma_f32_16x16x32_bf16 v[108:111], v[224:227], v[200:203], v[108:111]
	v_mfma_f32_16x16x32_bf16 v[100:103], v[232:235], v[200:203], v[100:103]
	v_mfma_f32_16x16x32_bf16 v[92:95], v[224:227], v[208:211], v[92:95]
	v_mfma_f32_16x16x32_bf16 v[84:87], v[232:235], v[208:211], v[84:87]
	v_mfma_f32_16x16x32_bf16 v[76:79], v[224:227], v[216:219], v[76:79]
	v_mfma_f32_16x16x32_bf16 v[68:71], v[232:235], v[216:219], v[68:71]
	v_mfma_f32_16x16x32_bf16 v[124:127], v[228:231], v[196:199], v[124:127]
	v_mfma_f32_16x16x32_bf16 v[116:119], v[236:239], v[196:199], v[116:119]
	v_mfma_f32_16x16x32_bf16 v[108:111], v[228:231], v[204:207], v[108:111]
	v_mfma_f32_16x16x32_bf16 v[100:103], v[236:239], v[204:207], v[100:103]
	v_mfma_f32_16x16x32_bf16 v[92:95], v[228:231], v[212:215], v[92:95]
	v_mfma_f32_16x16x32_bf16 v[84:87], v[236:239], v[212:215], v[84:87]
	v_mfma_f32_16x16x32_bf16 v[76:79], v[228:231], v[220:223], v[76:79]
	v_mfma_f32_16x16x32_bf16 v[68:71], v[236:239], v[220:223], v[68:71]
	s_setprio 0
	s_barrier
	s_mov_b32 m0, s37
	v_lshl_add_u64 v[244:245], s[10:11], 0, v[128:129]
	ds_read_b128 v[192:195], v159 offset:16384
	ds_read_b128 v[196:199], v159 offset:17408
	ds_read_b128 v[200:203], v159 offset:18432
	ds_read_b128 v[204:207], v159 offset:19456
	ds_read_b128 v[208:211], v159 offset:20480
	ds_read_b128 v[212:215], v159 offset:21504
	ds_read_b128 v[216:219], v159 offset:22528
	ds_read_b128 v[220:223], v159 offset:23552
	global_load_lds_dwordx4 v[244:245], off
	v_lshl_add_u64 v[246:247], s[10:11], 0, v[132:133]
	s_mov_b32 m0, s38
	s_nop 0
	global_load_lds_dwordx4 v[246:247], off
	s_barrier
	s_waitcnt lgkmcnt(0)
	s_setprio 1
	s_waitcnt lgkmcnt(0)
	v_mfma_f32_16x16x32_bf16 v[56:59], v[176:179], v[192:195], v[56:59]
	v_mfma_f32_16x16x32_bf16 v[48:51], v[184:187], v[192:195], v[48:51]
	v_mfma_f32_16x16x32_bf16 v[40:43], v[176:179], v[200:203], v[40:43]
	v_mfma_f32_16x16x32_bf16 v[32:35], v[184:187], v[200:203], v[32:35]
	v_mfma_f32_16x16x32_bf16 v[24:27], v[176:179], v[208:211], v[24:27]
	v_mfma_f32_16x16x32_bf16 v[16:19], v[184:187], v[208:211], v[16:19]
	v_mfma_f32_16x16x32_bf16 v[8:11], v[176:179], v[216:219], v[8:11]
	v_mfma_f32_16x16x32_bf16 v[4:7], v[184:187], v[216:219], v[4:7]
	v_mfma_f32_16x16x32_bf16 v[56:59], v[180:183], v[196:199], v[56:59]
	v_mfma_f32_16x16x32_bf16 v[48:51], v[188:191], v[196:199], v[48:51]
	v_mfma_f32_16x16x32_bf16 v[40:43], v[180:183], v[204:207], v[40:43]
	v_mfma_f32_16x16x32_bf16 v[32:35], v[188:191], v[204:207], v[32:35]
	v_mfma_f32_16x16x32_bf16 v[24:27], v[180:183], v[212:215], v[24:27]
	v_mfma_f32_16x16x32_bf16 v[16:19], v[188:191], v[212:215], v[16:19]
	v_mfma_f32_16x16x32_bf16 v[8:11], v[180:183], v[220:223], v[8:11]
	v_mfma_f32_16x16x32_bf16 v[4:7], v[188:191], v[220:223], v[4:7]
	s_setprio 0
	s_barrier
; #define PG8_STAGE(bufoff, gbase, voff) do { _Pragma("unroll") for (int _i = 0; _i < 2; ++_i) \
;         __builtin_amdgcn_global_load_lds((const unsigned*)((const char*)(gbase) + (voff)[_i]), (LAS unsigned*)(lds + (bufoff) + ldsw + _i * 8192), 16, 0, 0); } while (0)
; #define PG8_LDA(dst, b, h) do { _Pragma("unroll") for (int m = 0; m < 4; ++m) _Pragma("unroll") for (int k = 0; k < 2; ++k) dst[m][k] = *(const LAS bf16x8*)(lds + PG8_SA(b, h) + aoff + m * 2048 + k * 1024); } while (0)
; #define PG8_LDB(dst, b, h) do { _Pragma("unroll") for (int n = 0; n < 2; ++n) _Pragma("unroll") for (int k = 0; k < 2; ++k) dst[n][k] = *(const LAS bf16x8*)(lds + PG8_SB(b, h) + boff + n * 2048 + k * 1024); } while (0)
; #define PG8_MMA(ai, bj, At, Bt) do { __builtin_amdgcn_s_setprio(1); _Pragma("unroll") for (int m = 0; m < 4; ++m) _Pragma("unroll") for (int n = 0; n < 2; ++n) _Pragma("unroll") for (int k = 0; k < 2; ++k) \
;         acc[ai][bj][m][n] = __builtin_amdgcn_mfma_f32_16x16x32_bf16(Bt[n][k], At[m][k], acc[ai][bj][m][n], 0, 0, 0); __builtin_amdgcn_s_setprio(0); } while (0)
; #define PG8_WAIT_V(n) asm volatile("s_waitcnt vmcnt(" #n ")" ::: "memory")
; #define PG8_WAIT_L(n) asm volatile("s_waitcnt lgkmcnt(" #n ")" ::: "memory")
; #define PG8_BAR __builtin_amdgcn_s_barrier()
; #define PG8_SCHED __builtin_amdgcn_sched_barrier(0)
; template <class Epi, class Sched, bool ATILE = false>
; __device__ __forceinline__ void gemm_phase(LAS unsigned char* lds, const Gemm g, const Sched& S, const Epi& E) {
;     ...
;             PG8_STAGE(PG8_SB(0, 1), b2 + hstepB, voffB);
;             PG8_WAIT_V(6); PG8_BAR; PG8_MMA(1, 1, At, B1); PG8_BAR;
;             PG8_LDB(B0, 1, 0); PG8_SCHED; PG8_LDA(At, 1, 0); PG8_STAGE(PG8_SA(0, 1), a2 + hstepA, voffA);
;             PG8_WAIT_L(8); PG8_BAR; PG8_WAIT_L(0); PG8_MMA(0, 0, At, B0); PG8_BAR; PG8_SCHED;
;             PG8_LDB(B1, 1, 1); PG8_STAGE(PG8_SB(1, 0), b3, voffB);
;             PG8_BAR; PG8_WAIT_L(0); PG8_MMA(0, 1, At, B1); PG8_BAR;
	s_add_u32 s54, s8, 0x80000
	s_addc_u32 s55, s9, 0
	s_add_i32 s35, s52, s36
	s_mov_b32 m0, s35
	s_nop 0
	global_load_lds_dwordx4 v130, s[54:55]
	s_add_i32 m0, s35, 0x2000
	s_nop 0
	global_load_lds_dwordx4 v134, s[54:55]
	s_waitcnt vmcnt(6)
	s_barrier
	s_setprio 1
	v_mfma_f32_16x16x32_bf16 v[60:63], v[224:227], v[192:195], v[60:63]
	v_mfma_f32_16x16x32_bf16 v[52:55], v[232:235], v[192:195], v[52:55]
	v_mfma_f32_16x16x32_bf16 v[44:47], v[224:227], v[200:203], v[44:47]
	v_mfma_f32_16x16x32_bf16 v[36:39], v[232:235], v[200:203], v[36:39]
	v_mfma_f32_16x16x32_bf16 v[28:31], v[224:227], v[208:211], v[28:31]
	v_mfma_f32_16x16x32_bf16 v[20:23], v[232:235], v[208:211], v[20:23]
	v_mfma_f32_16x16x32_bf16 v[12:15], v[224:227], v[216:219], v[12:15]
	v_mfma_f32_16x16x32_bf16 v[0:3], v[232:235], v[216:219], v[0:3]
	v_mfma_f32_16x16x32_bf16 v[60:63], v[228:231], v[196:199], v[60:63]
	v_mfma_f32_16x16x32_bf16 v[52:55], v[236:239], v[196:199], v[52:55]
	v_mfma_f32_16x16x32_bf16 v[44:47], v[228:231], v[204:207], v[44:47]
	v_mfma_f32_16x16x32_bf16 v[36:39], v[236:239], v[204:207], v[36:39]
	v_mfma_f32_16x16x32_bf16 v[28:31], v[228:231], v[212:215], v[28:31]
	v_mfma_f32_16x16x32_bf16 v[20:23], v[236:239], v[212:215], v[20:23]
	v_mfma_f32_16x16x32_bf16 v[12:15], v[228:231], v[220:223], v[12:15]
	v_mfma_f32_16x16x32_bf16 v[0:3], v[236:239], v[220:223], v[0:3]
	s_setprio 0
	s_barrier
	s_add_i32 s35, 0, 0x18000
	v_add_u32_e32 v172, s35, v157
	ds_read_b128 v[176:179], v172
	ds_read_b128 v[180:183], v172 offset:1024
	ds_read_b128 v[184:187], v172 offset:2048
	ds_read_b128 v[188:191], v172 offset:3072
	s_add_u32 s10, s10, 0x80000
	s_addc_u32 s11, s11, 0
	s_mov_b32 m0, s39
	ds_read_b128 v[192:195], v159 offset:32768
	ds_read_b128 v[196:199], v159 offset:33792
	ds_read_b128 v[200:203], v159 offset:34816
	ds_read_b128 v[204:207], v159 offset:35840
	ds_read_b128 v[208:211], v159 offset:36864
	ds_read_b128 v[212:215], v159 offset:37888
	ds_read_b128 v[216:219], v159 offset:38912
	ds_read_b128 v[220:223], v159 offset:39936
	global_load_lds_dwordx4 v128, s[10:11]
	s_mov_b32 m0, s40
	s_nop 0
	global_load_lds_dwordx4 v132, s[10:11]
	s_waitcnt lgkmcnt(8)
	s_barrier
	s_waitcnt lgkmcnt(0)
	s_setprio 1
	s_waitcnt lgkmcnt(0)
	v_mfma_f32_16x16x32_bf16 v[120:123], v[176:179], v[192:195], v[120:123]
	v_mfma_f32_16x16x32_bf16 v[112:115], v[184:187], v[192:195], v[112:115]
	v_mfma_f32_16x16x32_bf16 v[104:107], v[176:179], v[200:203], v[104:107]
	v_mfma_f32_16x16x32_bf16 v[96:99], v[184:187], v[200:203], v[96:99]
	v_mfma_f32_16x16x32_bf16 v[88:91], v[176:179], v[208:211], v[88:91]
	v_mfma_f32_16x16x32_bf16 v[80:83], v[184:187], v[208:211], v[80:83]
	v_mfma_f32_16x16x32_bf16 v[72:75], v[176:179], v[216:219], v[72:75]
	v_mfma_f32_16x16x32_bf16 v[64:67], v[184:187], v[216:219], v[64:67]
	v_mfma_f32_16x16x32_bf16 v[120:123], v[180:183], v[196:199], v[120:123]
	v_mfma_f32_16x16x32_bf16 v[112:115], v[188:191], v[196:199], v[112:115]
	v_mfma_f32_16x16x32_bf16 v[104:107], v[180:183], v[204:207], v[104:107]
	v_mfma_f32_16x16x32_bf16 v[96:99], v[188:191], v[204:207], v[96:99]
	v_mfma_f32_16x16x32_bf16 v[88:91], v[180:183], v[212:215], v[88:91]
	v_mfma_f32_16x16x32_bf16 v[80:83], v[188:191], v[212:215], v[80:83]
	v_mfma_f32_16x16x32_bf16 v[72:75], v[180:183], v[220:223], v[72:75]
	v_mfma_f32_16x16x32_bf16 v[64:67], v[188:191], v[220:223], v[64:67]
	s_setprio 0
	s_barrier
	s_add_i32 s10, 0, 0x1c000
	s_add_i32 s11, s35, s36
	v_add_u32_e32 v172, s10, v157
	v_lshl_add_u64 v[240:241], v[240:241], 0, s[22:23]
	s_mov_b32 m0, s11
	ds_read_b128 v[224:227], v172
	ds_read_b128 v[228:231], v172 offset:1024
	ds_read_b128 v[232:235], v172 offset:2048
	ds_read_b128 v[236:239], v172 offset:3072
	global_load_lds_dwordx4 v[240:241], off
	v_lshl_add_u64 v[240:241], v[242:243], 0, s[22:23]
	s_add_i32 m0, s11, 0x2000
	s_nop 0
	global_load_lds_dwordx4 v[240:241], off
	s_barrier
; #define PG8_STAGE(bufoff, gbase, voff) do { _Pragma("unroll") for (int _i = 0; _i < 2; ++_i) \
;         __builtin_amdgcn_global_load_lds((const unsigned*)((const char*)(gbase) + (voff)[_i]), (LAS unsigned*)(lds + (bufoff) + ldsw + _i * 8192), 16, 0, 0); } while (0)
; #define PG8_LDA(dst, b, h) do { _Pragma("unroll") for (int m = 0; m < 4; ++m) _Pragma("unroll") for (int k = 0; k < 2; ++k) dst[m][k] = *(const LAS bf16x8*)(lds + PG8_SA(b, h) + aoff + m * 2048 + k * 1024); } while (0)
; #define PG8_MMA(ai, bj, At, Bt) do { __builtin_amdgcn_s_setprio(1); _Pragma("unroll") for (int m = 0; m < 4; ++m) _Pragma("unroll") for (int n = 0; n < 2; ++n) _Pragma("unroll") for (int k = 0; k < 2; ++k) \
;         acc[ai][bj][m][n] = __builtin_amdgcn_mfma_f32_16x16x32_bf16(Bt[n][k], At[m][k], acc[ai][bj][m][n], 0, 0, 0); __builtin_amdgcn_s_setprio(0); } while (0)
; #define PG8_WAIT_V(n) asm volatile("s_waitcnt vmcnt(" #n ")" ::: "memory")
; #define PG8_WAIT_L(n) asm volatile("s_waitcnt lgkmcnt(" #n ")" ::: "memory")
; #define PG8_BAR __builtin_amdgcn_s_barrier()
; #define PG8_SCHED __builtin_amdgcn_sched_barrier(0)
; template <class Epi, class Sched, bool ATILE = false>
; __device__ __forceinline__ void gemm_phase(LAS unsigned char* lds, const Gemm g, const Sched& S, const Epi& E) {
;     ...
;             PG8_BAR; PG8_WAIT_L(0); PG8_MMA(0, 1, At, B1); PG8_BAR;
;             PG8_LDA(At, 1, 1); PG8_STAGE(PG8_SA(1, 0), a3, voffA);
;             PG8_BAR; PG8_WAIT_L(0); PG8_MMA(1, 0, At, B0); PG8_BAR; PG8_SCHED;
;             PG8_STAGE(PG8_SB(1, 1), b3 + hstepB, voffB);
;             PG8_WAIT_V(6); PG8_BAR; PG8_MMA(1, 1, At, B1); PG8_BAR;
;         }
;         E(acc, cur, wr, wc, fr, fq);
;         if (!has_next) break;
	s_waitcnt lgkmcnt(0)
	s_setprio 1
	s_waitcnt lgkmcnt(0)
	v_mfma_f32_16x16x32_bf16 v[124:127], v[224:227], v[192:195], v[124:127]
	v_mfma_f32_16x16x32_bf16 v[116:119], v[232:235], v[192:195], v[116:119]
	v_mfma_f32_16x16x32_bf16 v[108:111], v[224:227], v[200:203], v[108:111]
	v_mfma_f32_16x16x32_bf16 v[100:103], v[232:235], v[200:203], v[100:103]
	v_mfma_f32_16x16x32_bf16 v[92:95], v[224:227], v[208:211], v[92:95]
	v_mfma_f32_16x16x32_bf16 v[84:87], v[232:235], v[208:211], v[84:87]
	v_mfma_f32_16x16x32_bf16 v[76:79], v[224:227], v[216:219], v[76:79]
	v_mfma_f32_16x16x32_bf16 v[68:71], v[232:235], v[216:219], v[68:71]
	v_mfma_f32_16x16x32_bf16 v[124:127], v[228:231], v[196:199], v[124:127]
	v_mfma_f32_16x16x32_bf16 v[116:119], v[236:239], v[196:199], v[116:119]
	v_mfma_f32_16x16x32_bf16 v[108:111], v[228:231], v[204:207], v[108:111]
	v_mfma_f32_16x16x32_bf16 v[100:103], v[236:239], v[204:207], v[100:103]
	v_mfma_f32_16x16x32_bf16 v[92:95], v[228:231], v[212:215], v[92:95]
	v_mfma_f32_16x16x32_bf16 v[84:87], v[236:239], v[212:215], v[84:87]
	v_mfma_f32_16x16x32_bf16 v[76:79], v[228:231], v[220:223], v[76:79]
	v_mfma_f32_16x16x32_bf16 v[68:71], v[236:239], v[220:223], v[68:71]
	s_setprio 0
	s_barrier
	s_mov_b32 m0, s43
	v_lshl_add_u64 v[240:241], v[244:245], 0, s[22:23]
	ds_read_b128 v[192:195], v159 offset:49152
	ds_read_b128 v[196:199], v159 offset:50176
	ds_read_b128 v[200:203], v159 offset:51200
	ds_read_b128 v[204:207], v159 offset:52224
	ds_read_b128 v[208:211], v159 offset:53248
	ds_read_b128 v[212:215], v159 offset:54272
	ds_read_b128 v[216:219], v159 offset:55296
	ds_read_b128 v[220:223], v159 offset:56320
	global_load_lds_dwordx4 v[240:241], off
	v_lshl_add_u64 v[240:241], v[246:247], 0, s[22:23]
	s_mov_b32 m0, s44
	s_nop 0
	global_load_lds_dwordx4 v[240:241], off
	s_barrier
	s_waitcnt lgkmcnt(0)
	s_setprio 1
	s_waitcnt lgkmcnt(0)
	v_mfma_f32_16x16x32_bf16 v[56:59], v[176:179], v[192:195], v[56:59]
	v_mfma_f32_16x16x32_bf16 v[48:51], v[184:187], v[192:195], v[48:51]
	v_mfma_f32_16x16x32_bf16 v[40:43], v[176:179], v[200:203], v[40:43]
	v_mfma_f32_16x16x32_bf16 v[32:35], v[184:187], v[200:203], v[32:35]
	v_mfma_f32_16x16x32_bf16 v[24:27], v[176:179], v[208:211], v[24:27]
	v_mfma_f32_16x16x32_bf16 v[16:19], v[184:187], v[208:211], v[16:19]
	v_mfma_f32_16x16x32_bf16 v[8:11], v[176:179], v[216:219], v[8:11]
	v_mfma_f32_16x16x32_bf16 v[4:7], v[184:187], v[216:219], v[4:7]
	v_mfma_f32_16x16x32_bf16 v[56:59], v[180:183], v[196:199], v[56:59]
	v_mfma_f32_16x16x32_bf16 v[48:51], v[188:191], v[196:199], v[48:51]
	v_mfma_f32_16x16x32_bf16 v[40:43], v[180:183], v[204:207], v[40:43]
	v_mfma_f32_16x16x32_bf16 v[32:35], v[188:191], v[204:207], v[32:35]
	v_mfma_f32_16x16x32_bf16 v[24:27], v[180:183], v[212:215], v[24:27]
	v_mfma_f32_16x16x32_bf16 v[16:19], v[188:191], v[212:215], v[16:19]
	v_mfma_f32_16x16x32_bf16 v[8:11], v[180:183], v[220:223], v[8:11]
	v_mfma_f32_16x16x32_bf16 v[4:7], v[188:191], v[220:223], v[4:7]
	s_setprio 0
	s_barrier
	s_add_u32 s8, s8, 0x80080
	s_addc_u32 s9, s9, 0
	s_add_i32 s10, s10, s36
	s_mov_b32 m0, s10
	s_nop 0
	global_load_lds_dwordx4 v130, s[8:9]
	s_add_i32 m0, s10, 0x2000
	s_nop 0
	global_load_lds_dwordx4 v134, s[8:9]
	s_waitcnt vmcnt(6)
	s_barrier
	s_setprio 1
	v_mfma_f32_16x16x32_bf16 v[60:63], v[224:227], v[192:195], v[60:63]
	v_mfma_f32_16x16x32_bf16 v[52:55], v[232:235], v[192:195], v[52:55]
	v_mfma_f32_16x16x32_bf16 v[44:47], v[224:227], v[200:203], v[44:47]
	v_mfma_f32_16x16x32_bf16 v[36:39], v[232:235], v[200:203], v[36:39]
	v_mfma_f32_16x16x32_bf16 v[28:31], v[224:227], v[208:211], v[28:31]
	v_mfma_f32_16x16x32_bf16 v[20:23], v[232:235], v[208:211], v[20:23]
	v_mfma_f32_16x16x32_bf16 v[12:15], v[224:227], v[216:219], v[12:15]
	v_mfma_f32_16x16x32_bf16 v[0:3], v[232:235], v[216:219], v[0:3]
	v_mfma_f32_16x16x32_bf16 v[60:63], v[228:231], v[196:199], v[60:63]
	v_mfma_f32_16x16x32_bf16 v[52:55], v[236:239], v[196:199], v[52:55]
	v_mfma_f32_16x16x32_bf16 v[44:47], v[228:231], v[204:207], v[44:47]
	v_mfma_f32_16x16x32_bf16 v[36:39], v[236:239], v[204:207], v[36:39]
	v_mfma_f32_16x16x32_bf16 v[28:31], v[228:231], v[212:215], v[28:31]
	v_mfma_f32_16x16x32_bf16 v[20:23], v[236:239], v[212:215], v[20:23]
	v_mfma_f32_16x16x32_bf16 v[12:15], v[228:231], v[220:223], v[12:15]
	v_mfma_f32_16x16x32_bf16 v[0:3], v[236:239], v[220:223], v[0:3]
	s_setprio 0
	s_barrier
	s_add_u32 s6, s6, 0x100
	s_addc_u32 s7, s7, 0
	s_add_u32 s25, s25, 0x100
	s_addc_u32 s27, s27, 0
	s_cmp_ge_i32 s34, s12
	s_mov_b32 s8, s34
	s_cbranch_scc0 .LBB0_1812
	s_branch .LBB0_1803

; #define PG8_STAGE(bufoff, gbase, voff) do { _Pragma("unroll") for (int _i = 0; _i < 2; ++_i) \
;         __builtin_amdgcn_global_load_lds((const unsigned*)((const char*)(gbase) + (voff)[_i]), (LAS unsigned*)(lds + (bufoff) + ldsw + _i * 8192), 16, 0, 0); } while (0)
; #define PG8_LDA(dst, b, h) do { _Pragma("unroll") for (int m = 0; m < 4; ++m) _Pragma("unroll") for (int k = 0; k < 2; ++k) dst[m][k] = *(const LAS bf16x8*)(lds + PG8_SA(b, h) + aoff + m * 2048 + k * 1024); } while (0)
; #define PG8_LDB(dst, b, h) do { _Pragma("unroll") for (int n = 0; n < 2; ++n) _Pragma("unroll") for (int k = 0; k < 2; ++k) dst[n][k] = *(const LAS bf16x8*)(lds + PG8_SB(b, h) + boff + n * 2048 + k * 1024); } while (0)
; #define PG8_MMA(ai, bj, At, Bt) do { __builtin_amdgcn_s_setprio(1); _Pragma("unroll") for (int m = 0; m < 4; ++m) _Pragma("unroll") for (int n = 0; n < 2; ++n) _Pragma("unroll") for (int k = 0; k < 2; ++k) \
;         acc[ai][bj][m][n] = __builtin_amdgcn_mfma_f32_16x16x32_bf16(Bt[n][k], At[m][k], acc[ai][bj][m][n], 0, 0, 0); __builtin_amdgcn_s_setprio(0); } while (0)
; #define PG8_WAIT_V(n) asm volatile("s_waitcnt vmcnt(" #n ")" ::: "memory")
; #define PG8_WAIT_L(n) asm volatile("s_waitcnt lgkmcnt(" #n ")" ::: "memory")
; #define PG8_BAR __builtin_amdgcn_s_barrier()
; #define PG8_SCHED __builtin_amdgcn_sched_barrier(0)
; template <class Epi, class Sched, bool ATILE = false>
; __device__ __forceinline__ void gemm_phase(LAS unsigned char* lds, const Gemm g, const Sched& S, const Epi& E) {
;     ...
;             PG8_LDB(B0, 0, 0); PG8_SCHED; PG8_LDA(At, 0, 0); PG8_STAGE(PG8_SA(1, 1), a1 + hstepA, voffA);
;             PG8_WAIT_L(8); PG8_BAR; PG8_WAIT_L(0); PG8_MMA(0, 0, At, B0); PG8_BAR; PG8_SCHED;
;             PG8_LDB(B1, 0, 1); PG8_STAGE(PG8_SB(0, 0), b2, voffB);
;             PG8_BAR; PG8_WAIT_L(0); PG8_MMA(0, 1, At, B1); PG8_BAR;
;             PG8_LDA(At, 0, 1); PG8_STAGE(PG8_SA(0, 0), a2, voffA);
;             PG8_BAR; PG8_WAIT_L(0); PG8_MMA(1, 0, At, B0); PG8_BAR; PG8_SCHED;
;             PG8_STAGE(PG8_SB(0, 1), b2 + hstepB, voffB);
;             PG8_WAIT_V(6); PG8_BAR; PG8_MMA(1, 1, At, B1); PG8_BAR;
.LBB0_1898:
	ds_read_b128 v[20:23], v180
	ds_read_b128 v[28:31], v180 offset:1024
	ds_read_b128 v[174:177], v180 offset:2048
	ds_read_b128 v[184:187], v180 offset:3072
	s_add_i32 s58, s26, 2
	s_add_u32 s27, s24, 0x4000
	s_addc_u32 s28, s25, 0
	s_cmp_eq_u32 s17, s26
	s_cselect_b32 s30, s20, s27
	s_cselect_b32 s31, s21, s28
	s_cselect_b32 s26, s22, s56
	s_cselect_b32 s27, s23, s57
	s_add_u32 s28, s30, 0x8000
	s_addc_u32 s29, s31, 0
	s_add_i32 m0, s34, 0xc000
	ds_read_b128 v[188:191], v181
	ds_read_b128 v[192:195], v181 offset:1024
	ds_read_b128 v[196:199], v181 offset:2048
	ds_read_b128 v[200:203], v181 offset:3072
	ds_read_b128 v[204:207], v181 offset:4096
	ds_read_b128 v[208:211], v181 offset:5120
	ds_read_b128 v[212:215], v181 offset:6144
	ds_read_b128 v[216:219], v181 offset:7168
	global_load_lds_dwordx4 v168, s[24:25]
	s_add_i32 m0, s34, 0xe000
	s_nop 0
	global_load_lds_dwordx4 v170, s[24:25]
	s_waitcnt lgkmcnt(8)
	s_barrier
	s_waitcnt lgkmcnt(0)
	s_setprio 1
	s_waitcnt lgkmcnt(0)
	v_mfma_f32_16x16x32_bf16 v[0:3], v[20:23], v[188:191], v[0:3]
	v_mfma_f32_16x16x32_bf16 v[4:7], v[174:177], v[188:191], v[4:7]
	v_mfma_f32_16x16x32_bf16 v[44:47], v[20:23], v[196:199], v[44:47]
	v_mfma_f32_16x16x32_bf16 v[36:39], v[174:177], v[196:199], v[36:39]
	v_mfma_f32_16x16x32_bf16 v[52:55], v[20:23], v[204:207], v[52:55]
	v_mfma_f32_16x16x32_bf16 v[48:51], v[174:177], v[204:207], v[48:51]
	v_mfma_f32_16x16x32_bf16 v[92:95], v[20:23], v[212:215], v[92:95]
	v_mfma_f32_16x16x32_bf16 v[84:87], v[174:177], v[212:215], v[84:87]
	v_mfma_f32_16x16x32_bf16 v[0:3], v[28:31], v[192:195], v[0:3]
	v_mfma_f32_16x16x32_bf16 v[4:7], v[184:187], v[192:195], v[4:7]
	v_mfma_f32_16x16x32_bf16 v[44:47], v[28:31], v[200:203], v[44:47]
	v_mfma_f32_16x16x32_bf16 v[36:39], v[184:187], v[200:203], v[36:39]
	v_mfma_f32_16x16x32_bf16 v[52:55], v[28:31], v[208:211], v[52:55]
	v_mfma_f32_16x16x32_bf16 v[48:51], v[184:187], v[208:211], v[48:51]
	v_mfma_f32_16x16x32_bf16 v[92:95], v[28:31], v[216:219], v[92:95]
	v_mfma_f32_16x16x32_bf16 v[84:87], v[184:187], v[216:219], v[84:87]
	s_setprio 0
	s_barrier
	s_add_i32 s59, s44, s33
	v_lshl_add_u64 v[178:179], s[26:27], 0, v[138:139]
	s_mov_b32 m0, s59
	ds_read_b128 v[220:223], v182
	ds_read_b128 v[224:227], v182 offset:1024
	ds_read_b128 v[228:231], v182 offset:2048
	ds_read_b128 v[232:235], v182 offset:3072
	global_load_lds_dwordx4 v[178:179], off
	v_lshl_add_u64 v[236:237], s[26:27], 0, v[142:143]
	s_add_i32 m0, s59, 0x2000
	s_nop 0
	global_load_lds_dwordx4 v[236:237], off
	s_barrier
	s_waitcnt lgkmcnt(0)
	s_setprio 1
	s_waitcnt lgkmcnt(0)
	v_mfma_f32_16x16x32_bf16 v[12:15], v[220:223], v[188:191], v[12:15]
	v_mfma_f32_16x16x32_bf16 v[8:11], v[228:231], v[188:191], v[8:11]
	v_mfma_f32_16x16x32_bf16 v[24:27], v[220:223], v[196:199], v[24:27]
	v_mfma_f32_16x16x32_bf16 v[16:19], v[228:231], v[196:199], v[16:19]
	v_mfma_f32_16x16x32_bf16 v[40:43], v[220:223], v[204:207], v[40:43]
	v_mfma_f32_16x16x32_bf16 v[32:35], v[228:231], v[204:207], v[32:35]
	v_mfma_f32_16x16x32_bf16 v[56:59], v[220:223], v[212:215], v[56:59]
	v_mfma_f32_16x16x32_bf16 v[60:63], v[228:231], v[212:215], v[60:63]
	v_mfma_f32_16x16x32_bf16 v[12:15], v[224:227], v[192:195], v[12:15]
	v_mfma_f32_16x16x32_bf16 v[8:11], v[232:235], v[192:195], v[8:11]
	v_mfma_f32_16x16x32_bf16 v[24:27], v[224:227], v[200:203], v[24:27]
	v_mfma_f32_16x16x32_bf16 v[16:19], v[232:235], v[200:203], v[16:19]
	v_mfma_f32_16x16x32_bf16 v[40:43], v[224:227], v[208:211], v[40:43]
	v_mfma_f32_16x16x32_bf16 v[32:35], v[232:235], v[208:211], v[32:35]
	v_mfma_f32_16x16x32_bf16 v[56:59], v[224:227], v[216:219], v[56:59]
	v_mfma_f32_16x16x32_bf16 v[60:63], v[232:235], v[216:219], v[60:63]
	s_setprio 0
	s_barrier
	s_mov_b32 m0, s34
	ds_read_b128 v[188:191], v181 offset:16384
	ds_read_b128 v[192:195], v181 offset:17408
	ds_read_b128 v[196:199], v181 offset:18432
	ds_read_b128 v[200:203], v181 offset:19456
	ds_read_b128 v[204:207], v181 offset:20480
	ds_read_b128 v[208:211], v181 offset:21504
	ds_read_b128 v[212:215], v181 offset:22528
	ds_read_b128 v[216:219], v181 offset:23552
	global_load_lds_dwordx4 v136, s[30:31]
	s_mov_b32 m0, s35
	s_nop 0
	global_load_lds_dwordx4 v140, s[30:31]
	s_barrier
	s_waitcnt lgkmcnt(0)
	s_setprio 1
	s_waitcnt lgkmcnt(0)
	v_mfma_f32_16x16x32_bf16 v[64:67], v[20:23], v[188:191], v[64:67]
	v_mfma_f32_16x16x32_bf16 v[68:71], v[174:177], v[188:191], v[68:71]
	v_mfma_f32_16x16x32_bf16 v[108:111], v[20:23], v[196:199], v[108:111]
	v_mfma_f32_16x16x32_bf16 v[100:103], v[174:177], v[196:199], v[100:103]
	v_mfma_f32_16x16x32_bf16 v[116:119], v[20:23], v[204:207], v[116:119]
	v_mfma_f32_16x16x32_bf16 v[112:115], v[174:177], v[204:207], v[112:115]
	v_mfma_f32_16x16x32_bf16 v[20:23], v[20:23], v[212:215], v[132:135]
	v_mfma_f32_16x16x32_bf16 v[64:67], v[28:31], v[192:195], v[64:67]
	v_mfma_f32_16x16x32_bf16 v[68:71], v[184:187], v[192:195], v[68:71]
	v_mfma_f32_16x16x32_bf16 v[108:111], v[28:31], v[200:203], v[108:111]
	v_mfma_f32_16x16x32_bf16 v[100:103], v[184:187], v[200:203], v[100:103]
	v_mfma_f32_16x16x32_bf16 v[116:119], v[28:31], v[208:211], v[116:119]
	v_mfma_f32_16x16x32_bf16 v[112:115], v[184:187], v[208:211], v[112:115]
	v_mfma_f32_16x16x32_bf16 v[20:23], v[28:31], v[216:219], v[20:23]
	v_mfma_f32_16x16x32_bf16 v[28:31], v[174:177], v[212:215], v[128:131]
	v_mfma_f32_16x16x32_bf16 v[28:31], v[184:187], v[216:219], v[28:31]
	s_setprio 0
	s_barrier
	s_add_u32 s60, s26, 0x158000
	s_addc_u32 s61, s27, 0
	s_add_i32 s59, s45, s33
	s_mov_b32 m0, s59
	s_nop 0
	global_load_lds_dwordx4 v138, s[60:61]
	s_add_i32 m0, s59, 0x2000
	s_nop 0
	global_load_lds_dwordx4 v142, s[60:61]
	s_waitcnt vmcnt(6)
	s_barrier
; #define PG8_STAGE(bufoff, gbase, voff) do { _Pragma("unroll") for (int _i = 0; _i < 2; ++_i) \
;         __builtin_amdgcn_global_load_lds((const unsigned*)((const char*)(gbase) + (voff)[_i]), (LAS unsigned*)(lds + (bufoff) + ldsw + _i * 8192), 16, 0, 0); } while (0)
; #define PG8_LDA(dst, b, h) do { _Pragma("unroll") for (int m = 0; m < 4; ++m) _Pragma("unroll") for (int k = 0; k < 2; ++k) dst[m][k] = *(const LAS bf16x8*)(lds + PG8_SA(b, h) + aoff + m * 2048 + k * 1024); } while (0)
; #define PG8_LDB(dst, b, h) do { _Pragma("unroll") for (int n = 0; n < 2; ++n) _Pragma("unroll") for (int k = 0; k < 2; ++k) dst[n][k] = *(const LAS bf16x8*)(lds + PG8_SB(b, h) + boff + n * 2048 + k * 1024); } while (0)
; #define PG8_MMA(ai, bj, At, Bt) do { __builtin_amdgcn_s_setprio(1); _Pragma("unroll") for (int m = 0; m < 4; ++m) _Pragma("unroll") for (int n = 0; n < 2; ++n) _Pragma("unroll") for (int k = 0; k < 2; ++k) \
;         acc[ai][bj][m][n] = __builtin_amdgcn_mfma_f32_16x16x32_bf16(Bt[n][k], At[m][k], acc[ai][bj][m][n], 0, 0, 0); __builtin_amdgcn_s_setprio(0); } while (0)
; #define PG8_WAIT_V(n) asm volatile("s_waitcnt vmcnt(" #n ")" ::: "memory")
; #define PG8_WAIT_L(n) asm volatile("s_waitcnt lgkmcnt(" #n ")" ::: "memory")
; #define PG8_BAR __builtin_amdgcn_s_barrier()
; #define PG8_SCHED __builtin_amdgcn_sched_barrier(0)
; template <class Epi, class Sched, bool ATILE = false>
; __device__ __forceinline__ void gemm_phase(LAS unsigned char* lds, const Gemm g, const Sched& S, const Epi& E) {
;     ...
;             PG8_WAIT_V(6); PG8_BAR; PG8_MMA(1, 1, At, B1); PG8_BAR;
;             PG8_LDB(B0, 1, 0); PG8_SCHED; PG8_LDA(At, 1, 0); PG8_STAGE(PG8_SA(0, 1), a2 + hstepA, voffA);
;             PG8_WAIT_L(8); PG8_BAR; PG8_WAIT_L(0); PG8_MMA(0, 0, At, B0); PG8_BAR; PG8_SCHED;
;             PG8_LDB(B1, 1, 1); PG8_STAGE(PG8_SB(1, 0), b3, voffB);
;             PG8_BAR; PG8_WAIT_L(0); PG8_MMA(0, 1, At, B1); PG8_BAR;
;             PG8_LDA(At, 1, 1); PG8_STAGE(PG8_SA(1, 0), a3, voffA);
	s_setprio 1
	v_mfma_f32_16x16x32_bf16 v[76:79], v[220:223], v[188:191], v[76:79]
	v_mfma_f32_16x16x32_bf16 v[72:75], v[228:231], v[188:191], v[72:75]
	v_mfma_f32_16x16x32_bf16 v[88:91], v[220:223], v[196:199], v[88:91]
	v_mfma_f32_16x16x32_bf16 v[80:83], v[228:231], v[196:199], v[80:83]
	v_mfma_f32_16x16x32_bf16 v[104:107], v[220:223], v[204:207], v[104:107]
	v_mfma_f32_16x16x32_bf16 v[96:99], v[228:231], v[204:207], v[96:99]
	v_mfma_f32_16x16x32_bf16 v[120:123], v[220:223], v[212:215], v[120:123]
	v_mfma_f32_16x16x32_bf16 v[124:127], v[228:231], v[212:215], v[124:127]
	v_mfma_f32_16x16x32_bf16 v[76:79], v[224:227], v[192:195], v[76:79]
	v_mfma_f32_16x16x32_bf16 v[72:75], v[232:235], v[192:195], v[72:75]
	v_mfma_f32_16x16x32_bf16 v[88:91], v[224:227], v[200:203], v[88:91]
	v_mfma_f32_16x16x32_bf16 v[80:83], v[232:235], v[200:203], v[80:83]
	v_mfma_f32_16x16x32_bf16 v[104:107], v[224:227], v[208:211], v[104:107]
	v_mfma_f32_16x16x32_bf16 v[96:99], v[232:235], v[208:211], v[96:99]
	v_mfma_f32_16x16x32_bf16 v[120:123], v[224:227], v[216:219], v[120:123]
	v_mfma_f32_16x16x32_bf16 v[124:127], v[232:235], v[216:219], v[124:127]
	s_setprio 0
	s_barrier
	s_add_i32 s59, 0, 0x18000
	v_add_u32_e32 v183, s59, v157
	ds_read_b128 v[128:131], v183
	ds_read_b128 v[132:135], v183 offset:1024
	ds_read_b128 v[174:177], v183 offset:2048
	ds_read_b128 v[184:187], v183 offset:3072
	s_add_u32 s30, s30, 0x4000
	s_addc_u32 s31, s31, 0
	s_mov_b32 m0, s36
	ds_read_b128 v[188:191], v181 offset:32768
	ds_read_b128 v[192:195], v181 offset:33792
	ds_read_b128 v[196:199], v181 offset:34816
	ds_read_b128 v[200:203], v181 offset:35840
	ds_read_b128 v[204:207], v181 offset:36864
	ds_read_b128 v[208:211], v181 offset:37888
	ds_read_b128 v[212:215], v181 offset:38912
	ds_read_b128 v[216:219], v181 offset:39936
	global_load_lds_dwordx4 v136, s[30:31]
	s_mov_b32 m0, s37
	s_nop 0
	global_load_lds_dwordx4 v140, s[30:31]
	s_waitcnt lgkmcnt(8)
	s_barrier
	s_waitcnt lgkmcnt(0)
	s_setprio 1
	s_waitcnt lgkmcnt(0)
	v_mfma_f32_16x16x32_bf16 v[0:3], v[128:131], v[188:191], v[0:3]
	v_mfma_f32_16x16x32_bf16 v[4:7], v[174:177], v[188:191], v[4:7]
	v_mfma_f32_16x16x32_bf16 v[44:47], v[128:131], v[196:199], v[44:47]
	v_mfma_f32_16x16x32_bf16 v[36:39], v[174:177], v[196:199], v[36:39]
	v_mfma_f32_16x16x32_bf16 v[52:55], v[128:131], v[204:207], v[52:55]
	v_mfma_f32_16x16x32_bf16 v[48:51], v[174:177], v[204:207], v[48:51]
	v_mfma_f32_16x16x32_bf16 v[92:95], v[128:131], v[212:215], v[92:95]
	v_mfma_f32_16x16x32_bf16 v[84:87], v[174:177], v[212:215], v[84:87]
	v_mfma_f32_16x16x32_bf16 v[0:3], v[132:135], v[192:195], v[0:3]
	v_mfma_f32_16x16x32_bf16 v[4:7], v[184:187], v[192:195], v[4:7]
	v_mfma_f32_16x16x32_bf16 v[44:47], v[132:135], v[200:203], v[44:47]
	v_mfma_f32_16x16x32_bf16 v[36:39], v[184:187], v[200:203], v[36:39]
	v_mfma_f32_16x16x32_bf16 v[52:55], v[132:135], v[208:211], v[52:55]
	v_mfma_f32_16x16x32_bf16 v[48:51], v[184:187], v[208:211], v[48:51]
	v_mfma_f32_16x16x32_bf16 v[92:95], v[132:135], v[216:219], v[92:95]
	v_mfma_f32_16x16x32_bf16 v[84:87], v[184:187], v[216:219], v[84:87]
	s_setprio 0
	s_barrier
	s_add_i32 s30, 0, 0x1c000
	s_add_i32 s31, s59, s33
	v_add_u32_e32 v183, s30, v157
	v_lshl_add_u64 v[178:179], v[178:179], 0, s[4:5]
	s_mov_b32 m0, s31
	ds_read_b128 v[220:223], v183
	ds_read_b128 v[224:227], v183 offset:1024
	ds_read_b128 v[228:231], v183 offset:2048
	ds_read_b128 v[232:235], v183 offset:3072
	global_load_lds_dwordx4 v[178:179], off
	v_lshl_add_u64 v[178:179], v[236:237], 0, s[4:5]
	s_add_i32 m0, s31, 0x2000
	s_nop 0
	global_load_lds_dwordx4 v[178:179], off
	s_barrier
	s_waitcnt lgkmcnt(0)
	s_setprio 1
	s_waitcnt lgkmcnt(0)
	v_mfma_f32_16x16x32_bf16 v[12:15], v[220:223], v[188:191], v[12:15]
	v_mfma_f32_16x16x32_bf16 v[8:11], v[228:231], v[188:191], v[8:11]
	v_mfma_f32_16x16x32_bf16 v[24:27], v[220:223], v[196:199], v[24:27]
	v_mfma_f32_16x16x32_bf16 v[16:19], v[228:231], v[196:199], v[16:19]
	v_mfma_f32_16x16x32_bf16 v[40:43], v[220:223], v[204:207], v[40:43]
	v_mfma_f32_16x16x32_bf16 v[32:35], v[228:231], v[204:207], v[32:35]
	v_mfma_f32_16x16x32_bf16 v[56:59], v[220:223], v[212:215], v[56:59]
	v_mfma_f32_16x16x32_bf16 v[60:63], v[228:231], v[212:215], v[60:63]
	v_mfma_f32_16x16x32_bf16 v[12:15], v[224:227], v[192:195], v[12:15]
	v_mfma_f32_16x16x32_bf16 v[8:11], v[232:235], v[192:195], v[8:11]
	v_mfma_f32_16x16x32_bf16 v[24:27], v[224:227], v[200:203], v[24:27]
	v_mfma_f32_16x16x32_bf16 v[16:19], v[232:235], v[200:203], v[16:19]
	v_mfma_f32_16x16x32_bf16 v[40:43], v[224:227], v[208:211], v[40:43]
	v_mfma_f32_16x16x32_bf16 v[32:35], v[232:235], v[208:211], v[32:35]
	v_mfma_f32_16x16x32_bf16 v[56:59], v[224:227], v[216:219], v[56:59]
	v_mfma_f32_16x16x32_bf16 v[60:63], v[232:235], v[216:219], v[60:63]
	s_setprio 0
	s_barrier
	s_mov_b32 m0, s39
	ds_read_b128 v[188:191], v181 offset:49152
	ds_read_b128 v[192:195], v181 offset:50176
	ds_read_b128 v[196:199], v181 offset:51200
	ds_read_b128 v[200:203], v181 offset:52224
	ds_read_b128 v[204:207], v181 offset:53248
	ds_read_b128 v[208:211], v181 offset:54272
	ds_read_b128 v[212:215], v181 offset:55296
	ds_read_b128 v[216:219], v181 offset:56320
	global_load_lds_dwordx4 v136, s[28:29]
	s_mov_b32 m0, s40
	s_nop 0
	global_load_lds_dwordx4 v140, s[28:29]
	s_barrier
; __device__ __forceinline__ float bflo(unsigned w) { return __uint_as_float(w << 16); }
; __device__ __forceinline__ float bfhi(unsigned w) { return __uint_as_float(w & 0xffff0000u); }
; #define PG8_STAGE(bufoff, gbase, voff) do { _Pragma("unroll") for (int _i = 0; _i < 2; ++_i) \
;         __builtin_amdgcn_global_load_lds((const unsigned*)((const char*)(gbase) + (voff)[_i]), (LAS unsigned*)(lds + (bufoff) + ldsw + _i * 8192), 16, 0, 0); } while (0)
; #define PG8_MMA(ai, bj, At, Bt) do { __builtin_amdgcn_s_setprio(1); _Pragma("unroll") for (int m = 0; m < 4; ++m) _Pragma("unroll") for (int n = 0; n < 2; ++n) _Pragma("unroll") for (int k = 0; k < 2; ++k) \
;         acc[ai][bj][m][n] = __builtin_amdgcn_mfma_f32_16x16x32_bf16(Bt[n][k], At[m][k], acc[ai][bj][m][n], 0, 0, 0); __builtin_amdgcn_s_setprio(0); } while (0)
; #define PG8_WAIT_V(n) asm volatile("s_waitcnt vmcnt(" #n ")" ::: "memory")
; #define PG8_WAIT_L(n) asm volatile("s_waitcnt lgkmcnt(" #n ")" ::: "memory")
; #define PG8_BAR __builtin_amdgcn_s_barrier()
; #define PG8_SCHED __builtin_amdgcn_sched_barrier(0)
; template <class Epi, class Sched, bool ATILE = false>
; __device__ __forceinline__ void gemm_phase(LAS unsigned char* lds, const Gemm g, const Sched& S, const Epi& E) {
;     ...
;             PG8_BAR; PG8_WAIT_L(0); PG8_MMA(1, 0, At, B0); PG8_BAR; PG8_SCHED;
;             PG8_STAGE(PG8_SB(1, 1), b3 + hstepB, voffB);
;             PG8_WAIT_V(6); PG8_BAR; PG8_MMA(1, 1, At, B1); PG8_BAR;
;         }
;         E(acc, cur, wr, wc, fr, fq);
;     __device__ __forceinline__ void operator()(const f32x4 (&acc)[2][2][4][2], const Unit& u, int wr, int wc, int fr, int fq) const {
;     ...
;                     const f32x4 v0 = (f32x4){bflo(x.x), bfhi(x.x), bflo(x.y), bfhi(x.y)} + alpha * acc[ai][bj][m][0];
;                     const f32x4 v1 = (f32x4){bflo(x.z), bfhi(x.z), bflo(x.w), bfhi(x.w)} + alpha * acc[ai][bj][m][1];
	s_waitcnt lgkmcnt(0)
	s_setprio 1
	s_waitcnt lgkmcnt(0)
	v_mfma_f32_16x16x32_bf16 v[64:67], v[128:131], v[188:191], v[64:67]
	v_mfma_f32_16x16x32_bf16 v[108:111], v[128:131], v[196:199], v[108:111]
	v_mfma_f32_16x16x32_bf16 v[116:119], v[128:131], v[204:207], v[116:119]
	v_mfma_f32_16x16x32_bf16 v[20:23], v[128:131], v[212:215], v[20:23]
	v_mfma_f32_16x16x32_bf16 v[64:67], v[132:135], v[192:195], v[64:67]
	v_mfma_f32_16x16x32_bf16 v[68:71], v[174:177], v[188:191], v[68:71]
	v_mfma_f32_16x16x32_bf16 v[108:111], v[132:135], v[200:203], v[108:111]
	v_mfma_f32_16x16x32_bf16 v[100:103], v[174:177], v[196:199], v[100:103]
	v_mfma_f32_16x16x32_bf16 v[116:119], v[132:135], v[208:211], v[116:119]
	v_mfma_f32_16x16x32_bf16 v[112:115], v[174:177], v[204:207], v[112:115]
	v_mfma_f32_16x16x32_bf16 v[132:135], v[132:135], v[216:219], v[20:23]
	v_mfma_f32_16x16x32_bf16 v[20:23], v[174:177], v[212:215], v[28:31]
	v_mfma_f32_16x16x32_bf16 v[68:71], v[184:187], v[192:195], v[68:71]
	v_mfma_f32_16x16x32_bf16 v[100:103], v[184:187], v[200:203], v[100:103]
	v_mfma_f32_16x16x32_bf16 v[112:115], v[184:187], v[208:211], v[112:115]
	v_mfma_f32_16x16x32_bf16 v[128:131], v[184:187], v[216:219], v[20:23]
	s_setprio 0
	s_barrier
	s_add_u32 s26, s26, 0x158080
	s_addc_u32 s27, s27, 0
	s_add_i32 s28, s30, s33
	s_mov_b32 m0, s28
	s_nop 0
	global_load_lds_dwordx4 v138, s[26:27]
	v_lshl_add_u64 v[20:21], s[26:27], 0, v[142:143]
	s_add_i32 m0, s28, 0x2000
	s_nop 0
	global_load_lds_dwordx4 v[20:21], off
	s_waitcnt vmcnt(6)
	s_barrier
	s_setprio 1
	v_mfma_f32_16x16x32_bf16 v[20:23], v[220:223], v[188:191], v[76:79]
	v_mfma_f32_16x16x32_bf16 v[76:79], v[224:227], v[192:195], v[20:23]
	v_mfma_f32_16x16x32_bf16 v[20:23], v[228:231], v[188:191], v[72:75]
	v_mfma_f32_16x16x32_bf16 v[72:75], v[232:235], v[192:195], v[20:23]
	v_mfma_f32_16x16x32_bf16 v[20:23], v[220:223], v[196:199], v[88:91]
	v_mfma_f32_16x16x32_bf16 v[88:91], v[224:227], v[200:203], v[20:23]
	v_mfma_f32_16x16x32_bf16 v[20:23], v[228:231], v[196:199], v[80:83]
	v_mfma_f32_16x16x32_bf16 v[80:83], v[232:235], v[200:203], v[20:23]
	v_mfma_f32_16x16x32_bf16 v[20:23], v[220:223], v[204:207], v[104:107]
	v_mfma_f32_16x16x32_bf16 v[104:107], v[224:227], v[208:211], v[20:23]
	v_mfma_f32_16x16x32_bf16 v[20:23], v[228:231], v[204:207], v[96:99]
	v_mfma_f32_16x16x32_bf16 v[96:99], v[232:235], v[208:211], v[20:23]
	v_mfma_f32_16x16x32_bf16 v[20:23], v[220:223], v[212:215], v[120:123]
	v_mfma_f32_16x16x32_bf16 v[120:123], v[224:227], v[216:219], v[20:23]
	v_mfma_f32_16x16x32_bf16 v[20:23], v[228:231], v[212:215], v[124:127]
	v_mfma_f32_16x16x32_bf16 v[124:127], v[232:235], v[216:219], v[20:23]
	s_setprio 0
	s_barrier
	s_add_u32 s56, s56, 0x100
	s_addc_u32 s57, s57, 0
	s_add_u32 s24, s24, 0x10000
	s_addc_u32 s25, s25, 0
	s_cmp_ge_i32 s58, s55
	s_mov_b32 s26, s58
	s_cbranch_scc0 .LBB0_1898
	v_pk_mul_f32 v[2:3], v[2:3], 0.5 op_sel_hi:[1,0]
	v_pk_mul_f32 v[0:1], v[0:1], 0.5 op_sel_hi:[1,0]
	v_pk_mul_f32 v[6:7], v[6:7], 0.5 op_sel_hi:[1,0]
	v_pk_mul_f32 v[4:5], v[4:5], 0.5 op_sel_hi:[1,0]
	v_pk_mul_f32 v[22:23], v[14:15], 0.5 op_sel_hi:[1,0]
	v_pk_mul_f32 v[20:21], v[12:13], 0.5 op_sel_hi:[1,0]
	v_pk_mul_f32 v[30:31], v[10:11], 0.5 op_sel_hi:[1,0]
	v_pk_mul_f32 v[28:29], v[8:9], 0.5 op_sel_hi:[1,0]
	v_pk_mul_f32 v[10:11], v[46:47], 0.5 op_sel_hi:[1,0]
	v_pk_mul_f32 v[8:9], v[44:45], 0.5 op_sel_hi:[1,0]
	v_pk_mul_f32 v[14:15], v[38:39], 0.5 op_sel_hi:[1,0]
	v_pk_mul_f32 v[12:13], v[36:37], 0.5 op_sel_hi:[1,0]
	v_pk_mul_f32 v[38:39], v[26:27], 0.5 op_sel_hi:[1,0]
	v_pk_mul_f32 v[36:37], v[24:25], 0.5 op_sel_hi:[1,0]
	v_pk_mul_f32 v[46:47], v[18:19], 0.5 op_sel_hi:[1,0]
	v_pk_mul_f32 v[44:45], v[16:17], 0.5 op_sel_hi:[1,0]
	v_pk_mul_f32 v[18:19], v[54:55], 0.5 op_sel_hi:[1,0]
	v_pk_mul_f32 v[16:17], v[52:53], 0.5 op_sel_hi:[1,0]
	v_pk_mul_f32 v[26:27], v[50:51], 0.5 op_sel_hi:[1,0]
	v_pk_mul_f32 v[24:25], v[48:49], 0.5 op_sel_hi:[1,0]
	v_pk_mul_f32 v[50:51], v[42:43], 0.5 op_sel_hi:[1,0]
	v_pk_mul_f32 v[48:49], v[40:41], 0.5 op_sel_hi:[1,0]
	v_pk_mul_f32 v[54:55], v[34:35], 0.5 op_sel_hi:[1,0]
	v_pk_mul_f32 v[52:53], v[32:33], 0.5 op_sel_hi:[1,0]
	v_pk_mul_f32 v[34:35], v[94:95], 0.5 op_sel_hi:[1,0]
	v_pk_mul_f32 v[32:33], v[92:93], 0.5 op_sel_hi:[1,0]
	v_pk_mul_f32 v[42:43], v[86:87], 0.5 op_sel_hi:[1,0]
	v_pk_mul_f32 v[40:41], v[84:85], 0.5 op_sel_hi:[1,0]
	v_pk_mul_f32 v[58:59], v[58:59], 0.5 op_sel_hi:[1,0]
	v_pk_mul_f32 v[56:57], v[56:57], 0.5 op_sel_hi:[1,0]
	v_pk_mul_f32 v[62:63], v[62:63], 0.5 op_sel_hi:[1,0]
	v_pk_mul_f32 v[60:61], v[60:61], 0.5 op_sel_hi:[1,0]
	v_pk_mul_f32 v[66:67], v[66:67], 0.5 op_sel_hi:[1,0]
	v_pk_mul_f32 v[64:65], v[64:65], 0.5 op_sel_hi:[1,0]
	v_pk_mul_f32 v[70:71], v[70:71], 0.5 op_sel_hi:[1,0]
	v_pk_mul_f32 v[68:69], v[68:69], 0.5 op_sel_hi:[1,0]
	v_pk_mul_f32 v[86:87], v[78:79], 0.5 op_sel_hi:[1,0]
	v_pk_mul_f32 v[84:85], v[76:77], 0.5 op_sel_hi:[1,0]
	v_pk_mul_f32 v[94:95], v[74:75], 0.5 op_sel_hi:[1,0]
	v_pk_mul_f32 v[92:93], v[72:73], 0.5 op_sel_hi:[1,0]
	v_pk_mul_f32 v[74:75], v[110:111], 0.5 op_sel_hi:[1,0]
	v_pk_mul_f32 v[72:73], v[108:109], 0.5 op_sel_hi:[1,0]
	v_pk_mul_f32 v[78:79], v[102:103], 0.5 op_sel_hi:[1,0]
	v_pk_mul_f32 v[76:77], v[100:101], 0.5 op_sel_hi:[1,0]
	v_pk_mul_f32 v[102:103], v[90:91], 0.5 op_sel_hi:[1,0]
	v_pk_mul_f32 v[100:101], v[88:89], 0.5 op_sel_hi:[1,0]
	v_pk_mul_f32 v[110:111], v[82:83], 0.5 op_sel_hi:[1,0]
	v_pk_mul_f32 v[108:109], v[80:81], 0.5 op_sel_hi:[1,0]
	v_pk_mul_f32 v[82:83], v[118:119], 0.5 op_sel_hi:[1,0]
	v_pk_mul_f32 v[80:81], v[116:117], 0.5 op_sel_hi:[1,0]
	v_pk_mul_f32 v[90:91], v[114:115], 0.5 op_sel_hi:[1,0]
	v_pk_mul_f32 v[88:89], v[112:113], 0.5 op_sel_hi:[1,0]
	v_pk_mul_f32 v[114:115], v[106:107], 0.5 op_sel_hi:[1,0]
	v_pk_mul_f32 v[112:113], v[104:105], 0.5 op_sel_hi:[1,0]
	v_pk_mul_f32 v[118:119], v[98:99], 0.5 op_sel_hi:[1,0]
	v_pk_mul_f32 v[116:117], v[96:97], 0.5 op_sel_hi:[1,0]
	v_pk_mul_f32 v[98:99], v[134:135], 0.5 op_sel_hi:[1,0]
	v_pk_mul_f32 v[96:97], v[132:133], 0.5 op_sel_hi:[1,0]
	v_pk_mul_f32 v[106:107], v[130:131], 0.5 op_sel_hi:[1,0]
	v_pk_mul_f32 v[104:105], v[128:129], 0.5 op_sel_hi:[1,0]
	v_pk_mul_f32 v[122:123], v[122:123], 0.5 op_sel_hi:[1,0]
	v_pk_mul_f32 v[120:121], v[120:121], 0.5 op_sel_hi:[1,0]
	v_pk_mul_f32 v[126:127], v[126:127], 0.5 op_sel_hi:[1,0]
	v_pk_mul_f32 v[124:125], v[124:125], 0.5 op_sel_hi:[1,0]
	s_branch .LBB0_1903
